# NSA selected/window walks: fp8 K fragments stored as 16-byte fragment pairs and fetched with 4 global_load_dwordx4 per step instead of 8 dwordx2 (walks are bound by vector-memory instruction rate); co
# speedup vs baseline: 1.0512x; 1.0297x over previous
; #define PG8_STAGE(bufoff, gbase, voff) do { _Pragma("unroll") for (int _i = 0; _i < 2; ++_i) \
;         __builtin_amdgcn_global_load_lds((const unsigned*)((const char*)(gbase) + (voff)[_i]), (LAS unsigned*)(lds + (bufoff) + ldsw + _i * 8192), 16, 0, 0); } while (0)
; template <class Epi, bool FP8 = false>
; __device__ __forceinline__ void gemm_phase(LAS unsigned char* lds, const Gemm g, const StaticOrder& S_, const Epi& E, const int tid) {
;     ...
;     const char* cA = (const char*)g.A + (size_t)cur.pm * tstepA; const char* cB = (const char*)g.Bt + (size_t)cur.pn * tstepB;
;     PG8_STAGE(PG8_SB(0, 0), cB, voffB); PG8_STAGE(PG8_SB(0, 1), cB + hstepB, voffB); PG8_STAGE(PG8_SA(0, 0), cA, voffA); PG8_STAGE(PG8_SA(0, 1), cA + hstepA, voffA);
;     if (wr == 1) PG8_BAR;
;     PG8_WAIT_V(2); PG8_BAR;
;     PG8_STAGE(PG8_SB(1, 0), cB + kstep, voffB); PG8_STAGE(PG8_SA(1, 0), cA + kstep, voffA); PG8_STAGE(PG8_SB(1, 1), cB + hstepB + kstep, voffB);
;     PG8_WAIT_V(6); PG8_BAR;
;     __device__ __forceinline__ void operator()(const pg8::Acc& acc, const pg8::Unit& u, int wr, int wc, int fr, int fq) const {
;     ...
;                 const int head = cw >> 6, d = cw & 63;
;                 const bool frag = (tile == 6) | (tile == 8);
;                 unsigned char* KF = (unsigned char*)kslf + (tile == 6 ? (size_t)0 : (size_t)16 << 20); const float* sn = cs + (size_t)S * 64;
; #pragma unroll
;                 for (int ai = 0; ai < 2; ++ai)
; #pragma unroll
;                     for (int m = 0; m < 4; ++m) {
;                         const int row = row0 + ai * 128 + m * 16;
;                         f32x4 o1[2], o2[2];
; #pragma unroll
;                         for (int n = 0; n < 2; ++n) {
;                             const f32x4 c = *(const f32x4*)(cs + (size_t)row * 64 + d + 4 * n), sv = *(const f32x4*)(sn + (size_t)row * 64 + d + 4 * n);
;                             const f32x4 x1 = acc[ai][0][m][n], x2 = acc[ai][1][m][n];
;                             o1[n] = x1 * c - x2 * sv; o2[n] = x2 * c + x1 * sv;
;                         }
;                         if (frag) {
;                             unsigned char* kb = KF + ((size_t)head * 1024 + (row >> 4)) * 2048 + (size_t)(d >> 5) * 512 + (size_t)(((d >> 3) & 3) * 16 + (row & 15)) * 8;
;                             *(u32x2*)kb = pack8_fp8(o1[0], o1[1]); *(u32x2*)(kb + 1024) = pack8_fp8(o2[0], o2[1]);
.LBB0_451:
	s_add_u32 s12, s4, 0xe000000
	s_addc_u32 s13, s5, 0
	s_add_u32 s24, s4, 0x1a000000
	s_addc_u32 s25, s5, 0
	v_bfe_u32 v15, v8, 4, 2
	s_add_u32 s76, s4, 0x14000000
	v_and_b32_e32 v155, 15, v8
	v_lshlrev_b32_e32 v17, 4, v15
	v_lshlrev_b32_e32 v18, 2, v8
	s_addc_u32 s77, s5, 0
	s_and_b32 s7, s22, 3
	s_lshl_b32 s78, s14, 6
	v_lshl_or_b32 v17, v155, 6, v17
	s_lshl_b32 s14, s14, 13
	v_and_b32_e32 v19, 32, v18
	v_bitop3_b32 v20, v17, s14, v19 bitop3:0xde
	s_lshl_b32 s14, s7, 12
	v_bitop3_b32 v163, s14, v17, v19 bitop3:0xf6
	s_mov_b64 s[14:15], 0x80
	s_add_i32 m0, s71, 0x18000
	v_lshl_add_u64 v[6:7], v[6:7], 0, s[14:15]
	s_lshl_b32 s20, s7, 5
	s_waitcnt vmcnt(2)
	s_barrier
	global_load_lds_dwordx4 v[6:7], off
	v_lshl_add_u64 v[4:5], v[4:5], 0, s[14:15]
	s_add_i32 m0, s71, 0x1a000
	s_add_i32 s79, s71, 0x8000
	s_add_i32 s80, s71, 0xa000
	global_load_lds_dwordx4 v[4:5], off
	v_lshl_add_u64 v[0:1], v[0:1], 0, s[14:15]
	s_mov_b32 m0, s79
	s_add_u32 s18, s56, 0x80080
	global_load_lds_dwordx4 v[0:1], off
	v_lshl_add_u64 v[0:1], v[2:3], 0, s[14:15]
	s_mov_b32 m0, s80
	s_addc_u32 s19, s57, 0
	global_load_lds_dwordx4 v[0:1], off
	s_add_i32 m0, s71, 0x1c000
	v_lshl_add_u64 v[0:1], s[18:19], 0, v[146:147]
	global_load_lds_dwordx4 v[0:1], off
	v_lshl_add_u64 v[0:1], s[18:19], 0, v[150:151]
	s_add_i32 m0, s71, 0x1e000
	s_cmpk_lt_u32 s16, 0x100
	global_load_lds_dwordx4 v[0:1], off
	s_cselect_b64 s[16:17], -1, 0
	s_cmp_eq_u32 s7, 0
	v_lshlrev_b32_e32 v16, 3, v15
	s_cselect_b64 s[18:19], -1, 0
	v_lshlrev_b32_e32 v0, 5, v8
	s_bfe_u32 s81, s22, 0x10001
	s_lshl_b32 s7, s22, 9
	v_or_b32_e32 v154, s20, v16
	v_and_b32_e32 v152, 0x180, v0
	v_bitop3_b32 v162, s20, 56, v16 bitop3:0xc8
	s_lshl_b32 s20, s81, 10
	s_and_b32 s22, s7, 0x200
	s_lshl_b32 s82, s81, 7
	s_ashr_i32 s83, s2, 31
	v_lshlrev_b32_e32 v0, 5, v154
	v_lshlrev_b32_e32 v189, 7, v15
	v_lshl_add_u64 v[166:167], s[24:25], 0, v[152:153]
	s_lshr_b32 s98, s22, 6
	s_add_u32 s24, s24, s98
	v_and_b32_e32 v158, 0xe00, v0
	v_lshlrev_b32_e32 v0, 8, v15
	v_lshl_or_b32 v0, v155, 4, v0
	v_mov_b32_e32 v1, v153
	s_addc_u32 s25, s25, 0
	v_lshlrev_b32_e32 v152, 2, v162
	v_lshl_add_u64 v[168:169], s[24:25], 0, v[0:1]
	v_lshl_add_u64 v[0:1], s[4:5], 0, v[152:153]
	s_mov_b64 s[24:25], 0x1c000000
	v_lshlrev_b32_e32 v2, 1, v154
	v_mov_b32_e32 v3, v153
	v_lshl_add_u64 v[170:171], v[0:1], 0, s[24:25]
	s_add_u32 s24, s4, 0x15800000
	v_lshl_add_u64 v[2:3], s[4:5], 0, v[2:3]
	s_addc_u32 s25, s5, 0
	s_mov_b64 s[4:5], 0x1c400000
	v_lshl_add_u64 v[172:173], v[0:1], 0, s[4:5]
	v_lshlrev_b32_e32 v0, 15, v9
	v_and_b32_e32 v0, 0xffff0000, v0
	v_lshl_add_u32 v0, v10, 12, v0
	v_and_b32_e32 v1, 1, v9
	v_lshl_or_b32 v0, v1, 6, v0
	v_lshl_add_u32 v174, v11, 1, v0
	v_lshlrev_b32_e32 v0, 15, v12
	v_and_b32_e32 v0, 0xffff0000, v0
	s_waitcnt vmcnt(6)
	v_lshl_add_u32 v0, v13, 12, v0
	v_and_b32_e32 v1, 1, v12
	s_mov_b64 s[26:27], 0x1b00000
	v_lshl_or_b32 v0, v1, 6, v0
	s_add_i32 s85, 0, 0x10000
	s_add_i32 s86, 0, 0x14000
	v_and_b32_e32 v156, 3, v8
	v_mov_b32_e32 v157, v153
	v_mov_b32_e32 v159, v153
	v_and_b32_e32 v160, 64, v18
	v_mov_b32_e32 v161, v153
	v_and_b32_e32 v188, 8, v16
	s_mov_b32 s21, s9
	s_mov_b32 s23, s9
	v_lshl_add_u64 v[164:165], v[2:3], 0, s[26:27]
	v_mov_b32_e32 v175, v153
	v_lshl_add_u32 v176, v14, 1, v0
	v_mov_b32_e32 v177, v153
	v_mov_b64_e32 v[178:179], 0x500
	s_movk_i32 s84, 0xa1
	v_add_u32_e32 v190, s85, v163
	v_add_u32_e32 v191, 0, v20
	s_movk_i32 s87, 0xd000
	s_mov_b32 s88, 0xfc000
	s_mov_b32 s89, 0x11c000
	s_mov_b32 s90, 0x13c000
	s_mov_b32 s91, 0x15c000
	s_mov_b32 s92, 0x800000
	s_mov_b32 s93, 0x200000
	s_movk_i32 s94, 0x1800
	s_movk_i32 s95, 0x78
	v_mov_b64_e32 v[180:181], 0x4ff
	v_add_u32_e32 v192, s86, v163
	s_mov_b32 s96, 0
	s_barrier
	s_branch .LBB0_454

; __device__ __forceinline__ unsigned cvt_pk_bf16(float lo, float hi) { f32x2 v = {lo, hi}; bf16x2_t b = __builtin_convertvector(v, bf16x2_t); return __builtin_bit_cast(unsigned, b); }
; __device__ __forceinline__ float bf2f(unsigned short b) { return __uint_as_float(((unsigned)b) << 16); }
; __device__ __forceinline__ float bflo(unsigned w) { return __uint_as_float(w << 16); }
; __device__ __forceinline__ float bfhi(unsigned w) { return __uint_as_float(w & 0xffff0000u); }
; __device__ __forceinline__ float quad_total(float v) { v += __shfl_xor(v, 16); v += __shfl_xor(v, 32); return v; }
; __device__ __forceinline__ void nsa_unit(int unit, const bf16_t* proj, const bf16_t* kc, const bf16_t* vc, const bf16_t* gn, const float* cs, const float* sn, ...
;     ...
;     { const float g2 = bf2f(gn[(size_t)tc * 32 + head * 3 + 2]); const float lt = quad_total(st.l), inv = (lt > 0.f ? 1.f / lt : 0.f) * g2;
; #pragma unroll
;         for (int i = 0; i < 8; ++i) { const f32x4 o = st.o[i] * inv; u32x2 w = outl[64 * i]; w.x = cvt_pk_bf16(bflo(w.x) + o[0], bfhi(w.x) + o[1]); w.y = cvt_pk_bf16(bflo(w.y) + o[2], bfhi(w.y) + o[3]); outl[64 * i] = w; } }
;     bf16_t* op = nsaout + (size_t)tc * NOLD + head * 128 + 4 * kq;
; #pragma unroll
;     for (int db = 0; db < 8; ++db) *(u32x2*)(op + 16 * db) = outl[64 * db];
.LBB0_926:
	s_waitcnt vmcnt(12)
	global_load_ushort v0, v[76:77], off offset:4
	ds_bpermute_b32 v35, v225, v34
	ds_read2st64_b64 v[36:39], v226 offset0:27 offset1:28
	ds_read2st64_b64 v[40:43], v226 offset0:29 offset1:30
	ds_read2st64_b64 v[44:47], v226 offset0:31 offset1:32
	ds_read2st64_b64 v[48:51], v226 offset0:33 offset1:34
	s_waitcnt lgkmcnt(3)
	v_lshlrev_b32_e32 v52, 16, v38
	v_and_b32_e32 v53, 0xffff0000, v38
	v_add_f32_e32 v64, v34, v35
	ds_bpermute_b32 v65, v224, v64
	v_lshlrev_b32_e32 v34, 16, v36
	v_and_b32_e32 v35, 0xffff0000, v36
	v_lshlrev_b32_e32 v36, 16, v37
	v_and_b32_e32 v37, 0xffff0000, v37
	s_waitcnt lgkmcnt(0)
	v_add_f32_e32 v64, v64, v65
	v_div_scale_f32 v65, s[10:11], v64, v64, 1.0
	v_rcp_f32_e32 v66, v65
	v_div_scale_f32 v67, vcc, 1.0, v64, 1.0
	v_lshlrev_b32_e32 v38, 16, v39
	v_fma_f32 v68, -v65, v66, 1.0
	v_fmac_f32_e32 v66, v68, v66
	v_mul_f32_e32 v68, v67, v66
	v_fma_f32 v69, -v65, v68, v67
	v_fmac_f32_e32 v68, v69, v66
	v_fma_f32 v65, -v65, v68, v67
	v_div_fmas_f32 v65, v65, v66, v68
	v_div_fixup_f32 v65, v65, v64, 1.0
	v_cmp_lt_f32_e32 vcc, 0, v64
	v_and_b32_e32 v39, 0xffff0000, v39
	v_lshlrev_b32_e32 v56, 16, v42
	v_cndmask_b32_e32 v64, 0, v65, vcc
	v_and_b32_e32 v57, 0xffff0000, v42
	v_lshlrev_b32_e32 v42, 16, v43
	v_and_b32_e32 v43, 0xffff0000, v43
	v_lshlrev_b32_e32 v62, 16, v48
	v_and_b32_e32 v63, 0xffff0000, v48
	v_lshlrev_b32_e32 v48, 16, v49
	v_and_b32_e32 v49, 0xffff0000, v49
	v_lshlrev_b32_e32 v54, 16, v40
	v_and_b32_e32 v55, 0xffff0000, v40
	v_lshlrev_b32_e32 v40, 16, v41
	v_and_b32_e32 v41, 0xffff0000, v41
	v_lshlrev_b32_e32 v58, 16, v44
	v_and_b32_e32 v59, 0xffff0000, v44
	v_lshlrev_b32_e32 v44, 16, v45
	v_and_b32_e32 v45, 0xffff0000, v45
	v_lshlrev_b32_e32 v60, 16, v46
	v_and_b32_e32 v61, 0xffff0000, v46
	v_lshlrev_b32_e32 v46, 16, v47
	v_and_b32_e32 v47, 0xffff0000, v47
	s_waitcnt vmcnt(0)
	v_lshlrev_b32_e32 v0, 16, v0
	v_mul_f32_e32 v0, v64, v0
	v_pk_fma_f32 v[6:7], v[6:7], v[0:1], v[34:35] op_sel_hi:[1,0,1]
	v_pk_fma_f32 v[8:9], v[8:9], v[0:1], v[36:37] op_sel_hi:[1,0,1]
	v_pk_fma_f32 v[12:13], v[12:13], v[0:1], v[38:39] op_sel_hi:[1,0,1]
	v_pk_fma_f32 v[20:21], v[20:21], v[0:1], v[42:43] op_sel_hi:[1,0,1]
	v_cvt_pk_bf16_f32 v6, v6, v7
	v_cvt_pk_bf16_f32 v7, v8, v9
	v_cvt_pk_bf16_f32 v9, v12, v13
	v_cvt_pk_bf16_f32 v13, v20, v21
	v_lshlrev_b32_e32 v20, 16, v50
	v_and_b32_e32 v21, 0xffff0000, v50
	v_pk_fma_f32 v[2:3], v[2:3], v[0:1], v[20:21] op_sel_hi:[1,0,1]
	v_lshlrev_b32_e32 v20, 16, v51
	v_and_b32_e32 v21, 0xffff0000, v51
	v_pk_fma_f32 v[10:11], v[10:11], v[0:1], v[52:53] op_sel_hi:[1,0,1]
	v_pk_fma_f32 v[18:19], v[18:19], v[0:1], v[56:57] op_sel_hi:[1,0,1]
	v_pk_fma_f32 v[30:31], v[30:31], v[0:1], v[62:63] op_sel_hi:[1,0,1]
	v_pk_fma_f32 v[32:33], v[32:33], v[0:1], v[48:49] op_sel_hi:[1,0,1]
	v_pk_fma_f32 v[4:5], v[4:5], v[0:1], v[20:21] op_sel_hi:[1,0,1]
	v_pk_fma_f32 v[14:15], v[14:15], v[0:1], v[54:55] op_sel_hi:[1,0,1]
	v_pk_fma_f32 v[16:17], v[16:17], v[0:1], v[40:41] op_sel_hi:[1,0,1]
	v_pk_fma_f32 v[22:23], v[22:23], v[0:1], v[58:59] op_sel_hi:[1,0,1]
	v_pk_fma_f32 v[24:25], v[24:25], v[0:1], v[44:45] op_sel_hi:[1,0,1]
	v_pk_fma_f32 v[26:27], v[26:27], v[0:1], v[60:61] op_sel_hi:[1,0,1]
	v_pk_fma_f32 v[28:29], v[28:29], v[0:1], v[46:47] op_sel_hi:[1,0,1]
	v_cvt_pk_bf16_f32 v8, v10, v11
	v_cvt_pk_bf16_f32 v12, v18, v19
	v_cvt_pk_bf16_f32 v18, v30, v31
	v_cvt_pk_bf16_f32 v19, v32, v33
	v_cvt_pk_bf16_f32 v2, v2, v3
	v_cvt_pk_bf16_f32 v3, v4, v5
	v_mad_i64_i32 v[4:5], s[10:11], v132, s88, v[126:127]
	v_cvt_pk_bf16_f32 v10, v14, v15
	v_cvt_pk_bf16_f32 v11, v16, v17
	v_cvt_pk_bf16_f32 v14, v22, v23
	v_cvt_pk_bf16_f32 v15, v24, v25
	v_cvt_pk_bf16_f32 v16, v26, v27
	v_cvt_pk_bf16_f32 v17, v28, v29
	ds_write2st64_b64 v226, v[6:7], v[8:9] offset0:27 offset1:28
	ds_write2st64_b64 v226, v[10:11], v[12:13] offset0:29 offset1:30
	ds_write2st64_b64 v226, v[14:15], v[16:17] offset0:31 offset1:32
	ds_write2st64_b64 v226, v[18:19], v[2:3] offset0:33 offset1:34
	global_store_dwordx2 v[4:5], v[6:7], off
	global_store_dwordx2 v[4:5], v[8:9], off offset:32
	global_store_dwordx2 v[4:5], v[10:11], off offset:64
	global_store_dwordx2 v[4:5], v[12:13], off offset:96
	global_store_dwordx2 v[4:5], v[14:15], off offset:128
	global_store_dwordx2 v[4:5], v[16:17], off offset:160
	global_store_dwordx2 v[4:5], v[18:19], off offset:192
	global_store_dwordx2 v[4:5], v[2:3], off offset:224

; __device__ __forceinline__ void nsa_unit(int unit, const bf16_t* proj, const bf16_t* kc, const bf16_t* vc, const bf16_t* gn, const float* cs, const float* sn, ...
;     ...
;     for (int s2 = 0; s2 < 2; ++s2) {
;         const int d = 32 * s2 + 8 * kq; f32x4 c[2], sv[2];
;         c[0] = *(const f32x4*)(cs + (size_t)tc * 64 + d); c[1] = *(const f32x4*)(cs + (size_t)tc * 64 + d + 4);
;         sv[0] = *(const f32x4*)(sn + (size_t)tc * 64 + d); sv[1] = *(const f32x4*)(sn + (size_t)tc * 64 + d + 4);
;         float o1[8], o2[8];
; #pragma unroll
;         for (int j = 0; j < 8; ++j) { const float x1 = bf2f((unsigned short)qf[s2][j]), x2 = bf2f((unsigned short)qf[s2 + 2][j]), cc = c[j >> 2][j & 3], ss = sv[j >> 2][j & 3];
;             o1[j] = x1 * cc - x2 * ss; o2[j] = x2 * cc + x1 * ss; }
;         u32x4 w1, w2; w1.x = cvt_pk_bf16(o1[0], o1[1]); w1.y = cvt_pk_bf16(o1[2], o1[3]); w1.z = cvt_pk_bf16(o1[4], o1[5]); w1.w = cvt_pk_bf16(o1[6], o1[7]);
;         w2.x = cvt_pk_bf16(o2[0], o2[1]); w2.y = cvt_pk_bf16(o2[2], o2[3]); w2.z = cvt_pk_bf16(o2[4], o2[5]); w2.w = cvt_pk_bf16(o2[6], o2[7]);
;         qf[s2] = __builtin_bit_cast(bf16x8, w1); qf[s2 + 2] = __builtin_bit_cast(bf16x8, w2);
;     }
;     unsigned key[4][4];
; #pragma unroll
;     for (int q = 0; q < 4; ++q) { const int cur = (t0 + q) >> 6; const f32x4 v = *(const LAS f32x4*)(imp + q * IMP_LD + 4 * lane);
; #pragma unroll
;         for (int i = 0; i < 4; ++i) { const int j = 4 * lane + i; const bool valid = j <= cur, forced = (j == 0) | (j == cur) | (j == cur - 1);
;             const unsigned kb = forced ? 0xffffffu : ((__float_as_uint(fmaxf(v[i], 0.f)) >> 8) + 1u);
;             key[q][i] = valid ? ((kb << 8) | (unsigned)(255 - j)) : 0u; } }
; #pragma unroll 1
;     for (int r = 0; r < 16; ++r) {
;         unsigned mx[4];
; #pragma unroll
;         for (int q = 0; q < 4; ++q) { unsigned a = key[q][0] > key[q][1] ? key[q][0] : key[q][1], b = key[q][2] > key[q][3] ? key[q][2] : key[q][3]; mx[q] = a > b ? a : b; }
; #pragma unroll
;         for (int o = 1; o < 64; o <<= 1)
; #pragma unroll
;             for (int q = 0; q < 4; ++q) { const unsigned other = (unsigned)__shfl_xor((int)mx[q], o); mx[q] = other > mx[q] ? other : mx[q]; }
; #pragma unroll
;         for (int q = 0; q < 4; ++q) {
; #pragma unroll
;             for (int i = 0; i < 4; ++i) if (key[q][i] == mx[q]) key[q][i] = 0u;
.LBB0_959:
	s_or_b64 exec, exec, s[12:13]
	v_and_b32_e32 v51, 0xffff0000, v14
	v_lshlrev_b32_e32 v50, 16, v14
	v_and_b32_e32 v53, 0xffff0000, v10
	v_lshlrev_b32_e32 v52, 16, v10
	s_waitcnt vmcnt(4)
	v_pk_mul_f32 v[54:55], v[46:47], v[52:53]
	v_pk_mul_f32 v[46:47], v[46:47], v[50:51]
	v_pk_fma_f32 v[54:55], v[42:43], v[50:51], v[54:55] neg_lo:[0,0,1] neg_hi:[0,0,1]
	v_pk_fma_f32 v[42:43], v[42:43], v[52:53], v[46:47]
	v_and_b32_e32 v47, 0xffff0000, v15
	v_lshlrev_b32_e32 v46, 16, v15
	v_and_b32_e32 v15, 0xffff0000, v11
	v_lshlrev_b32_e32 v14, 16, v11
	v_pk_mul_f32 v[10:11], v[48:49], v[14:15]
	v_cvt_pk_bf16_f32 v0, v54, v55
	v_pk_fma_f32 v[10:11], v[44:45], v[46:47], v[10:11] neg_lo:[0,0,1] neg_hi:[0,0,1]
	v_pk_mul_f32 v[46:47], v[48:49], v[46:47]
	v_mov_b32_e32 v79, v1
	v_pk_fma_f32 v[14:15], v[44:45], v[14:15], v[46:47]
	v_and_b32_e32 v45, 0xffff0000, v16
	v_lshlrev_b32_e32 v44, 16, v16
	v_and_b32_e32 v47, 0xffff0000, v12
	v_lshlrev_b32_e32 v46, 16, v12
	v_pk_mul_f32 v[48:49], v[38:39], v[46:47]
	v_pk_mul_f32 v[38:39], v[38:39], v[44:45]
	v_pk_fma_f32 v[48:49], v[34:35], v[44:45], v[48:49] neg_lo:[0,0,1] neg_hi:[0,0,1]
	v_pk_fma_f32 v[34:35], v[34:35], v[46:47], v[38:39]
	v_and_b32_e32 v39, 0xffff0000, v17
	v_lshlrev_b32_e32 v38, 16, v17
	v_and_b32_e32 v17, 0xffff0000, v13
	v_lshlrev_b32_e32 v16, 16, v13
	v_pk_mul_f32 v[12:13], v[40:41], v[16:17]
	v_cvt_pk_bf16_f32 v34, v34, v35
	v_pk_fma_f32 v[12:13], v[36:37], v[38:39], v[12:13] neg_lo:[0,0,1] neg_hi:[0,0,1]
	v_pk_mul_f32 v[38:39], v[40:41], v[38:39]
	v_cvt_pk_bf16_f32 v40, v14, v15
	v_pk_fma_f32 v[16:17], v[36:37], v[16:17], v[38:39]
	v_cvt_pk_bf16_f32 v38, v12, v13
	v_and_b32_e32 v13, 0xffff0000, v2
	v_lshlrev_b32_e32 v12, 16, v2
	v_cvt_pk_bf16_f32 v36, v10, v11
	v_and_b32_e32 v11, 0xffff0000, v6
	v_lshlrev_b32_e32 v10, 16, v6
	s_waitcnt vmcnt(0)
	v_pk_mul_f32 v[14:15], v[30:31], v[12:13]
	v_lshlrev_b32_e32 v6, 16, v3
	v_pk_fma_f32 v[14:15], v[26:27], v[10:11], v[14:15] neg_lo:[0,0,1] neg_hi:[0,0,1]
	v_pk_mul_f32 v[10:11], v[30:31], v[10:11]
	v_cvt_pk_bf16_f32 v35, v16, v17
	v_pk_fma_f32 v[10:11], v[26:27], v[12:13], v[10:11]
	v_and_b32_e32 v13, 0xffff0000, v7
	v_lshlrev_b32_e32 v12, 16, v7
	v_and_b32_e32 v7, 0xffff0000, v3
	v_pk_mul_f32 v[2:3], v[32:33], v[6:7]
	v_and_b32_e32 v17, 0xffff0000, v4
	v_pk_fma_f32 v[2:3], v[28:29], v[12:13], v[2:3] neg_lo:[0,0,1] neg_hi:[0,0,1]
	v_pk_mul_f32 v[12:13], v[32:33], v[12:13]
	v_lshlrev_b32_e32 v16, 16, v4
	v_pk_fma_f32 v[6:7], v[28:29], v[6:7], v[12:13]
	v_and_b32_e32 v13, 0xffff0000, v8
	v_lshlrev_b32_e32 v12, 16, v8
	v_pk_mul_f32 v[26:27], v[22:23], v[16:17]
	v_lshlrev_b32_e32 v8, 16, v5
	v_pk_fma_f32 v[26:27], v[18:19], v[12:13], v[26:27] neg_lo:[0,0,1] neg_hi:[0,0,1]
	v_pk_mul_f32 v[12:13], v[22:23], v[12:13]
	v_cvt_pk_bf16_f32 v37, v48, v49
	v_pk_fma_f32 v[12:13], v[18:19], v[16:17], v[12:13]
	v_and_b32_e32 v17, 0xffff0000, v9
	v_lshlrev_b32_e32 v16, 16, v9
	v_and_b32_e32 v9, 0xffff0000, v5
	v_pk_mul_f32 v[4:5], v[24:25], v[8:9]
	v_mov_b32_e32 v78, v1
	v_pk_fma_f32 v[4:5], v[20:21], v[16:17], v[4:5] neg_lo:[0,0,1] neg_hi:[0,0,1]
	v_pk_mul_f32 v[16:17], v[24:25], v[16:17]
	v_cvt_pk_bf16_f32 v4, v4, v5
	v_cvt_pk_bf16_f32 v5, v10, v11
	v_lshlrev_b32_e32 v10, 16, v37
	v_and_b32_e32 v11, 0xffff0000, v37
	v_pk_fma_f32 v[8:9], v[20:21], v[8:9], v[16:17]
	v_mul_f32_e32 v10, 0x3e0293ee, v10
	v_mul_f32_e32 v11, 0x3e0293ee, v11
	v_cvt_pk_bf16_f32 v8, v8, v9
	v_lshlrev_b32_e32 v9, 16, v0
	v_and_b32_e32 v0, 0xffff0000, v0
	v_cvt_pk_fp8_f32 v79, v10, v11
	v_mul_f32_e32 v9, 0x3e0293ee, v9
	v_mul_f32_e32 v0, 0x3e0293ee, v0
	v_cvt_pk_bf16_f32 v6, v6, v7
	v_cvt_pk_bf16_f32 v7, v12, v13
	v_lshlrev_b32_e32 v13, 16, v38
	v_cvt_pk_fp8_f32 v78, v9, v0
	v_and_b32_e32 v0, 0xffff0000, v38
	v_cvt_pk_bf16_f32 v14, v14, v15
	v_mul_f32_e32 v13, 0x3e0293ee, v13
	v_mul_f32_e32 v0, 0x3e0293ee, v0
	v_cvt_pk_fp8_f32 v79, v13, v0 op_sel:[0,0,1]
	v_lshlrev_b32_e32 v0, 16, v14
	v_and_b32_e32 v10, 0xffff0000, v14
	v_cvt_pk_bf16_f32 v2, v2, v3
	v_cvt_pk_bf16_f32 v3, v26, v27
	v_mul_f32_e32 v0, 0x3e0293ee, v0
	v_mul_f32_e32 v10, 0x3e0293ee, v10
	v_mov_b32_e32 v80, v1
	v_lshlrev_b32_e32 v9, 16, v3
	v_and_b32_e32 v3, 0xffff0000, v3
	v_cvt_pk_fp8_f32 v80, v0, v10
	v_mul_f32_e32 v9, 0x3e0293ee, v9
	v_mul_f32_e32 v3, 0x3e0293ee, v3
	v_mov_b32_e32 v81, v1
	v_lshlrev_b32_e32 v12, 16, v36
	v_and_b32_e32 v15, 0xffff0000, v36
	v_lshlrev_b32_e32 v11, 16, v2
	v_and_b32_e32 v2, 0xffff0000, v2
	v_cvt_pk_fp8_f32 v81, v9, v3
	v_mul_f32_e32 v12, 0x3e0293ee, v12
	v_mul_f32_e32 v15, 0x3e0293ee, v15
	v_mul_f32_e32 v11, 0x3e0293ee, v11
	v_mul_f32_e32 v2, 0x3e0293ee, v2
	v_cvt_pk_fp8_f32 v78, v12, v15 op_sel:[0,0,1]
	v_lshlrev_b32_e32 v12, 16, v4
	v_and_b32_e32 v0, 0xffff0000, v4
	v_cvt_pk_fp8_f32 v80, v11, v2 op_sel:[0,0,1]
	v_lshlrev_b32_e32 v2, 16, v34
	v_and_b32_e32 v4, 0xffff0000, v34
	v_cvt_pk_bf16_f32 v39, v42, v43
	v_mul_f32_e32 v12, 0x3e0293ee, v12
	v_mul_f32_e32 v0, 0x3e0293ee, v0
	v_mul_f32_e32 v2, 0x3e0293ee, v2
	v_mul_f32_e32 v4, 0x3e0293ee, v4
	v_mov_b32_e32 v83, v1
	v_cvt_pk_fp8_f32 v81, v12, v0 op_sel:[0,0,1]
	v_lshlrev_b32_e32 v0, 16, v39
	v_and_b32_e32 v3, 0xffff0000, v39
	v_cvt_pk_fp8_f32 v83, v2, v4
	v_mul_f32_e32 v0, 0x3e0293ee, v0
	v_mul_f32_e32 v3, 0x3e0293ee, v3
	v_mov_b32_e32 v82, v1
	v_lshlrev_b32_e32 v10, 16, v35
	v_cvt_pk_fp8_f32 v82, v0, v3
	v_and_b32_e32 v0, 0xffff0000, v35
	v_mul_f32_e32 v10, 0x3e0293ee, v10
	v_mul_f32_e32 v0, 0x3e0293ee, v0
	v_cvt_pk_fp8_f32 v83, v10, v0 op_sel:[0,0,1]
	v_lshlrev_b32_e32 v0, 16, v5
	v_lshlrev_b32_e32 v2, 16, v7
	v_and_b32_e32 v3, 0xffff0000, v5
	v_and_b32_e32 v4, 0xffff0000, v7
	v_mul_f32_e32 v0, 0x3e0293ee, v0
	v_mul_f32_e32 v2, 0x3e0293ee, v2
	v_mul_f32_e32 v3, 0x3e0293ee, v3
	v_mul_f32_e32 v4, 0x3e0293ee, v4
	v_mov_b32_e32 v84, v1
	v_mov_b32_e32 v85, v1
	v_cvt_pk_fp8_f32 v84, v0, v3
	v_cvt_pk_fp8_f32 v85, v2, v4
	v_lshlrev_b32_e32 v9, 16, v40
	v_and_b32_e32 v11, 0xffff0000, v40
	v_lshlrev_b32_e32 v5, 16, v6
	v_lshlrev_b32_e32 v7, 16, v8
	v_and_b32_e32 v6, 0xffff0000, v6
	v_and_b32_e32 v0, 0xffff0000, v8
	v_mul_f32_e32 v9, 0x3e0293ee, v9
	v_mul_f32_e32 v11, 0x3e0293ee, v11
	v_mul_f32_e32 v5, 0x3e0293ee, v5
	v_mul_f32_e32 v7, 0x3e0293ee, v7
	v_mul_f32_e32 v6, 0x3e0293ee, v6
	v_mul_f32_e32 v0, 0x3e0293ee, v0
	v_cvt_pk_fp8_f32 v82, v9, v11 op_sel:[0,0,1]
	v_cvt_pk_fp8_f32 v84, v5, v6 op_sel:[0,0,1]
	v_cvt_pk_fp8_f32 v85, v7, v0 op_sel:[0,0,1]
	s_waitcnt lgkmcnt(0)
	s_mov_b64 s[10:11], s[52:53]
	s_cmp_eq_u64 vcc, 0
	s_cbranch_scc1 .LBB0_991
; #define LAS __attribute__((address_space(3)))
; template <bool SLC, class Desc>
; __device__ __forceinline__ void attn_run_frag8(const i64_t (&qf)[4], const unsigned char* __restrict__ KF, const unsigned char* __restrict__ VF, const Desc& desc, int n,
;                                                int lo_in, int hi, int qi, AState& st, int lane) {
;     if (n <= 0) return;
;     Frag8 fa, fb, fc;
;     constexpr int NM = ~(1 << 30);
;     int d0 = desc(0), d1 = desc(n > 1 ? 1 : 0);
;     load_frag8(fa, KF, VF, SLC ? (d0 & 0xfffff) : (d0 & NM), lane);
;     load_frag8(fb, KF, VF, SLC ? (d1 & 0xfffff) : (d1 & NM), lane);
; __device__ __forceinline__ void nsa_unit(int unit, const bf16_t* proj, const bf16_t* kc, const bf16_t* vc, const bf16_t* gn, const float* cs, const float* sn, ...
;     ...
;     LAS int* list = (LAS int*)(wl + VBUF_BYTES + 4 * IMP_LD * 4 + 256);
;     int nslc;
;     { const int b = sel[lane], q = lane >> 4, cur0 = t0 >> 6;
;       const bool forced = (b == 0) | (b == cur0) | (b == cur0 - 1);
;       const bool valid = (b >= 0) & !(forced & (q > 0)); const unsigned long long mask = __ballot(valid);
;       const int idx = __popcll(mask & ((1ull << lane) - 1ull)); nslc = 2 * __popcll(mask);
;       if (valid) { const int qc = (forced ? 4 : q) | (b < cur0 ? (1 << 10) : 0);
;                    list[2 * idx] = (64 * b) | (qc << 20); list[2 * idx + 1] = (64 * b + 32) | (qc << 20); } }
;     asm volatile("s_waitcnt lgkmcnt(0)" ::: "memory");
;     astate_init(st);
;     { auto desc = [&](int i) { return __builtin_amdgcn_readfirstlane(list[i]); };
;       unsigned long long goff = (unsigned long long)g * S * 128; asm volatile("" : "+s"(goff));
;       attn_run_frag8<true>(q8, (const unsigned char*)kslf + goff, (const unsigned char*)kslf + ((size_t)8 << 20) + goff, desc, nslc, 0, tc, qi, st, lane); }
	v_mov_b32_e32 v0, s3
	ds_read_b64 v[2:3], v0 offset:13632
	s_bcnt1_i32_b64 s12, vcc
	s_lshl_b32 s54, s12, 1
	s_add_u32 s12, s69, s10
	s_addc_u32 s13, s70, s11
	s_add_u32 s10, s67, s10
	s_waitcnt lgkmcnt(0)
	v_readfirstlane_b32 s57, v2
	s_addc_u32 s11, s68, s11
	s_lshl_b32 s16, s57, 7
	s_and_b32 s14, s16, 0x7fff800
	s_add_u32 s14, s10, s14
	s_addc_u32 s15, s11, 0
	v_readfirstlane_b32 s92, v3
	v_lshl_add_u64 v[2:3], s[14:15], 0, v[120:121]
	s_and_b32 s14, s16, 0x7fff000
	s_add_u32 s14, s12, s14
	s_addc_u32 s15, s13, 0
	s_lshl_b32 s16, s92, 7
	v_lshl_add_u64 v[246:247], v[2:3], 0, v[120:121]
	global_load_dwordx4 v[138:141], v[246:247], off
	global_load_dwordx4 v[142:145], v[246:247], off offset:1024
	global_load_dwordx4 v[146:149], v[246:247], off offset:2048
	global_load_dwordx4 v[150:153], v[246:247], off offset:3072
	v_lshl_add_u64 v[2:3], s[14:15], 0, v[120:121]
	s_and_b32 s14, s16, 0x7fff800
	s_add_u32 s14, s10, s14
	s_addc_u32 s15, s11, 0
	global_load_dwordx2 v[90:91], v[2:3], off
	global_load_dwordx2 v[92:93], v[2:3], off offset:512
	global_load_dwordx2 v[94:95], v[2:3], off offset:1024
	global_load_dwordx2 v[96:97], v[2:3], off offset:1536
	global_load_dwordx2 v[104:105], v[2:3], off offset:2048
	global_load_dwordx2 v[102:103], v[2:3], off offset:2560
	global_load_dwordx2 v[100:101], v[2:3], off offset:3072
	global_load_dwordx2 v[98:99], v[2:3], off offset:3584
	v_lshl_add_u64 v[2:3], s[14:15], 0, v[120:121]
	s_and_b32 s14, s16, 0x7fff000
	s_add_u32 s14, s12, s14
	s_addc_u32 s15, s13, 0
	v_lshl_add_u64 v[246:247], v[2:3], 0, v[120:121]
	global_load_dwordx4 v[154:157], v[246:247], off
	global_load_dwordx4 v[158:161], v[246:247], off offset:1024
	global_load_dwordx4 v[162:165], v[246:247], off offset:2048
	global_load_dwordx4 v[166:169], v[246:247], off offset:3072
	v_lshl_add_u64 v[2:3], s[14:15], 0, v[120:121]
	global_load_dwordx2 v[106:107], v[2:3], off
	global_load_dwordx2 v[110:111], v[2:3], off offset:512
	global_load_dwordx2 v[112:113], v[2:3], off offset:1024
	global_load_dwordx2 v[116:117], v[2:3], off offset:1536
	global_load_dwordx2 v[136:137], v[2:3], off offset:2048
	global_load_dwordx2 v[134:135], v[2:3], off offset:2560
	global_load_dwordx2 v[114:115], v[2:3], off offset:3072
	global_load_dwordx2 v[108:109], v[2:3], off offset:3584
	v_mov_b32_e32 v2, v1
	v_mov_b32_e32 v3, v1
	v_mov_b32_e32 v0, v1
	v_mov_b64_e32 v[38:39], v[2:3]
	v_mov_b64_e32 v[42:43], v[2:3]
	v_mov_b64_e32 v[46:47], v[2:3]
	v_mov_b64_e32 v[50:51], v[2:3]
	v_mov_b64_e32 v[54:55], v[2:3]
	v_mov_b64_e32 v[58:59], v[2:3]
	v_mov_b64_e32 v[62:63], v[2:3]
	v_mov_b64_e32 v[66:67], v[2:3]
	v_lshl_add_u64 v[86:87], s[10:11], 0, v[120:121]
	v_lshl_add_u64 v[88:89], s[12:13], 0, v[120:121]
	s_add_i32 s55, s54, -1
	v_mov_b32_e32 v202, 0xf149f2ca
	v_mov_b32_e32 v203, 0
	s_mov_b32 s56, 4
	v_mov_b64_e32 v[36:37], v[0:1]
	v_mov_b64_e32 v[40:41], v[0:1]
	v_mov_b64_e32 v[44:45], v[0:1]
	v_mov_b64_e32 v[48:49], v[0:1]
	v_mov_b64_e32 v[52:53], v[0:1]
	v_mov_b64_e32 v[56:57], v[0:1]
	v_mov_b64_e32 v[60:61], v[0:1]
	v_mov_b64_e32 v[64:65], v[0:1]
	s_branch .LBB0_963

; template <bool SLC, bool NOMASK> ...
;     const int kq = lane >> 4;
;     const int pos0 = SLC ? (dcur & 0xfffff) : dcur;
;     const int lo = SLC ? ((((dcur >> 20) == qi) | ((dcur >> 20) == 4)) ? 0 : (1 << 30)) : lo_in;
;     load_frag8(nxt, KF, VF, SLC ? (dnext & 0xfffff) : dnext, lane);
;     f32x4 sa[2] = {(f32x4){0.f, 0.f, 0.f, 0.f}, (f32x4){0.f, 0.f, 0.f, 0.f}};
; #pragma unroll
;     for (int T = 0; T < 2; ++T)
; #pragma unroll
;         for (int s2 = 0; s2 < 4; ++s2) sa[T] = __builtin_amdgcn_mfma_f32_16x16x32_fp8_fp8(cur.k[T][s2], qf[s2], sa[T], 0, 0, 0);
;     float sc[8]; bool vd[8]; float mx = -1e30f;
;     const bool act = lo == 0 || !SLC;
;     if (NOMASK) {
; #pragma unroll
;         for (int j = 0; j < 8; ++j) { sc[j] = sa[j >> 2][j & 3]; vd[j] = act; }
;         mx = fmaxf(fmaxf(fmaxf(sc[0], sc[1]), fmaxf(sc[2], sc[3])), fmaxf(fmaxf(sc[4], sc[5]), fmaxf(sc[6], sc[7])));
;         mx = act ? mx : -1e30f;
;     } else {
; #pragma unroll
;         for (int T = 0; T < 2; ++T)
; #pragma unroll
;             for (int r = 0; r < 4; ++r) { const int p = pos0 + 16 * T + 4 * kq + r; const bool v = (p >= lo) & (p <= hi); const float x = sa[T][r];
;                 sc[4 * T + r] = x; vd[4 * T + r] = v; mx = v ? fmaxf(mx, x) : mx; }
;     }
;     if (__builtin_amdgcn_ballot_w64(mx > st.m + 4.f) != 0ull) {
;         mx = fmaxf(mx, __shfl_xor(mx, 16)); mx = fmaxf(mx, __shfl_xor(mx, 32));
;         const float mn = fmaxf(st.m, mx), alpha = __builtin_amdgcn_exp2f(st.m - mn); st.m = mn; st.l *= alpha;
; #pragma unroll
;         for (int j = 0; j < 8; ++j) st.o[j] = st.o[j] * alpha;
;     }
;     f32x4 pa, pb; float ps = 0.f;
;     const float mref = st.m - 4.f;
;     if (NOMASK) {
; #pragma unroll
;         for (int j = 0; j < 4; ++j) { pa[j] = __builtin_amdgcn_exp2f(sc[j] - mref); pb[j] = __builtin_amdgcn_exp2f(sc[4 + j] - mref); }
;         if (SLC) {
; #pragma unroll
;             for (int j = 0; j < 4; ++j) { pa[j] = act ? pa[j] : 0.f; pb[j] = act ? pb[j] : 0.f; }
;         }
; #pragma unroll
;         for (int j = 0; j < 4; ++j) ps += pa[j] + pb[j];
;     } else {
; #pragma unroll
;         for (int j = 0; j < 4; ++j) { pa[j] = vd[j] ? __builtin_amdgcn_exp2f(sc[j] - mref) : 0.f; pb[j] = vd[4 + j] ? __builtin_amdgcn_exp2f(sc[4 + j] - mref) : 0.f; ps += pa[j] + pb[j]; }
;     }
;     st.l += ps;
;     const u32x2 pw = pack8_fp8(pa, pb);
.LBB0_969:
	s_and_b32 s13, s12, 0xfffffbff
	s_cmp_eq_u32 s13, 4
	s_cselect_b64 s[10:11], -1, 0
	s_lshl_b32 s14, s66, 7
	s_and_b32 s50, s14, 0x7fff800
	v_lshl_add_u64 v[10:11], v[86:87], 0, s[50:51]
	s_and_b32 s50, s14, 0x7fff000
	v_lshl_add_u64 v[246:247], v[10:11], 0, v[120:121]
	global_load_dwordx4 v[186:189], v[246:247], off
	global_load_dwordx4 v[190:193], v[246:247], off offset:1024
	global_load_dwordx4 v[194:197], v[246:247], off offset:2048
	global_load_dwordx4 v[198:201], v[246:247], off offset:3072
	v_lshl_add_u64 v[10:11], v[88:89], 0, s[50:51]
	global_load_dwordx2 v[170:171], v[10:11], off
	global_load_dwordx2 v[172:173], v[10:11], off offset:512
	global_load_dwordx2 v[174:175], v[10:11], off offset:1024
	global_load_dwordx2 v[176:177], v[10:11], off offset:1536
	global_load_dwordx2 v[184:185], v[10:11], off offset:2048
	global_load_dwordx2 v[182:183], v[10:11], off offset:2560
	global_load_dwordx2 v[180:181], v[10:11], off offset:3072
	global_load_dwordx2 v[178:179], v[10:11], off offset:3584
	s_waitcnt vmcnt(32)
	v_mfma_f32_16x16x32_fp8_fp8 v[2:5], v[138:139], v[78:79], 0
	v_cmp_eq_u32_e32 vcc, s13, v209
	s_or_b64 s[10:11], s[10:11], vcc
	v_mov_b64_e32 v[74:75], v[38:39]
	v_mfma_f32_16x16x32_fp8_fp8 v[6:9], v[146:147], v[78:79], 0
	v_mov_b64_e32 v[70:71], v[42:43]
	v_mov_b64_e32 v[30:31], v[44:45]
	v_mov_b64_e32 v[26:27], v[48:49]
	v_mfma_f32_16x16x32_fp8_fp8 v[2:5], v[140:141], v[80:81], v[2:5]
	v_mov_b64_e32 v[22:23], v[52:53]
	v_mov_b64_e32 v[18:19], v[56:57]
	v_mov_b64_e32 v[14:15], v[60:61]
	v_mfma_f32_16x16x32_fp8_fp8 v[6:9], v[148:149], v[80:81], v[6:9]
	v_mov_b64_e32 v[72:73], v[36:37]
	v_mov_b64_e32 v[68:69], v[40:41]
	v_mov_b64_e32 v[32:33], v[46:47]
	v_mfma_f32_16x16x32_fp8_fp8 v[2:5], v[142:143], v[82:83], v[2:5]
	v_mov_b64_e32 v[28:29], v[50:51]
	v_mov_b64_e32 v[24:25], v[54:55]
	v_mov_b64_e32 v[20:21], v[58:59]
	v_mfma_f32_16x16x32_fp8_fp8 v[6:9], v[150:151], v[82:83], v[6:9]
	v_mov_b64_e32 v[16:17], v[62:63]
	v_mov_b32_e32 v133, v203
	v_mfma_f32_16x16x32_fp8_fp8 v[2:5], v[144:145], v[84:85], v[2:5]
	v_mfma_f32_16x16x32_fp8_fp8 v[6:9], v[152:153], v[84:85], v[6:9]
	s_nop 5
	v_max_f32_e32 v0, v3, v3
	v_max_f32_e32 v10, v2, v2
	v_max_f32_e32 v0, v10, v0
	v_max_f32_e32 v10, v5, v5
	v_max_f32_e32 v11, v4, v4
	v_max_f32_e32 v10, v11, v10
	v_max_f32_e32 v11, v9, v9
	v_max_f32_e32 v12, v8, v8
	v_max_f32_e32 v11, v12, v11
	v_max3_f32 v11, v6, v7, v11
	v_max3_f32 v0, v0, v10, v11
	v_cndmask_b32_e64 v34, v220, v0, s[10:11]
	v_mov_b64_e32 v[10:11], v[64:65]
	v_cmp_gt_f32_e32 vcc, v34, v204
	v_mov_b32_e32 v0, v202
	v_mov_b64_e32 v[12:13], v[66:67]
	s_cbranch_vccz .LBB0_971
	ds_bpermute_b32 v0, v225, v34
	v_max_f32_e32 v10, v34, v34
	s_waitcnt lgkmcnt(0)
	v_max_f32_e32 v0, v0, v0
	v_max_f32_e32 v0, v10, v0
	ds_bpermute_b32 v10, v224, v0
	s_waitcnt lgkmcnt(0)
	v_max3_f32 v0, v202, v0, v10
	v_sub_f32_e32 v10, v202, v0
	v_exp_f32_e32 v34, v10
	s_nop 0
	v_mul_f32_e32 v133, v203, v34
	v_pk_mul_f32 v[12:13], v[66:67], v[34:35] op_sel_hi:[1,0]
	v_pk_mul_f32 v[10:11], v[64:65], v[34:35] op_sel_hi:[1,0]
	v_pk_mul_f32 v[16:17], v[62:63], v[34:35] op_sel_hi:[1,0]
	v_pk_mul_f32 v[14:15], v[60:61], v[34:35] op_sel_hi:[1,0]
	v_pk_mul_f32 v[20:21], v[58:59], v[34:35] op_sel_hi:[1,0]
	v_pk_mul_f32 v[18:19], v[56:57], v[34:35] op_sel_hi:[1,0]
	v_pk_mul_f32 v[24:25], v[54:55], v[34:35] op_sel_hi:[1,0]
	v_pk_mul_f32 v[22:23], v[52:53], v[34:35] op_sel_hi:[1,0]
	v_pk_mul_f32 v[28:29], v[50:51], v[34:35] op_sel_hi:[1,0]
	v_pk_mul_f32 v[26:27], v[48:49], v[34:35] op_sel_hi:[1,0]
	v_pk_mul_f32 v[32:33], v[46:47], v[34:35] op_sel_hi:[1,0]
	v_pk_mul_f32 v[30:31], v[44:45], v[34:35] op_sel_hi:[1,0]
	v_pk_mul_f32 v[70:71], v[42:43], v[34:35] op_sel_hi:[1,0]
	v_pk_mul_f32 v[68:69], v[40:41], v[34:35] op_sel_hi:[1,0]
	v_pk_mul_f32 v[74:75], v[38:39], v[34:35] op_sel_hi:[1,0]
	v_pk_mul_f32 v[72:73], v[36:37], v[34:35] op_sel_hi:[1,0]
.LBB0_971:
	v_add_f32_e32 v34, -4.0, v0
	v_sub_f32_e32 v2, v2, v34
	v_sub_f32_e32 v6, v6, v34
	v_sub_f32_e32 v3, v3, v34
	v_sub_f32_e32 v7, v7, v34
	v_exp_f32_e32 v2, v2
	v_exp_f32_e32 v6, v6
	v_exp_f32_e32 v3, v3
	v_exp_f32_e32 v7, v7
	v_sub_f32_e32 v4, v4, v34
	v_sub_f32_e32 v8, v8, v34
	v_sub_f32_e32 v5, v5, v34
	v_sub_f32_e32 v9, v9, v34
	v_exp_f32_e32 v4, v4
	v_exp_f32_e32 v8, v8
	v_exp_f32_e32 v5, v5
	v_exp_f32_e32 v9, v9
	v_cndmask_b32_e64 v34, 0, v2, s[10:11]
	v_cndmask_b32_e64 v6, 0, v6, s[10:11]
	v_cndmask_b32_e64 v35, 0, v3, s[10:11]
	v_cndmask_b32_e64 v7, 0, v7, s[10:11]
	v_mov_b32_e32 v2, v1
	v_mov_b32_e32 v3, v1
	v_cvt_pk_fp8_f32 v2, v34, v35
	v_cvt_pk_fp8_f32 v3, v6, v7
	v_cndmask_b32_e64 v4, 0, v4, s[10:11]
	v_cndmask_b32_e64 v205, 0, v8, s[10:11]
	v_cndmask_b32_e64 v5, 0, v5, s[10:11]
	v_cndmask_b32_e64 v227, 0, v9, s[10:11]
	v_add_f32_e32 v6, v34, v6
	v_cvt_pk_fp8_f32 v2, v4, v5 op_sel:[0,0,1]
	v_cvt_pk_fp8_f32 v3, v205, v227 op_sel:[0,0,1]
	v_add_f32_e32 v6, 0, v6
	v_add_f32_e32 v7, v35, v7
	v_add_f32_e32 v6, v7, v6
	v_add_f32_e32 v4, v4, v205
	v_add_f32_e32 v4, v4, v6
	v_add_f32_e32 v5, v5, v227
	v_add_f32_e32 v4, v5, v4
	s_waitcnt vmcnt(31)
	v_mfma_f32_16x16x32_fp8_fp8 v[8:11], v[90:91], v[2:3], v[10:13]
	v_add_f32_e32 v133, v133, v4
	s_waitcnt vmcnt(30)
	v_mfma_f32_16x16x32_fp8_fp8 v[12:15], v[92:93], v[2:3], v[14:17]
	s_waitcnt vmcnt(29)
	v_mfma_f32_16x16x32_fp8_fp8 v[16:19], v[94:95], v[2:3], v[18:21]
	s_waitcnt vmcnt(28)
	v_mfma_f32_16x16x32_fp8_fp8 v[20:23], v[96:97], v[2:3], v[22:25]
	s_waitcnt vmcnt(27)
	v_mfma_f32_16x16x32_fp8_fp8 v[24:27], v[104:105], v[2:3], v[26:29]
	s_waitcnt vmcnt(26)
	v_mfma_f32_16x16x32_fp8_fp8 v[32:35], v[102:103], v[2:3], v[30:33]
	s_waitcnt vmcnt(25)
	v_mfma_f32_16x16x32_fp8_fp8 v[28:31], v[100:101], v[2:3], v[68:71]
	s_waitcnt vmcnt(24)
	v_mfma_f32_16x16x32_fp8_fp8 v[4:7], v[98:99], v[2:3], v[72:75]
	s_branch .LBB0_965
; template <bool SLC, bool NOMASK> ...
;     const int kq = lane >> 4;
;     const int pos0 = SLC ? (dcur & 0xfffff) : dcur;
;     const int lo = SLC ? ((((dcur >> 20) == qi) | ((dcur >> 20) == 4)) ? 0 : (1 << 30)) : lo_in;
;     load_frag8(nxt, KF, VF, SLC ? (dnext & 0xfffff) : dnext, lane);
;     f32x4 sa[2] = {(f32x4){0.f, 0.f, 0.f, 0.f}, (f32x4){0.f, 0.f, 0.f, 0.f}};
; #pragma unroll
;     for (int T = 0; T < 2; ++T)
; #pragma unroll
;         for (int s2 = 0; s2 < 4; ++s2) sa[T] = __builtin_amdgcn_mfma_f32_16x16x32_fp8_fp8(cur.k[T][s2], qf[s2], sa[T], 0, 0, 0);
;     float sc[8]; bool vd[8]; float mx = -1e30f;
;     const bool act = lo == 0 || !SLC;
;     if (NOMASK) {
; #pragma unroll
;         for (int j = 0; j < 8; ++j) { sc[j] = sa[j >> 2][j & 3]; vd[j] = act; }
;         mx = fmaxf(fmaxf(fmaxf(sc[0], sc[1]), fmaxf(sc[2], sc[3])), fmaxf(fmaxf(sc[4], sc[5]), fmaxf(sc[6], sc[7])));
;         mx = act ? mx : -1e30f;
;     } else {
; #pragma unroll
;         for (int T = 0; T < 2; ++T)
; #pragma unroll
;             for (int r = 0; r < 4; ++r) { const int p = pos0 + 16 * T + 4 * kq + r; const bool v = (p >= lo) & (p <= hi); const float x = sa[T][r];
;                 sc[4 * T + r] = x; vd[4 * T + r] = v; mx = v ? fmaxf(mx, x) : mx; }
;     }
;     if (__builtin_amdgcn_ballot_w64(mx > st.m + 4.f) != 0ull) {
;         mx = fmaxf(mx, __shfl_xor(mx, 16)); mx = fmaxf(mx, __shfl_xor(mx, 32));
;         const float mn = fmaxf(st.m, mx), alpha = __builtin_amdgcn_exp2f(st.m - mn); st.m = mn; st.l *= alpha;
; #pragma unroll
;         for (int j = 0; j < 8; ++j) st.o[j] = st.o[j] * alpha;
;     }
;     f32x4 pa, pb; float ps = 0.f;
;     const float mref = st.m - 4.f;
;     if (NOMASK) {
; #pragma unroll
;         for (int j = 0; j < 4; ++j) { pa[j] = __builtin_amdgcn_exp2f(sc[j] - mref); pb[j] = __builtin_amdgcn_exp2f(sc[4 + j] - mref); }
;         if (SLC) {
; #pragma unroll
;             for (int j = 0; j < 4; ++j) { pa[j] = act ? pa[j] : 0.f; pb[j] = act ? pb[j] : 0.f; }
;         }
; #pragma unroll
;         for (int j = 0; j < 4; ++j) ps += pa[j] + pb[j];
;     } else {
; #pragma unroll
;         for (int j = 0; j < 4; ++j) { pa[j] = vd[j] ? __builtin_amdgcn_exp2f(sc[j] - mref) : 0.f; pb[j] = vd[4 + j] ? __builtin_amdgcn_exp2f(sc[4 + j] - mref) : 0.f; ps += pa[j] + pb[j]; }
;     }
;     st.l += ps;
;     const u32x2 pw = pack8_fp8(pa, pb);
.LBB0_972:
	s_cmp_eq_u32 s12, 4
	s_cselect_b64 s[10:11], -1, 0
	s_lshl_b32 s13, s66, 7
	s_and_b32 s50, s13, 0x7fff800
	v_lshl_add_u64 v[10:11], v[86:87], 0, s[50:51]
	s_and_b32 s50, s13, 0x7fff000
	v_lshl_add_u64 v[246:247], v[10:11], 0, v[120:121]
	global_load_dwordx4 v[186:189], v[246:247], off
	global_load_dwordx4 v[190:193], v[246:247], off offset:1024
	global_load_dwordx4 v[194:197], v[246:247], off offset:2048
	global_load_dwordx4 v[198:201], v[246:247], off offset:3072
	v_lshl_add_u64 v[10:11], v[88:89], 0, s[50:51]
	global_load_dwordx2 v[170:171], v[10:11], off
	global_load_dwordx2 v[172:173], v[10:11], off offset:512
	global_load_dwordx2 v[174:175], v[10:11], off offset:1024
	global_load_dwordx2 v[176:177], v[10:11], off offset:1536
	global_load_dwordx2 v[184:185], v[10:11], off offset:2048
	global_load_dwordx2 v[182:183], v[10:11], off offset:2560
	global_load_dwordx2 v[180:181], v[10:11], off offset:3072
	global_load_dwordx2 v[178:179], v[10:11], off offset:3584
	s_waitcnt vmcnt(32)
	v_mfma_f32_16x16x32_fp8_fp8 v[2:5], v[138:139], v[78:79], 0
	s_and_b32 s13, s57, 0xfffff
	v_cmp_eq_u32_e32 vcc, s12, v209
	v_add_u32_e32 v0, s13, v210
	v_mfma_f32_16x16x32_fp8_fp8 v[2:5], v[140:141], v[80:81], v[2:5]
	s_or_b64 s[18:19], s[10:11], vcc
	v_cmp_le_i32_e32 vcc, v0, v132
	s_and_b64 s[16:17], s[18:19], vcc
	v_mfma_f32_16x16x32_fp8_fp8 v[2:5], v[142:143], v[82:83], v[2:5]
	v_cmp_lt_i32_e32 vcc, v0, v132
	s_and_b64 s[12:13], s[18:19], vcc
	v_mfma_f32_16x16x32_fp8_fp8 v[6:9], v[146:147], v[78:79], 0
	v_mfma_f32_16x16x32_fp8_fp8 v[2:5], v[144:145], v[84:85], v[2:5]
	v_mfma_f32_16x16x32_fp8_fp8 v[6:9], v[148:149], v[80:81], v[6:9]
	v_mfma_f32_16x16x32_fp8_fp8 v[6:9], v[150:151], v[82:83], v[6:9]
	s_nop 3
	v_max_f32_e32 v10, v2, v2
	v_max_f32_e32 v10, 0xf149f2ca, v10
	v_cndmask_b32_e64 v10, v220, v10, s[16:17]
	v_max_f32_e32 v11, v3, v3
	v_max_f32_e32 v11, v10, v11
	v_cndmask_b32_e64 v10, v10, v11, s[12:13]
	v_add_u32_e32 v11, 2, v0
	v_cmp_le_i32_e32 vcc, v11, v132
	v_max_f32_e32 v11, v4, v4
	v_max_f32_e32 v11, v10, v11
	s_and_b64 s[14:15], s[18:19], vcc
	v_mfma_f32_16x16x32_fp8_fp8 v[6:9], v[152:153], v[84:85], v[6:9]
	v_cndmask_b32_e64 v10, v10, v11, s[14:15]
	v_add_u32_e32 v11, 3, v0
	v_cmp_le_i32_e32 vcc, v11, v132
	v_max_f32_e32 v11, v5, v5
	v_max_f32_e32 v11, v10, v11
	s_and_b64 s[10:11], s[18:19], vcc
	v_cndmask_b32_e64 v10, v10, v11, s[10:11]
	v_add_u32_e32 v11, 16, v0
	v_cmp_le_i32_e32 vcc, v11, v132
	v_max_f32_e32 v11, v6, v6
	v_max_f32_e32 v11, v10, v11
	s_and_b64 s[24:25], s[18:19], vcc
	v_cndmask_b32_e64 v10, v10, v11, s[24:25]
	v_add_u32_e32 v11, 17, v0
	v_cmp_le_i32_e32 vcc, v11, v132
	v_max_f32_e32 v11, v10, v10
	v_max_f32_e32 v12, v7, v7
	v_max_f32_e32 v11, v11, v12
	s_and_b64 s[20:21], s[18:19], vcc
	v_cndmask_b32_e64 v10, v10, v11, s[20:21]
	v_add_u32_e32 v11, 18, v0
	v_cmp_le_i32_e32 vcc, v11, v132
	v_max_f32_e32 v11, v10, v10
	v_max_f32_e32 v12, v8, v8
	v_max_f32_e32 v11, v11, v12
	s_and_b64 s[22:23], s[18:19], vcc
	v_cndmask_b32_e64 v10, v10, v11, s[22:23]
	v_add_u32_e32 v0, 19, v0
	v_cmp_le_i32_e32 vcc, v0, v132
	v_max_f32_e32 v0, v10, v10
	v_max_f32_e32 v11, v9, v9
	v_max_f32_e32 v0, v0, v11
	s_and_b64 s[18:19], s[18:19], vcc
	v_cndmask_b32_e64 v0, v10, v0, s[18:19]
	v_cmp_gt_f32_e32 vcc, v0, v204
	s_cbranch_vccz .LBB0_974
	ds_bpermute_b32 v10, v225, v0
	v_max_f32_e32 v0, v0, v0
	s_waitcnt lgkmcnt(0)
	v_max_f32_e32 v10, v10, v10
	v_max_f32_e32 v0, v0, v10
	ds_bpermute_b32 v10, v224, v0
	s_waitcnt lgkmcnt(0)
	v_max3_f32 v10, v202, v0, v10
	v_sub_f32_e32 v0, v202, v10
	v_exp_f32_e32 v0, v0
	v_mov_b32_e32 v202, v10
	v_mul_f32_e32 v203, v203, v0
	v_pk_mul_f32 v[66:67], v[66:67], v[0:1] op_sel_hi:[1,0]
	v_pk_mul_f32 v[64:65], v[64:65], v[0:1] op_sel_hi:[1,0]
	v_pk_mul_f32 v[62:63], v[62:63], v[0:1] op_sel_hi:[1,0]
	v_pk_mul_f32 v[60:61], v[60:61], v[0:1] op_sel_hi:[1,0]
	v_pk_mul_f32 v[58:59], v[58:59], v[0:1] op_sel_hi:[1,0]
	v_pk_mul_f32 v[56:57], v[56:57], v[0:1] op_sel_hi:[1,0]
	v_pk_mul_f32 v[54:55], v[54:55], v[0:1] op_sel_hi:[1,0]
	v_pk_mul_f32 v[52:53], v[52:53], v[0:1] op_sel_hi:[1,0]
	v_pk_mul_f32 v[50:51], v[50:51], v[0:1] op_sel_hi:[1,0]
	v_pk_mul_f32 v[48:49], v[48:49], v[0:1] op_sel_hi:[1,0]
	v_pk_mul_f32 v[46:47], v[46:47], v[0:1] op_sel_hi:[1,0]
	v_pk_mul_f32 v[44:45], v[44:45], v[0:1] op_sel_hi:[1,0]
	v_pk_mul_f32 v[42:43], v[42:43], v[0:1] op_sel_hi:[1,0]
	v_pk_mul_f32 v[40:41], v[40:41], v[0:1] op_sel_hi:[1,0]
	v_pk_mul_f32 v[38:39], v[38:39], v[0:1] op_sel_hi:[1,0]
	v_pk_mul_f32 v[36:37], v[36:37], v[0:1] op_sel_hi:[1,0]
.LBB0_974:
	v_add_f32_e32 v0, -4.0, v202
	v_sub_f32_e32 v2, v2, v0
	v_exp_f32_e32 v2, v2
	v_sub_f32_e32 v6, v6, v0
	v_exp_f32_e32 v6, v6
	v_sub_f32_e32 v4, v4, v0
	v_cndmask_b32_e64 v28, 0, v2, s[16:17]
	v_sub_f32_e32 v2, v3, v0
	v_exp_f32_e32 v2, v2
	v_sub_f32_e32 v3, v7, v0
	v_exp_f32_e32 v3, v3
	v_sub_f32_e32 v7, v8, v0
	v_cndmask_b32_e64 v29, 0, v2, s[12:13]
	v_sub_f32_e32 v2, v5, v0
	v_sub_f32_e32 v0, v9, v0
	v_cndmask_b32_e64 v6, 0, v6, s[24:25]
	v_exp_f32_e32 v4, v4
	v_exp_f32_e32 v7, v7
	v_cndmask_b32_e64 v30, 0, v3, s[20:21]
	v_exp_f32_e32 v5, v2
	v_exp_f32_e32 v0, v0
	v_mov_b32_e32 v2, v1
	v_mov_b32_e32 v3, v1
	v_cvt_pk_fp8_f32 v2, v28, v29
	v_cvt_pk_fp8_f32 v3, v6, v30
	v_cndmask_b32_e64 v4, 0, v4, s[14:15]
	v_cndmask_b32_e64 v7, 0, v7, s[22:23]
	v_cndmask_b32_e64 v5, 0, v5, s[10:11]
	v_cndmask_b32_e64 v0, 0, v0, s[18:19]
	v_cvt_pk_fp8_f32 v2, v4, v5 op_sel:[0,0,1]
	v_cvt_pk_fp8_f32 v3, v7, v0 op_sel:[0,0,1]
	v_add_f32_e32 v6, v28, v6
	v_add_f32_e32 v6, 0, v6
	v_add_f32_e32 v28, v29, v30
	v_add_f32_e32 v6, v28, v6
	v_add_f32_e32 v4, v4, v7
	v_add_f32_e32 v4, v4, v6
	v_add_f32_e32 v0, v5, v0
	s_waitcnt vmcnt(31)
	v_mfma_f32_16x16x32_fp8_fp8 v[8:11], v[90:91], v[2:3], v[64:67]
	v_add_f32_e32 v0, v0, v4
	v_add_f32_e32 v133, v203, v0
	v_mov_b32_e32 v0, v202
	s_waitcnt vmcnt(30)
	v_mfma_f32_16x16x32_fp8_fp8 v[12:15], v[92:93], v[2:3], v[60:63]
	s_waitcnt vmcnt(29)
	v_mfma_f32_16x16x32_fp8_fp8 v[16:19], v[94:95], v[2:3], v[56:59]
	s_waitcnt vmcnt(28)
	v_mfma_f32_16x16x32_fp8_fp8 v[20:23], v[96:97], v[2:3], v[52:55]
	s_waitcnt vmcnt(27)
	v_mfma_f32_16x16x32_fp8_fp8 v[24:27], v[104:105], v[2:3], v[48:51]
	s_waitcnt vmcnt(26)
	v_mfma_f32_16x16x32_fp8_fp8 v[32:35], v[102:103], v[2:3], v[44:47]
	s_waitcnt vmcnt(25)
	v_mfma_f32_16x16x32_fp8_fp8 v[28:31], v[100:101], v[2:3], v[40:43]
	s_waitcnt vmcnt(24)
	v_mfma_f32_16x16x32_fp8_fp8 v[4:7], v[98:99], v[2:3], v[36:39]
	s_add_i32 s10, s56, -3
	s_cmp_ge_u32 s10, s54
	s_mov_b64 s[10:11], -1
	s_cbranch_scc0 .LBB0_966

; template <bool SLC, bool NOMASK> ...
;     const int kq = lane >> 4;
;     const int pos0 = SLC ? (dcur & 0xfffff) : dcur;
;     const int lo = SLC ? ((((dcur >> 20) == qi) | ((dcur >> 20) == 4)) ? 0 : (1 << 30)) : lo_in;
;     load_frag8(nxt, KF, VF, SLC ? (dnext & 0xfffff) : dnext, lane);
;     f32x4 sa[2] = {(f32x4){0.f, 0.f, 0.f, 0.f}, (f32x4){0.f, 0.f, 0.f, 0.f}};
; #pragma unroll
;     for (int T = 0; T < 2; ++T)
; #pragma unroll
;         for (int s2 = 0; s2 < 4; ++s2) sa[T] = __builtin_amdgcn_mfma_f32_16x16x32_fp8_fp8(cur.k[T][s2], qf[s2], sa[T], 0, 0, 0);
;     float sc[8]; bool vd[8]; float mx = -1e30f;
;     const bool act = lo == 0 || !SLC;
;     if (NOMASK) {
; #pragma unroll
;         for (int j = 0; j < 8; ++j) { sc[j] = sa[j >> 2][j & 3]; vd[j] = act; }
;         mx = fmaxf(fmaxf(fmaxf(sc[0], sc[1]), fmaxf(sc[2], sc[3])), fmaxf(fmaxf(sc[4], sc[5]), fmaxf(sc[6], sc[7])));
;         mx = act ? mx : -1e30f;
;     } else {
; #pragma unroll
;         for (int T = 0; T < 2; ++T)
; #pragma unroll
;             for (int r = 0; r < 4; ++r) { const int p = pos0 + 16 * T + 4 * kq + r; const bool v = (p >= lo) & (p <= hi); const float x = sa[T][r];
;                 sc[4 * T + r] = x; vd[4 * T + r] = v; mx = v ? fmaxf(mx, x) : mx; }
;     }
;     if (__builtin_amdgcn_ballot_w64(mx > st.m + 4.f) != 0ull) {
;         mx = fmaxf(mx, __shfl_xor(mx, 16)); mx = fmaxf(mx, __shfl_xor(mx, 32));
;         const float mn = fmaxf(st.m, mx), alpha = __builtin_amdgcn_exp2f(st.m - mn); st.m = mn; st.l *= alpha;
; #pragma unroll
;         for (int j = 0; j < 8; ++j) st.o[j] = st.o[j] * alpha;
;     }
;     f32x4 pa, pb; float ps = 0.f;
;     const float mref = st.m - 4.f;
;     if (NOMASK) {
; #pragma unroll
;         for (int j = 0; j < 4; ++j) { pa[j] = __builtin_amdgcn_exp2f(sc[j] - mref); pb[j] = __builtin_amdgcn_exp2f(sc[4 + j] - mref); }
;         if (SLC) {
; #pragma unroll
;             for (int j = 0; j < 4; ++j) { pa[j] = act ? pa[j] : 0.f; pb[j] = act ? pb[j] : 0.f; }
;         }
; #pragma unroll
;         for (int j = 0; j < 4; ++j) ps += pa[j] + pb[j];
;     } else {
; #pragma unroll
;         for (int j = 0; j < 4; ++j) { pa[j] = vd[j] ? __builtin_amdgcn_exp2f(sc[j] - mref) : 0.f; pb[j] = vd[4 + j] ? __builtin_amdgcn_exp2f(sc[4 + j] - mref) : 0.f; ps += pa[j] + pb[j]; }
;     }
;     st.l += ps;
;     const u32x2 pw = pack8_fp8(pa, pb);
.LBB0_976:
	s_and_b32 s13, s12, 0xfffffbff
	s_cmp_eq_u32 s13, 4
	s_cselect_b64 s[10:11], -1, 0
	s_lshl_b32 s14, s57, 7
	s_and_b32 s50, s14, 0x7fff800
	v_lshl_add_u64 v[44:45], v[86:87], 0, s[50:51]
	s_and_b32 s50, s14, 0x7fff000
	v_lshl_add_u64 v[246:247], v[44:45], 0, v[120:121]
	global_load_dwordx4 v[138:141], v[246:247], off
	global_load_dwordx4 v[142:145], v[246:247], off offset:1024
	global_load_dwordx4 v[146:149], v[246:247], off offset:2048
	global_load_dwordx4 v[150:153], v[246:247], off offset:3072
	v_lshl_add_u64 v[44:45], v[88:89], 0, s[50:51]
	global_load_dwordx2 v[90:91], v[44:45], off
	global_load_dwordx2 v[92:93], v[44:45], off offset:512
	global_load_dwordx2 v[94:95], v[44:45], off offset:1024
	global_load_dwordx2 v[96:97], v[44:45], off offset:1536
	global_load_dwordx2 v[104:105], v[44:45], off offset:2048
	global_load_dwordx2 v[102:103], v[44:45], off offset:2560
	global_load_dwordx2 v[100:101], v[44:45], off offset:3072
	global_load_dwordx2 v[98:99], v[44:45], off offset:3584
	s_waitcnt vmcnt(32)
	v_mfma_f32_16x16x32_fp8_fp8 v[36:39], v[154:155], v[78:79], 0
	v_cmp_eq_u32_e32 vcc, s13, v209
	s_or_b64 s[10:11], s[10:11], vcc
	v_mov_b64_e32 v[74:75], v[6:7]
	v_mfma_f32_16x16x32_fp8_fp8 v[40:43], v[162:163], v[78:79], 0
	v_mov_b64_e32 v[70:71], v[30:31]
	v_mov_b64_e32 v[66:67], v[34:35]
	v_mov_b64_e32 v[62:63], v[26:27]
	v_mfma_f32_16x16x32_fp8_fp8 v[36:39], v[156:157], v[80:81], v[36:39]
	v_mov_b64_e32 v[58:59], v[22:23]
	v_mov_b64_e32 v[54:55], v[18:19]
	v_mov_b64_e32 v[50:51], v[14:15]
	v_mfma_f32_16x16x32_fp8_fp8 v[40:43], v[164:165], v[80:81], v[40:43]
	v_mov_b32_e32 v203, v0
	v_mov_b64_e32 v[72:73], v[4:5]
	v_mov_b64_e32 v[68:69], v[28:29]
	v_mfma_f32_16x16x32_fp8_fp8 v[36:39], v[158:159], v[82:83], v[36:39]
	v_mov_b64_e32 v[64:65], v[32:33]
	v_mov_b64_e32 v[60:61], v[24:25]
	v_mov_b64_e32 v[56:57], v[20:21]
	v_mfma_f32_16x16x32_fp8_fp8 v[40:43], v[166:167], v[82:83], v[40:43]
	v_mov_b64_e32 v[52:53], v[16:17]
	v_mov_b64_e32 v[48:49], v[12:13]
	v_mfma_f32_16x16x32_fp8_fp8 v[36:39], v[160:161], v[84:85], v[36:39]
	v_mfma_f32_16x16x32_fp8_fp8 v[40:43], v[168:169], v[84:85], v[40:43]
	s_nop 5
	v_max_f32_e32 v3, v37, v37
	v_max_f32_e32 v44, v36, v36
	v_max_f32_e32 v3, v44, v3
	v_max_f32_e32 v44, v39, v39
	v_max_f32_e32 v45, v38, v38
	v_max_f32_e32 v44, v45, v44
	v_max_f32_e32 v45, v43, v43
	v_max_f32_e32 v46, v42, v42
	v_max_f32_e32 v45, v46, v45
	v_max3_f32 v45, v40, v41, v45
	v_max3_f32 v3, v3, v44, v45
	v_cndmask_b32_e64 v202, v220, v3, s[10:11]
	v_mov_b64_e32 v[46:47], v[10:11]
	v_cmp_gt_f32_e32 vcc, v202, v2
	v_mov_b64_e32 v[44:45], v[8:9]
	v_mov_b32_e32 v3, v133
	s_cbranch_vccz .LBB0_978
	ds_bpermute_b32 v3, v225, v202
	v_max_f32_e32 v44, v202, v202
	s_waitcnt lgkmcnt(0)
	v_max_f32_e32 v3, v3, v3
	v_max_f32_e32 v3, v44, v3
	ds_bpermute_b32 v44, v224, v3
	s_waitcnt lgkmcnt(0)
	v_max3_f32 v203, v0, v3, v44
	v_sub_f32_e32 v3, v0, v203
	v_exp_f32_e32 v72, v3
	s_nop 0
	v_mul_f32_e32 v3, v133, v72
	v_pk_mul_f32 v[46:47], v[10:11], v[72:73] op_sel_hi:[1,0]
	v_pk_mul_f32 v[44:45], v[8:9], v[72:73] op_sel_hi:[1,0]
	v_pk_mul_f32 v[50:51], v[14:15], v[72:73] op_sel_hi:[1,0]
	v_pk_mul_f32 v[48:49], v[12:13], v[72:73] op_sel_hi:[1,0]
	v_pk_mul_f32 v[54:55], v[18:19], v[72:73] op_sel_hi:[1,0]
	v_pk_mul_f32 v[52:53], v[16:17], v[72:73] op_sel_hi:[1,0]
	v_pk_mul_f32 v[58:59], v[22:23], v[72:73] op_sel_hi:[1,0]
	v_pk_mul_f32 v[56:57], v[20:21], v[72:73] op_sel_hi:[1,0]
	v_pk_mul_f32 v[62:63], v[26:27], v[72:73] op_sel_hi:[1,0]
	v_pk_mul_f32 v[60:61], v[24:25], v[72:73] op_sel_hi:[1,0]
	v_pk_mul_f32 v[66:67], v[34:35], v[72:73] op_sel_hi:[1,0]
	v_pk_mul_f32 v[64:65], v[32:33], v[72:73] op_sel_hi:[1,0]
	v_pk_mul_f32 v[70:71], v[30:31], v[72:73] op_sel_hi:[1,0]
	v_pk_mul_f32 v[68:69], v[28:29], v[72:73] op_sel_hi:[1,0]
	v_pk_mul_f32 v[74:75], v[6:7], v[72:73] op_sel_hi:[1,0]
	v_pk_mul_f32 v[72:73], v[4:5], v[72:73] op_sel_hi:[1,0]
.LBB0_978:
	v_add_f32_e32 v202, -4.0, v203
	v_sub_f32_e32 v36, v36, v202
	v_sub_f32_e32 v40, v40, v202
	v_sub_f32_e32 v37, v37, v202
	v_sub_f32_e32 v41, v41, v202
	v_exp_f32_e32 v36, v36
	v_exp_f32_e32 v40, v40
	v_exp_f32_e32 v37, v37
	v_exp_f32_e32 v41, v41
	v_sub_f32_e32 v38, v38, v202
	v_sub_f32_e32 v42, v42, v202
	v_sub_f32_e32 v39, v39, v202
	v_sub_f32_e32 v43, v43, v202
	v_exp_f32_e32 v38, v38
	v_exp_f32_e32 v42, v42
	v_exp_f32_e32 v39, v39
	v_exp_f32_e32 v43, v43
	v_cndmask_b32_e64 v202, 0, v36, s[10:11]
	v_cndmask_b32_e64 v204, 0, v40, s[10:11]
	v_cndmask_b32_e64 v205, 0, v37, s[10:11]
	v_cndmask_b32_e64 v227, 0, v41, s[10:11]
	v_mov_b32_e32 v228, v1
	v_mov_b32_e32 v229, v1
	v_cvt_pk_fp8_f32 v228, v202, v205
	v_cvt_pk_fp8_f32 v229, v204, v227
	v_cndmask_b32_e64 v230, 0, v38, s[10:11]
	v_cndmask_b32_e64 v231, 0, v42, s[10:11]
	v_cndmask_b32_e64 v232, 0, v39, s[10:11]
	v_cndmask_b32_e64 v233, 0, v43, s[10:11]
	v_cvt_pk_fp8_f32 v228, v230, v232 op_sel:[0,0,1]
	v_cvt_pk_fp8_f32 v229, v231, v233 op_sel:[0,0,1]
	s_nop 0
	s_waitcnt vmcnt(31)
	v_mfma_f32_16x16x32_fp8_fp8 v[40:43], v[110:111], v[228:229], v[48:51]
	s_waitcnt vmcnt(30)
	v_mfma_f32_16x16x32_fp8_fp8 v[48:51], v[116:117], v[228:229], v[56:59]
	s_nop 2
	v_add_f32_e32 v56, v202, v204
	s_waitcnt vmcnt(29)
	v_mfma_f32_16x16x32_fp8_fp8 v[36:39], v[106:107], v[228:229], v[44:47]
	s_waitcnt vmcnt(28)
	v_mfma_f32_16x16x32_fp8_fp8 v[44:47], v[112:113], v[228:229], v[52:55]
	s_waitcnt vmcnt(27)
	v_mfma_f32_16x16x32_fp8_fp8 v[52:55], v[136:137], v[228:229], v[60:63]
	s_nop 2
	v_add_f32_e32 v60, 0, v56
	v_add_f32_e32 v61, v205, v227
	v_add_f32_e32 v60, v61, v60
	v_add_f32_e32 v61, v230, v231
	s_waitcnt vmcnt(26)
	v_mfma_f32_16x16x32_fp8_fp8 v[56:59], v[134:135], v[228:229], v[64:67]
	s_nop 2
	v_add_f32_e32 v64, v61, v60
	v_add_f32_e32 v65, v232, v233
	v_add_f32_e32 v64, v65, v64
	s_waitcnt vmcnt(25)
	v_mfma_f32_16x16x32_fp8_fp8 v[60:63], v[114:115], v[228:229], v[68:71]
	v_add_f32_e32 v204, v3, v64
	s_waitcnt vmcnt(24)
	v_mfma_f32_16x16x32_fp8_fp8 v[64:67], v[108:109], v[228:229], v[72:75]
	s_branch .LBB0_968
; template <bool SLC, bool NOMASK> ...
;     const int kq = lane >> 4;
;     const int pos0 = SLC ? (dcur & 0xfffff) : dcur;
;     const int lo = SLC ? ((((dcur >> 20) == qi) | ((dcur >> 20) == 4)) ? 0 : (1 << 30)) : lo_in;
;     load_frag8(nxt, KF, VF, SLC ? (dnext & 0xfffff) : dnext, lane);
;     f32x4 sa[2] = {(f32x4){0.f, 0.f, 0.f, 0.f}, (f32x4){0.f, 0.f, 0.f, 0.f}};
; #pragma unroll
;     for (int T = 0; T < 2; ++T)
; #pragma unroll
;         for (int s2 = 0; s2 < 4; ++s2) sa[T] = __builtin_amdgcn_mfma_f32_16x16x32_fp8_fp8(cur.k[T][s2], qf[s2], sa[T], 0, 0, 0);
;     float sc[8]; bool vd[8]; float mx = -1e30f;
;     const bool act = lo == 0 || !SLC;
;     if (NOMASK) {
; #pragma unroll
;         for (int j = 0; j < 8; ++j) { sc[j] = sa[j >> 2][j & 3]; vd[j] = act; }
;         mx = fmaxf(fmaxf(fmaxf(sc[0], sc[1]), fmaxf(sc[2], sc[3])), fmaxf(fmaxf(sc[4], sc[5]), fmaxf(sc[6], sc[7])));
;         mx = act ? mx : -1e30f;
;     } else {
; #pragma unroll
;         for (int T = 0; T < 2; ++T)
; #pragma unroll
;             for (int r = 0; r < 4; ++r) { const int p = pos0 + 16 * T + 4 * kq + r; const bool v = (p >= lo) & (p <= hi); const float x = sa[T][r];
;                 sc[4 * T + r] = x; vd[4 * T + r] = v; mx = v ? fmaxf(mx, x) : mx; }
;     }
;     if (__builtin_amdgcn_ballot_w64(mx > st.m + 4.f) != 0ull) {
;         mx = fmaxf(mx, __shfl_xor(mx, 16)); mx = fmaxf(mx, __shfl_xor(mx, 32));
;         const float mn = fmaxf(st.m, mx), alpha = __builtin_amdgcn_exp2f(st.m - mn); st.m = mn; st.l *= alpha;
; #pragma unroll
;         for (int j = 0; j < 8; ++j) st.o[j] = st.o[j] * alpha;
;     }
;     f32x4 pa, pb; float ps = 0.f;
;     const float mref = st.m - 4.f;
;     if (NOMASK) {
; #pragma unroll
;         for (int j = 0; j < 4; ++j) { pa[j] = __builtin_amdgcn_exp2f(sc[j] - mref); pb[j] = __builtin_amdgcn_exp2f(sc[4 + j] - mref); }
;         if (SLC) {
; #pragma unroll
;             for (int j = 0; j < 4; ++j) { pa[j] = act ? pa[j] : 0.f; pb[j] = act ? pb[j] : 0.f; }
;         }
; #pragma unroll
;         for (int j = 0; j < 4; ++j) ps += pa[j] + pb[j];
;     } else {
; #pragma unroll
;         for (int j = 0; j < 4; ++j) { pa[j] = vd[j] ? __builtin_amdgcn_exp2f(sc[j] - mref) : 0.f; pb[j] = vd[4 + j] ? __builtin_amdgcn_exp2f(sc[4 + j] - mref) : 0.f; ps += pa[j] + pb[j]; }
;     }
;     st.l += ps;
;     const u32x2 pw = pack8_fp8(pa, pb);
.LBB0_979:
	s_cmp_eq_u32 s12, 4
	s_cselect_b64 s[10:11], -1, 0
	s_lshl_b32 s13, s57, 7
	s_and_b32 s50, s13, 0x7fff800
	v_lshl_add_u64 v[44:45], v[86:87], 0, s[50:51]
	s_and_b32 s50, s13, 0x7fff000
	v_lshl_add_u64 v[246:247], v[44:45], 0, v[120:121]
	global_load_dwordx4 v[138:141], v[246:247], off
	global_load_dwordx4 v[142:145], v[246:247], off offset:1024
	global_load_dwordx4 v[146:149], v[246:247], off offset:2048
	global_load_dwordx4 v[150:153], v[246:247], off offset:3072
	v_lshl_add_u64 v[44:45], v[88:89], 0, s[50:51]
	global_load_dwordx2 v[90:91], v[44:45], off
	global_load_dwordx2 v[92:93], v[44:45], off offset:512
	global_load_dwordx2 v[94:95], v[44:45], off offset:1024
	global_load_dwordx2 v[96:97], v[44:45], off offset:1536
	global_load_dwordx2 v[104:105], v[44:45], off offset:2048
	global_load_dwordx2 v[102:103], v[44:45], off offset:2560
	global_load_dwordx2 v[100:101], v[44:45], off offset:3072
	global_load_dwordx2 v[98:99], v[44:45], off offset:3584
	s_waitcnt vmcnt(32)
	v_mfma_f32_16x16x32_fp8_fp8 v[36:39], v[154:155], v[78:79], 0
	s_and_b32 s13, s92, 0xfffff
	v_cmp_eq_u32_e32 vcc, s12, v209
	v_add_u32_e32 v3, s13, v210
	v_mfma_f32_16x16x32_fp8_fp8 v[36:39], v[156:157], v[80:81], v[36:39]
	s_or_b64 s[18:19], s[10:11], vcc
	v_cmp_le_i32_e32 vcc, v3, v132
	s_and_b64 s[16:17], s[18:19], vcc
	v_mfma_f32_16x16x32_fp8_fp8 v[36:39], v[158:159], v[82:83], v[36:39]
	v_cmp_lt_i32_e32 vcc, v3, v132
	s_and_b64 s[12:13], s[18:19], vcc
	v_mfma_f32_16x16x32_fp8_fp8 v[40:43], v[162:163], v[78:79], 0
	v_mfma_f32_16x16x32_fp8_fp8 v[36:39], v[160:161], v[84:85], v[36:39]
	v_mfma_f32_16x16x32_fp8_fp8 v[40:43], v[164:165], v[80:81], v[40:43]
	v_mfma_f32_16x16x32_fp8_fp8 v[40:43], v[166:167], v[82:83], v[40:43]
	s_nop 3
	v_max_f32_e32 v44, v36, v36
	v_max_f32_e32 v44, 0xf149f2ca, v44
	v_cndmask_b32_e64 v44, v220, v44, s[16:17]
	v_max_f32_e32 v45, v37, v37
	v_max_f32_e32 v45, v44, v45
	v_cndmask_b32_e64 v44, v44, v45, s[12:13]
	v_add_u32_e32 v45, 2, v3
	v_cmp_le_i32_e32 vcc, v45, v132
	v_max_f32_e32 v45, v38, v38
	v_max_f32_e32 v45, v44, v45
	s_and_b64 s[14:15], s[18:19], vcc
	v_mfma_f32_16x16x32_fp8_fp8 v[40:43], v[168:169], v[84:85], v[40:43]
	v_cndmask_b32_e64 v44, v44, v45, s[14:15]
	v_add_u32_e32 v45, 3, v3
	v_cmp_le_i32_e32 vcc, v45, v132
	v_max_f32_e32 v45, v39, v39
	v_max_f32_e32 v45, v44, v45
	s_and_b64 s[10:11], s[18:19], vcc
	v_cndmask_b32_e64 v44, v44, v45, s[10:11]
	v_add_u32_e32 v45, 16, v3
	v_cmp_le_i32_e32 vcc, v45, v132
	v_max_f32_e32 v45, v40, v40
	v_max_f32_e32 v45, v44, v45
	s_and_b64 s[24:25], s[18:19], vcc
	v_cndmask_b32_e64 v44, v44, v45, s[24:25]
	v_add_u32_e32 v45, 17, v3
	v_cmp_le_i32_e32 vcc, v45, v132
	v_max_f32_e32 v45, v44, v44
	v_max_f32_e32 v46, v41, v41
	v_max_f32_e32 v45, v45, v46
	s_and_b64 s[20:21], s[18:19], vcc
	v_cndmask_b32_e64 v44, v44, v45, s[20:21]
	v_add_u32_e32 v45, 18, v3
	v_cmp_le_i32_e32 vcc, v45, v132
	v_max_f32_e32 v45, v44, v44
	v_max_f32_e32 v46, v42, v42
	v_max_f32_e32 v45, v45, v46
	s_and_b64 s[22:23], s[18:19], vcc
	v_cndmask_b32_e64 v44, v44, v45, s[22:23]
	v_add_u32_e32 v3, 19, v3
	v_cmp_le_i32_e32 vcc, v3, v132
	v_max_f32_e32 v3, v44, v44
	v_max_f32_e32 v45, v43, v43
	v_max_f32_e32 v3, v3, v45
	s_and_b64 s[18:19], s[18:19], vcc
	v_cndmask_b32_e64 v3, v44, v3, s[18:19]
	v_cmp_gt_f32_e32 vcc, v3, v2
	s_cbranch_vccz .LBB0_981
	ds_bpermute_b32 v2, v225, v3
	v_max_f32_e32 v3, v3, v3
	s_waitcnt lgkmcnt(0)
	v_max_f32_e32 v2, v2, v2
	v_max_f32_e32 v2, v3, v2
	ds_bpermute_b32 v3, v224, v2
	s_waitcnt lgkmcnt(0)
	v_max3_f32 v2, v0, v2, v3
	v_sub_f32_e32 v0, v0, v2
	v_exp_f32_e32 v0, v0
	s_nop 0
	v_mul_f32_e32 v133, v133, v0
	v_pk_mul_f32 v[10:11], v[10:11], v[0:1] op_sel_hi:[1,0]
	v_pk_mul_f32 v[8:9], v[8:9], v[0:1] op_sel_hi:[1,0]
	v_pk_mul_f32 v[14:15], v[14:15], v[0:1] op_sel_hi:[1,0]
	v_pk_mul_f32 v[12:13], v[12:13], v[0:1] op_sel_hi:[1,0]
	v_pk_mul_f32 v[18:19], v[18:19], v[0:1] op_sel_hi:[1,0]
	v_pk_mul_f32 v[16:17], v[16:17], v[0:1] op_sel_hi:[1,0]
	v_pk_mul_f32 v[22:23], v[22:23], v[0:1] op_sel_hi:[1,0]
	v_pk_mul_f32 v[20:21], v[20:21], v[0:1] op_sel_hi:[1,0]
	v_pk_mul_f32 v[26:27], v[26:27], v[0:1] op_sel_hi:[1,0]
	v_pk_mul_f32 v[24:25], v[24:25], v[0:1] op_sel_hi:[1,0]
	v_pk_mul_f32 v[34:35], v[34:35], v[0:1] op_sel_hi:[1,0]
	v_pk_mul_f32 v[32:33], v[32:33], v[0:1] op_sel_hi:[1,0]
	v_pk_mul_f32 v[30:31], v[30:31], v[0:1] op_sel_hi:[1,0]
	v_pk_mul_f32 v[28:29], v[28:29], v[0:1] op_sel_hi:[1,0]
	v_pk_mul_f32 v[6:7], v[6:7], v[0:1] op_sel_hi:[1,0]
	v_pk_mul_f32 v[4:5], v[4:5], v[0:1] op_sel_hi:[1,0]
	v_mov_b32_e32 v0, v2
.LBB0_981:
	v_add_f32_e32 v2, -4.0, v0
	v_sub_f32_e32 v3, v36, v2
	v_exp_f32_e32 v3, v3
	v_sub_f32_e32 v36, v40, v2
	v_exp_f32_e32 v36, v36
	v_mov_b32_e32 v203, v0
	v_cndmask_b32_e64 v56, 0, v3, s[16:17]
	v_sub_f32_e32 v3, v37, v2
	v_cndmask_b32_e64 v57, 0, v36, s[24:25]
	v_exp_f32_e32 v3, v3
	v_sub_f32_e32 v36, v41, v2
	v_sub_f32_e32 v37, v38, v2
	v_exp_f32_e32 v36, v36
	v_exp_f32_e32 v37, v37
	v_sub_f32_e32 v38, v42, v2
	v_cndmask_b32_e64 v58, 0, v3, s[12:13]
	v_sub_f32_e32 v3, v39, v2
	v_sub_f32_e32 v2, v43, v2
	v_exp_f32_e32 v38, v38
	v_cndmask_b32_e64 v59, 0, v36, s[20:21]
	v_cndmask_b32_e64 v60, 0, v37, s[14:15]
	v_exp_f32_e32 v36, v3
	v_exp_f32_e32 v37, v2
	v_mov_b32_e32 v2, v1
	v_mov_b32_e32 v3, v1
	v_cvt_pk_fp8_f32 v2, v56, v58
	v_cvt_pk_fp8_f32 v3, v57, v59
	v_cndmask_b32_e64 v61, 0, v38, s[22:23]
	v_cndmask_b32_e64 v64, 0, v36, s[10:11]
	v_cndmask_b32_e64 v65, 0, v37, s[18:19]
	v_cvt_pk_fp8_f32 v2, v60, v64 op_sel:[0,0,1]
	v_cvt_pk_fp8_f32 v3, v61, v65 op_sel:[0,0,1]
	s_nop 0
	s_waitcnt vmcnt(31)
	v_mfma_f32_16x16x32_fp8_fp8 v[36:39], v[106:107], v[2:3], v[8:11]
	s_nop 2
	v_add_f32_e32 v8, v56, v57
	v_add_f32_e32 v8, 0, v8
	v_add_f32_e32 v9, v58, v59
	v_add_f32_e32 v8, v9, v8
	v_add_f32_e32 v9, v60, v61
	s_waitcnt vmcnt(30)
	v_mfma_f32_16x16x32_fp8_fp8 v[40:43], v[110:111], v[2:3], v[12:15]
	v_add_f32_e32 v8, v9, v8
	v_add_f32_e32 v9, v64, v65
	v_add_f32_e32 v8, v9, v8
	s_waitcnt vmcnt(29)
	v_mfma_f32_16x16x32_fp8_fp8 v[44:47], v[112:113], v[2:3], v[16:19]
	v_add_f32_e32 v204, v133, v8
	s_waitcnt vmcnt(28)
	v_mfma_f32_16x16x32_fp8_fp8 v[48:51], v[116:117], v[2:3], v[20:23]
	s_waitcnt vmcnt(27)
	v_mfma_f32_16x16x32_fp8_fp8 v[52:55], v[136:137], v[2:3], v[24:27]
	s_waitcnt vmcnt(26)
	v_mfma_f32_16x16x32_fp8_fp8 v[56:59], v[134:135], v[2:3], v[32:35]
	s_waitcnt vmcnt(25)
	v_mfma_f32_16x16x32_fp8_fp8 v[60:63], v[114:115], v[2:3], v[28:31]
	s_waitcnt vmcnt(24)
	v_mfma_f32_16x16x32_fp8_fp8 v[64:67], v[108:109], v[2:3], v[4:7]
	s_andn2_b64 vcc, exec, s[26:27]
	s_mov_b64 s[10:11], -1
	s_cbranch_vccnz .LBB0_961
; template <bool SLC, bool NOMASK> ...
;     const int kq = lane >> 4;
;     const int pos0 = SLC ? (dcur & 0xfffff) : dcur;
;     const int lo = SLC ? ((((dcur >> 20) == qi) | ((dcur >> 20) == 4)) ? 0 : (1 << 30)) : lo_in;
;     load_frag8(nxt, KF, VF, SLC ? (dnext & 0xfffff) : dnext, lane);
;     f32x4 sa[2] = {(f32x4){0.f, 0.f, 0.f, 0.f}, (f32x4){0.f, 0.f, 0.f, 0.f}};
; #pragma unroll
;     for (int T = 0; T < 2; ++T)
; #pragma unroll
;         for (int s2 = 0; s2 < 4; ++s2) sa[T] = __builtin_amdgcn_mfma_f32_16x16x32_fp8_fp8(cur.k[T][s2], qf[s2], sa[T], 0, 0, 0);
;     float sc[8]; bool vd[8]; float mx = -1e30f;
;     const bool act = lo == 0 || !SLC;
;     if (NOMASK) {
; #pragma unroll
;         for (int j = 0; j < 8; ++j) { sc[j] = sa[j >> 2][j & 3]; vd[j] = act; }
;         mx = fmaxf(fmaxf(fmaxf(sc[0], sc[1]), fmaxf(sc[2], sc[3])), fmaxf(fmaxf(sc[4], sc[5]), fmaxf(sc[6], sc[7])));
;         mx = act ? mx : -1e30f;
;     } else {
; #pragma unroll
;         for (int T = 0; T < 2; ++T)
; #pragma unroll
;             for (int r = 0; r < 4; ++r) { const int p = pos0 + 16 * T + 4 * kq + r; const bool v = (p >= lo) & (p <= hi); const float x = sa[T][r];
;                 sc[4 * T + r] = x; vd[4 * T + r] = v; mx = v ? fmaxf(mx, x) : mx; }
;     }
;     if (__builtin_amdgcn_ballot_w64(mx > st.m + 4.f) != 0ull) {
;         mx = fmaxf(mx, __shfl_xor(mx, 16)); mx = fmaxf(mx, __shfl_xor(mx, 32));
;         const float mn = fmaxf(st.m, mx), alpha = __builtin_amdgcn_exp2f(st.m - mn); st.m = mn; st.l *= alpha;
; #pragma unroll
;         for (int j = 0; j < 8; ++j) st.o[j] = st.o[j] * alpha;
;     }
;     f32x4 pa, pb; float ps = 0.f;
;     const float mref = st.m - 4.f;
;     if (NOMASK) {
; #pragma unroll
;         for (int j = 0; j < 4; ++j) { pa[j] = __builtin_amdgcn_exp2f(sc[j] - mref); pb[j] = __builtin_amdgcn_exp2f(sc[4 + j] - mref); }
;         if (SLC) {
; #pragma unroll
;             for (int j = 0; j < 4; ++j) { pa[j] = act ? pa[j] : 0.f; pb[j] = act ? pb[j] : 0.f; }
;         }
; #pragma unroll
;         for (int j = 0; j < 4; ++j) ps += pa[j] + pb[j];
;     } else {
; #pragma unroll
;         for (int j = 0; j < 4; ++j) { pa[j] = vd[j] ? __builtin_amdgcn_exp2f(sc[j] - mref) : 0.f; pb[j] = vd[4 + j] ? __builtin_amdgcn_exp2f(sc[4 + j] - mref) : 0.f; ps += pa[j] + pb[j]; }
;     }
;     st.l += ps;
;     const u32x2 pw = pack8_fp8(pa, pb);
.LBB0_982:
	s_cmp_lt_u32 s56, s54
	s_cselect_b32 s10, s56, s55
	s_lshl_b32 s10, s10, 2
	s_add_i32 s10, s3, s10
	v_mov_b32_e32 v0, s10
	ds_read_b32 v0, v0 offset:13632
	s_and_b32 s13, s66, 2.0
	s_ashr_i32 s12, s66, 20
	s_mov_b64 s[10:11], -1
	s_cmp_eq_u32 s13, 0
	s_waitcnt lgkmcnt(0)
	v_readfirstlane_b32 s92, v0
	v_add_f32_e32 v0, 4.0, v203
	s_cbranch_scc1 .LBB0_986
	s_and_b32 s13, s12, 0xfffffbff
	s_cmp_eq_u32 s13, 4
	s_cselect_b64 s[10:11], -1, 0
	s_lshl_b32 s14, s92, 7
	s_and_b32 s50, s14, 0x7fff800
	v_lshl_add_u64 v[10:11], v[86:87], 0, s[50:51]
	s_and_b32 s50, s14, 0x7fff000
	v_lshl_add_u64 v[246:247], v[10:11], 0, v[120:121]
	global_load_dwordx4 v[154:157], v[246:247], off
	global_load_dwordx4 v[158:161], v[246:247], off offset:1024
	global_load_dwordx4 v[162:165], v[246:247], off offset:2048
	global_load_dwordx4 v[166:169], v[246:247], off offset:3072
	v_lshl_add_u64 v[10:11], v[88:89], 0, s[50:51]
	global_load_dwordx2 v[106:107], v[10:11], off
	global_load_dwordx2 v[110:111], v[10:11], off offset:512
	global_load_dwordx2 v[112:113], v[10:11], off offset:1024
	global_load_dwordx2 v[116:117], v[10:11], off offset:1536
	global_load_dwordx2 v[136:137], v[10:11], off offset:2048
	global_load_dwordx2 v[134:135], v[10:11], off offset:2560
	global_load_dwordx2 v[114:115], v[10:11], off offset:3072
	global_load_dwordx2 v[108:109], v[10:11], off offset:3584
	s_waitcnt vmcnt(32)
	v_mfma_f32_16x16x32_fp8_fp8 v[2:5], v[186:187], v[78:79], 0
	v_cmp_eq_u32_e32 vcc, s13, v209
	s_or_b64 s[10:11], s[10:11], vcc
	v_mov_b64_e32 v[74:75], v[66:67]
	v_mfma_f32_16x16x32_fp8_fp8 v[6:9], v[194:195], v[78:79], 0
	v_mov_b64_e32 v[70:71], v[62:63]
	v_mov_b64_e32 v[30:31], v[56:57]
	v_mov_b64_e32 v[26:27], v[52:53]
	v_mfma_f32_16x16x32_fp8_fp8 v[2:5], v[188:189], v[80:81], v[2:5]
	v_mov_b64_e32 v[22:23], v[48:49]
	v_mov_b64_e32 v[18:19], v[44:45]
	v_mov_b64_e32 v[14:15], v[40:41]
	v_mfma_f32_16x16x32_fp8_fp8 v[6:9], v[196:197], v[80:81], v[6:9]
	v_mov_b32_e32 v202, v203
	v_mov_b64_e32 v[72:73], v[64:65]
	v_mov_b64_e32 v[68:69], v[60:61]
	v_mfma_f32_16x16x32_fp8_fp8 v[2:5], v[190:191], v[82:83], v[2:5]
	v_mov_b64_e32 v[32:33], v[58:59]
	v_mov_b64_e32 v[28:29], v[54:55]
	v_mov_b64_e32 v[24:25], v[50:51]
	v_mfma_f32_16x16x32_fp8_fp8 v[6:9], v[198:199], v[82:83], v[6:9]
	v_mov_b64_e32 v[20:21], v[46:47]
	v_mov_b64_e32 v[16:17], v[42:43]
	v_mov_b32_e32 v133, v204
	v_mfma_f32_16x16x32_fp8_fp8 v[2:5], v[192:193], v[84:85], v[2:5]
	v_mfma_f32_16x16x32_fp8_fp8 v[6:9], v[200:201], v[84:85], v[6:9]
	s_nop 5
	v_max_f32_e32 v10, v3, v3
	v_max_f32_e32 v11, v2, v2
	v_max_f32_e32 v10, v11, v10
	v_max_f32_e32 v11, v5, v5
	v_max_f32_e32 v12, v4, v4
	v_max_f32_e32 v11, v12, v11
	v_max_f32_e32 v12, v9, v9
	v_max_f32_e32 v13, v8, v8
	v_max_f32_e32 v12, v13, v12
	v_max3_f32 v12, v6, v7, v12
	v_max3_f32 v10, v10, v11, v12
	v_cndmask_b32_e64 v34, v220, v10, s[10:11]
	v_mov_b64_e32 v[10:11], v[36:37]
	v_cmp_gt_f32_e32 vcc, v34, v0
	v_mov_b64_e32 v[12:13], v[38:39]
	s_cbranch_vccz .LBB0_985
	ds_bpermute_b32 v10, v225, v34
	v_max_f32_e32 v11, v34, v34
	s_waitcnt lgkmcnt(0)
	v_max_f32_e32 v10, v10, v10
	v_max_f32_e32 v10, v11, v10
	ds_bpermute_b32 v11, v224, v10
	s_waitcnt lgkmcnt(0)
	v_max3_f32 v202, v203, v10, v11
	v_sub_f32_e32 v10, v203, v202
	v_exp_f32_e32 v34, v10
	s_nop 0
	v_mul_f32_e32 v133, v204, v34
	v_pk_mul_f32 v[12:13], v[38:39], v[34:35] op_sel_hi:[1,0]
	v_pk_mul_f32 v[10:11], v[36:37], v[34:35] op_sel_hi:[1,0]
	v_pk_mul_f32 v[16:17], v[42:43], v[34:35] op_sel_hi:[1,0]
	v_pk_mul_f32 v[14:15], v[40:41], v[34:35] op_sel_hi:[1,0]
	v_pk_mul_f32 v[20:21], v[46:47], v[34:35] op_sel_hi:[1,0]
	v_pk_mul_f32 v[18:19], v[44:45], v[34:35] op_sel_hi:[1,0]
	v_pk_mul_f32 v[24:25], v[50:51], v[34:35] op_sel_hi:[1,0]
	v_pk_mul_f32 v[22:23], v[48:49], v[34:35] op_sel_hi:[1,0]
	v_pk_mul_f32 v[28:29], v[54:55], v[34:35] op_sel_hi:[1,0]
	v_pk_mul_f32 v[26:27], v[52:53], v[34:35] op_sel_hi:[1,0]
	v_pk_mul_f32 v[32:33], v[58:59], v[34:35] op_sel_hi:[1,0]
	v_pk_mul_f32 v[30:31], v[56:57], v[34:35] op_sel_hi:[1,0]
	v_pk_mul_f32 v[70:71], v[62:63], v[34:35] op_sel_hi:[1,0]
	v_pk_mul_f32 v[68:69], v[60:61], v[34:35] op_sel_hi:[1,0]
	v_pk_mul_f32 v[74:75], v[66:67], v[34:35] op_sel_hi:[1,0]
	v_pk_mul_f32 v[72:73], v[64:65], v[34:35] op_sel_hi:[1,0]
.LBB0_985:
	v_add_f32_e32 v34, -4.0, v202
	v_sub_f32_e32 v2, v2, v34
	v_sub_f32_e32 v6, v6, v34
	v_sub_f32_e32 v3, v3, v34
	v_sub_f32_e32 v7, v7, v34
	v_exp_f32_e32 v2, v2
	v_exp_f32_e32 v6, v6
	v_exp_f32_e32 v3, v3
	v_exp_f32_e32 v7, v7
	v_sub_f32_e32 v4, v4, v34
	v_sub_f32_e32 v8, v8, v34
	v_sub_f32_e32 v5, v5, v34
	v_sub_f32_e32 v9, v9, v34
	v_exp_f32_e32 v4, v4
	v_exp_f32_e32 v8, v8
	v_exp_f32_e32 v5, v5
	v_exp_f32_e32 v9, v9
	v_cndmask_b32_e64 v34, 0, v2, s[10:11]
	v_cndmask_b32_e64 v6, 0, v6, s[10:11]
	v_cndmask_b32_e64 v35, 0, v3, s[10:11]
	v_cndmask_b32_e64 v7, 0, v7, s[10:11]
	v_mov_b32_e32 v2, v1
	v_mov_b32_e32 v3, v1
	v_cvt_pk_fp8_f32 v2, v34, v35
	v_cvt_pk_fp8_f32 v3, v6, v7
	v_cndmask_b32_e64 v4, 0, v4, s[10:11]
	v_cndmask_b32_e64 v205, 0, v8, s[10:11]
	v_cndmask_b32_e64 v5, 0, v5, s[10:11]
	v_cndmask_b32_e64 v227, 0, v9, s[10:11]
	v_add_f32_e32 v6, v34, v6
	v_cvt_pk_fp8_f32 v2, v4, v5 op_sel:[0,0,1]
	v_cvt_pk_fp8_f32 v3, v205, v227 op_sel:[0,0,1]
	v_add_f32_e32 v6, 0, v6
	v_add_f32_e32 v7, v35, v7
	v_add_f32_e32 v6, v7, v6
	v_add_f32_e32 v4, v4, v205
	v_add_f32_e32 v4, v4, v6
	v_add_f32_e32 v5, v5, v227
	v_add_f32_e32 v4, v5, v4
	s_waitcnt vmcnt(31)
	v_mfma_f32_16x16x32_fp8_fp8 v[8:11], v[170:171], v[2:3], v[10:13]
	v_add_f32_e32 v133, v133, v4
	s_mov_b64 s[10:11], 0
	s_waitcnt vmcnt(30)
	v_mfma_f32_16x16x32_fp8_fp8 v[12:15], v[172:173], v[2:3], v[14:17]
	s_waitcnt vmcnt(29)
	v_mfma_f32_16x16x32_fp8_fp8 v[16:19], v[174:175], v[2:3], v[18:21]
	s_waitcnt vmcnt(28)
	v_mfma_f32_16x16x32_fp8_fp8 v[20:23], v[176:177], v[2:3], v[22:25]
	s_waitcnt vmcnt(27)
	v_mfma_f32_16x16x32_fp8_fp8 v[24:27], v[184:185], v[2:3], v[26:29]
	s_waitcnt vmcnt(26)
	v_mfma_f32_16x16x32_fp8_fp8 v[32:35], v[182:183], v[2:3], v[30:33]
	s_waitcnt vmcnt(25)
	v_mfma_f32_16x16x32_fp8_fp8 v[28:31], v[180:181], v[2:3], v[68:71]
	s_waitcnt vmcnt(24)
	v_mfma_f32_16x16x32_fp8_fp8 v[4:7], v[178:179], v[2:3], v[72:75]
; template <bool SLC, bool NOMASK> ...
;     const int kq = lane >> 4;
;     const int pos0 = SLC ? (dcur & 0xfffff) : dcur;
;     const int lo = SLC ? ((((dcur >> 20) == qi) | ((dcur >> 20) == 4)) ? 0 : (1 << 30)) : lo_in;
;     load_frag8(nxt, KF, VF, SLC ? (dnext & 0xfffff) : dnext, lane);
;     f32x4 sa[2] = {(f32x4){0.f, 0.f, 0.f, 0.f}, (f32x4){0.f, 0.f, 0.f, 0.f}};
; #pragma unroll
;     for (int T = 0; T < 2; ++T)
; #pragma unroll
;         for (int s2 = 0; s2 < 4; ++s2) sa[T] = __builtin_amdgcn_mfma_f32_16x16x32_fp8_fp8(cur.k[T][s2], qf[s2], sa[T], 0, 0, 0);
;     float sc[8]; bool vd[8]; float mx = -1e30f;
;     const bool act = lo == 0 || !SLC;
;     if (NOMASK) {
; #pragma unroll
;         for (int j = 0; j < 8; ++j) { sc[j] = sa[j >> 2][j & 3]; vd[j] = act; }
;         mx = fmaxf(fmaxf(fmaxf(sc[0], sc[1]), fmaxf(sc[2], sc[3])), fmaxf(fmaxf(sc[4], sc[5]), fmaxf(sc[6], sc[7])));
;         mx = act ? mx : -1e30f;
;     } else {
; #pragma unroll
;         for (int T = 0; T < 2; ++T)
; #pragma unroll
;             for (int r = 0; r < 4; ++r) { const int p = pos0 + 16 * T + 4 * kq + r; const bool v = (p >= lo) & (p <= hi); const float x = sa[T][r];
;                 sc[4 * T + r] = x; vd[4 * T + r] = v; mx = v ? fmaxf(mx, x) : mx; }
;     }
;     if (__builtin_amdgcn_ballot_w64(mx > st.m + 4.f) != 0ull) {
;         mx = fmaxf(mx, __shfl_xor(mx, 16)); mx = fmaxf(mx, __shfl_xor(mx, 32));
;         const float mn = fmaxf(st.m, mx), alpha = __builtin_amdgcn_exp2f(st.m - mn); st.m = mn; st.l *= alpha;
; #pragma unroll
;         for (int j = 0; j < 8; ++j) st.o[j] = st.o[j] * alpha;
;     }
;     f32x4 pa, pb; float ps = 0.f;
;     const float mref = st.m - 4.f;
;     if (NOMASK) {
; #pragma unroll
;         for (int j = 0; j < 4; ++j) { pa[j] = __builtin_amdgcn_exp2f(sc[j] - mref); pb[j] = __builtin_amdgcn_exp2f(sc[4 + j] - mref); }
;         if (SLC) {
; #pragma unroll
;             for (int j = 0; j < 4; ++j) { pa[j] = act ? pa[j] : 0.f; pb[j] = act ? pb[j] : 0.f; }
;         }
; #pragma unroll
;         for (int j = 0; j < 4; ++j) ps += pa[j] + pb[j];
;     } else {
; #pragma unroll
;         for (int j = 0; j < 4; ++j) { pa[j] = vd[j] ? __builtin_amdgcn_exp2f(sc[j] - mref) : 0.f; pb[j] = vd[4 + j] ? __builtin_amdgcn_exp2f(sc[4 + j] - mref) : 0.f; ps += pa[j] + pb[j]; }
;     }
;     st.l += ps;
;     const u32x2 pw = pack8_fp8(pa, pb);
.LBB0_986:
	s_and_b64 vcc, exec, s[10:11]
	s_cbranch_vccz .LBB0_990
	s_cmp_eq_u32 s12, 4
	s_cselect_b64 s[10:11], -1, 0
	s_lshl_b32 s13, s92, 7
	s_and_b32 s50, s13, 0x7fff800
	v_lshl_add_u64 v[10:11], v[86:87], 0, s[50:51]
	s_and_b32 s50, s13, 0x7fff000
	v_lshl_add_u64 v[246:247], v[10:11], 0, v[120:121]
	global_load_dwordx4 v[154:157], v[246:247], off
	global_load_dwordx4 v[158:161], v[246:247], off offset:1024
	global_load_dwordx4 v[162:165], v[246:247], off offset:2048
	global_load_dwordx4 v[166:169], v[246:247], off offset:3072
	v_lshl_add_u64 v[10:11], v[88:89], 0, s[50:51]
	global_load_dwordx2 v[106:107], v[10:11], off
	global_load_dwordx2 v[110:111], v[10:11], off offset:512
	global_load_dwordx2 v[112:113], v[10:11], off offset:1024
	global_load_dwordx2 v[116:117], v[10:11], off offset:1536
	global_load_dwordx2 v[136:137], v[10:11], off offset:2048
	global_load_dwordx2 v[134:135], v[10:11], off offset:2560
	global_load_dwordx2 v[114:115], v[10:11], off offset:3072
	global_load_dwordx2 v[108:109], v[10:11], off offset:3584
	s_waitcnt vmcnt(32)
	v_mfma_f32_16x16x32_fp8_fp8 v[2:5], v[186:187], v[78:79], 0
	s_and_b32 s13, s66, 0xfffff
	v_cmp_eq_u32_e32 vcc, s12, v209
	v_add_u32_e32 v10, s13, v210
	v_mfma_f32_16x16x32_fp8_fp8 v[2:5], v[188:189], v[80:81], v[2:5]
	s_or_b64 s[18:19], s[10:11], vcc
	v_cmp_le_i32_e32 vcc, v10, v132
	s_and_b64 s[16:17], s[18:19], vcc
	v_mfma_f32_16x16x32_fp8_fp8 v[2:5], v[190:191], v[82:83], v[2:5]
	v_cmp_lt_i32_e32 vcc, v10, v132
	s_and_b64 s[12:13], s[18:19], vcc
	v_mfma_f32_16x16x32_fp8_fp8 v[6:9], v[194:195], v[78:79], 0
	v_mfma_f32_16x16x32_fp8_fp8 v[2:5], v[192:193], v[84:85], v[2:5]
	v_mfma_f32_16x16x32_fp8_fp8 v[6:9], v[196:197], v[80:81], v[6:9]
	v_mfma_f32_16x16x32_fp8_fp8 v[6:9], v[198:199], v[82:83], v[6:9]
	s_nop 3
	v_max_f32_e32 v11, v2, v2
	v_max_f32_e32 v11, 0xf149f2ca, v11
	v_cndmask_b32_e64 v11, v220, v11, s[16:17]
	v_max_f32_e32 v12, v3, v3
	v_max_f32_e32 v12, v11, v12
	v_cndmask_b32_e64 v11, v11, v12, s[12:13]
	v_add_u32_e32 v12, 2, v10
	v_cmp_le_i32_e32 vcc, v12, v132
	v_max_f32_e32 v12, v4, v4
	v_max_f32_e32 v12, v11, v12
	s_and_b64 s[14:15], s[18:19], vcc
	v_mfma_f32_16x16x32_fp8_fp8 v[6:9], v[200:201], v[84:85], v[6:9]
	v_cndmask_b32_e64 v11, v11, v12, s[14:15]
	v_add_u32_e32 v12, 3, v10
	v_cmp_le_i32_e32 vcc, v12, v132
	v_max_f32_e32 v12, v5, v5
	v_max_f32_e32 v12, v11, v12
	s_and_b64 s[10:11], s[18:19], vcc
	v_cndmask_b32_e64 v11, v11, v12, s[10:11]
	v_add_u32_e32 v12, 16, v10
	v_cmp_le_i32_e32 vcc, v12, v132
	v_max_f32_e32 v12, v6, v6
	v_max_f32_e32 v12, v11, v12
	s_and_b64 s[24:25], s[18:19], vcc
	v_cndmask_b32_e64 v11, v11, v12, s[24:25]
	v_add_u32_e32 v12, 17, v10
	v_cmp_le_i32_e32 vcc, v12, v132
	v_max_f32_e32 v12, v11, v11
	v_max_f32_e32 v13, v7, v7
	v_max_f32_e32 v12, v12, v13
	s_and_b64 s[20:21], s[18:19], vcc
	v_cndmask_b32_e64 v11, v11, v12, s[20:21]
	v_add_u32_e32 v12, 18, v10
	v_cmp_le_i32_e32 vcc, v12, v132
	v_max_f32_e32 v12, v11, v11
	v_max_f32_e32 v13, v8, v8
	v_max_f32_e32 v12, v12, v13
	s_and_b64 s[22:23], s[18:19], vcc
	v_cndmask_b32_e64 v11, v11, v12, s[22:23]
	v_add_u32_e32 v10, 19, v10
	v_cmp_le_i32_e32 vcc, v10, v132
	v_max_f32_e32 v10, v11, v11
	v_max_f32_e32 v12, v9, v9
	v_max_f32_e32 v10, v10, v12
	s_and_b64 s[18:19], s[18:19], vcc
	v_cndmask_b32_e64 v10, v11, v10, s[18:19]
	v_cmp_gt_f32_e32 vcc, v10, v0
	s_cbranch_vccz .LBB0_989
	ds_bpermute_b32 v0, v225, v10
	v_max_f32_e32 v10, v10, v10
	s_waitcnt lgkmcnt(0)
	v_max_f32_e32 v0, v0, v0
	v_max_f32_e32 v0, v10, v0
	ds_bpermute_b32 v10, v224, v0
	s_waitcnt lgkmcnt(0)
	v_max3_f32 v10, v203, v0, v10
	v_sub_f32_e32 v0, v203, v10
	v_exp_f32_e32 v0, v0
	v_mov_b32_e32 v203, v10
	v_mul_f32_e32 v204, v204, v0
	v_pk_mul_f32 v[38:39], v[38:39], v[0:1] op_sel_hi:[1,0]
	v_pk_mul_f32 v[36:37], v[36:37], v[0:1] op_sel_hi:[1,0]
	v_pk_mul_f32 v[42:43], v[42:43], v[0:1] op_sel_hi:[1,0]
	v_pk_mul_f32 v[40:41], v[40:41], v[0:1] op_sel_hi:[1,0]
	v_pk_mul_f32 v[46:47], v[46:47], v[0:1] op_sel_hi:[1,0]
	v_pk_mul_f32 v[44:45], v[44:45], v[0:1] op_sel_hi:[1,0]
	v_pk_mul_f32 v[50:51], v[50:51], v[0:1] op_sel_hi:[1,0]
	v_pk_mul_f32 v[48:49], v[48:49], v[0:1] op_sel_hi:[1,0]
	v_pk_mul_f32 v[54:55], v[54:55], v[0:1] op_sel_hi:[1,0]
	v_pk_mul_f32 v[52:53], v[52:53], v[0:1] op_sel_hi:[1,0]
	v_pk_mul_f32 v[58:59], v[58:59], v[0:1] op_sel_hi:[1,0]
	v_pk_mul_f32 v[56:57], v[56:57], v[0:1] op_sel_hi:[1,0]
	v_pk_mul_f32 v[62:63], v[62:63], v[0:1] op_sel_hi:[1,0]
	v_pk_mul_f32 v[60:61], v[60:61], v[0:1] op_sel_hi:[1,0]
	v_pk_mul_f32 v[66:67], v[66:67], v[0:1] op_sel_hi:[1,0]
	v_pk_mul_f32 v[64:65], v[64:65], v[0:1] op_sel_hi:[1,0]
.LBB0_989:
	v_add_f32_e32 v0, -4.0, v203
	v_sub_f32_e32 v2, v2, v0
	v_exp_f32_e32 v2, v2
	v_sub_f32_e32 v6, v6, v0
	v_exp_f32_e32 v6, v6
	v_sub_f32_e32 v4, v4, v0
	v_cndmask_b32_e64 v28, 0, v2, s[16:17]
	v_sub_f32_e32 v2, v3, v0
	v_exp_f32_e32 v2, v2
	v_sub_f32_e32 v3, v7, v0
	v_exp_f32_e32 v3, v3
	v_sub_f32_e32 v7, v8, v0
	v_cndmask_b32_e64 v29, 0, v2, s[12:13]
	v_sub_f32_e32 v2, v5, v0
	v_sub_f32_e32 v0, v9, v0
	v_cndmask_b32_e64 v6, 0, v6, s[24:25]
	v_exp_f32_e32 v4, v4
	v_exp_f32_e32 v7, v7
	v_cndmask_b32_e64 v30, 0, v3, s[20:21]
	v_exp_f32_e32 v5, v2
	v_exp_f32_e32 v0, v0
	v_mov_b32_e32 v2, v1
	v_mov_b32_e32 v3, v1
	v_cvt_pk_fp8_f32 v2, v28, v29
	v_cvt_pk_fp8_f32 v3, v6, v30
	v_cndmask_b32_e64 v4, 0, v4, s[14:15]
	v_cndmask_b32_e64 v7, 0, v7, s[22:23]
	v_cndmask_b32_e64 v5, 0, v5, s[10:11]
	v_cndmask_b32_e64 v0, 0, v0, s[18:19]
	v_cvt_pk_fp8_f32 v2, v4, v5 op_sel:[0,0,1]
	v_cvt_pk_fp8_f32 v3, v7, v0 op_sel:[0,0,1]
	v_add_f32_e32 v6, v28, v6
	v_add_f32_e32 v6, 0, v6
	v_add_f32_e32 v28, v29, v30
	v_add_f32_e32 v6, v28, v6
	v_add_f32_e32 v4, v4, v7
	v_add_f32_e32 v4, v4, v6
	v_add_f32_e32 v0, v5, v0
	s_waitcnt vmcnt(31)
	v_mfma_f32_16x16x32_fp8_fp8 v[8:11], v[170:171], v[2:3], v[36:39]
	v_add_f32_e32 v0, v0, v4
	v_add_f32_e32 v133, v204, v0
	v_mov_b32_e32 v202, v203
	s_waitcnt vmcnt(30)
	v_mfma_f32_16x16x32_fp8_fp8 v[12:15], v[172:173], v[2:3], v[40:43]
	s_waitcnt vmcnt(29)
	v_mfma_f32_16x16x32_fp8_fp8 v[16:19], v[174:175], v[2:3], v[44:47]
	s_waitcnt vmcnt(28)
	v_mfma_f32_16x16x32_fp8_fp8 v[20:23], v[176:177], v[2:3], v[48:51]
	s_waitcnt vmcnt(27)
	v_mfma_f32_16x16x32_fp8_fp8 v[24:27], v[184:185], v[2:3], v[52:55]
	s_waitcnt vmcnt(26)
	v_mfma_f32_16x16x32_fp8_fp8 v[32:35], v[182:183], v[2:3], v[56:59]
	s_waitcnt vmcnt(25)
	v_mfma_f32_16x16x32_fp8_fp8 v[28:31], v[180:181], v[2:3], v[60:63]
	s_waitcnt vmcnt(24)
	v_mfma_f32_16x16x32_fp8_fp8 v[4:7], v[178:179], v[2:3], v[64:67]

; __device__ __forceinline__ unsigned cvt_pk_bf16(float lo, float hi) { f32x2 v = {lo, hi}; bf16x2_t b = __builtin_convertvector(v, bf16x2_t); return __builtin_bit_cast(unsigned, b); }
; __device__ __forceinline__ float bf2f(unsigned short b) { return __uint_as_float(((unsigned)b) << 16); }
; __device__ __forceinline__ float bflo(unsigned w) { return __uint_as_float(w << 16); }
; __device__ __forceinline__ float bfhi(unsigned w) { return __uint_as_float(w & 0xffff0000u); }
; __device__ __forceinline__ float quad_total(float v) { v += __shfl_xor(v, 16); v += __shfl_xor(v, 32); return v; }
; __device__ __forceinline__ void nsa_unit(int unit, const bf16_t* proj, const bf16_t* kc, const bf16_t* vc, const bf16_t* gn, const float* cs, const float* sn, ...
;     ...
;     { const float g1 = bf2f(gn[(size_t)tc * 32 + head * 3 + 1]); const float lt = quad_total(st.l), inv = (lt > 0.f ? 1.f / lt : 0.f) * g1;
; #pragma unroll
;         for (int i = 0; i < 8; ++i) { const f32x4 o = st.o[i] * inv; u32x2 w = outl[64 * i]; w.x = cvt_pk_bf16(bflo(w.x) + o[0], bfhi(w.x) + o[1]); w.y = cvt_pk_bf16(bflo(w.y) + o[2], bfhi(w.y) + o[3]); outl[64 * i] = w; } }
;     astate_init(st);
;     { const int lo = tc - 511 < 0 ? 0 : tc - 511; const int first = t0 < 511 ? 0 : (t0 - 511) >> 5, last = (t0 + 3) >> 5;
.LBB0_992:
	s_waitcnt vmcnt(12)
	global_load_ushort v0, v[76:77], off offset:2
	ds_bpermute_b32 v2, v225, v133
	ds_read2st64_b64 v[36:39], v226 offset0:27 offset1:28
	ds_read2st64_b64 v[40:43], v226 offset0:29 offset1:30
	ds_read2st64_b64 v[44:47], v226 offset0:31 offset1:32
	ds_read2st64_b64 v[48:51], v226 offset0:33 offset1:34
	s_mov_b32 s56, 0
	s_waitcnt lgkmcnt(3)
	v_and_b32_e32 v3, 0xffff0000, v36
	v_lshlrev_b32_e32 v52, 16, v38
	v_add_f32_e32 v64, v133, v2
	ds_bpermute_b32 v65, v224, v64
	v_lshlrev_b32_e32 v2, 16, v36
	v_lshlrev_b32_e32 v36, 16, v37
	v_and_b32_e32 v37, 0xffff0000, v37
	v_and_b32_e32 v53, 0xffff0000, v38
	s_waitcnt lgkmcnt(0)
	v_add_f32_e32 v64, v64, v65
	v_div_scale_f32 v65, s[10:11], v64, v64, 1.0
	v_rcp_f32_e32 v66, v65
	v_div_scale_f32 v67, vcc, 1.0, v64, 1.0
	v_lshlrev_b32_e32 v38, 16, v39
	v_fma_f32 v68, -v65, v66, 1.0
	v_fmac_f32_e32 v66, v68, v66
	v_mul_f32_e32 v68, v67, v66
	v_fma_f32 v69, -v65, v68, v67
	v_fmac_f32_e32 v68, v69, v66
	v_fma_f32 v65, -v65, v68, v67
	v_div_fmas_f32 v65, v65, v66, v68
	v_div_fixup_f32 v65, v65, v64, 1.0
	v_cmp_lt_f32_e32 vcc, 0, v64
	v_and_b32_e32 v39, 0xffff0000, v39
	v_lshlrev_b32_e32 v54, 16, v40
	v_cndmask_b32_e32 v64, 0, v65, vcc
	v_and_b32_e32 v55, 0xffff0000, v40
	v_lshlrev_b32_e32 v40, 16, v41
	v_and_b32_e32 v41, 0xffff0000, v41
	v_lshlrev_b32_e32 v56, 16, v42
	v_and_b32_e32 v57, 0xffff0000, v42
	v_lshlrev_b32_e32 v42, 16, v43
	v_and_b32_e32 v43, 0xffff0000, v43
	v_lshlrev_b32_e32 v58, 16, v44
	v_and_b32_e32 v59, 0xffff0000, v44
	v_lshlrev_b32_e32 v44, 16, v45
	v_and_b32_e32 v45, 0xffff0000, v45
	v_lshlrev_b32_e32 v60, 16, v46
	v_and_b32_e32 v61, 0xffff0000, v46
	v_lshlrev_b32_e32 v46, 16, v47
	v_and_b32_e32 v47, 0xffff0000, v47
	v_lshlrev_b32_e32 v62, 16, v48
	v_and_b32_e32 v63, 0xffff0000, v48
	v_lshlrev_b32_e32 v48, 16, v49
	v_and_b32_e32 v49, 0xffff0000, v49
	s_add_i32 s10, s90, 0xfffffe01
	s_lshr_b32 s10, s10, 5
	s_cmpk_gt_i32 s90, 0x1fe
	s_cselect_b32 s26, s10, 0
	s_ashr_i32 s15, s91, 3
	s_sub_i32 s27, s15, s26
	s_mov_b64 s[12:13], s[52:53]
	s_cmp_lt_i32 s27, 0
	s_waitcnt vmcnt(0)
	v_lshlrev_b32_e32 v0, 16, v0
	v_mul_f32_e32 v0, v64, v0
	v_pk_fma_f32 v[2:3], v[8:9], v[0:1], v[2:3] op_sel_hi:[1,0,1]
	v_pk_fma_f32 v[8:9], v[10:11], v[0:1], v[36:37] op_sel_hi:[1,0,1]
	v_pk_fma_f32 v[10:11], v[12:13], v[0:1], v[52:53] op_sel_hi:[1,0,1]
	v_pk_fma_f32 v[12:13], v[14:15], v[0:1], v[38:39] op_sel_hi:[1,0,1]
	v_pk_fma_f32 v[14:15], v[16:17], v[0:1], v[54:55] op_sel_hi:[1,0,1]
	v_pk_fma_f32 v[16:17], v[18:19], v[0:1], v[40:41] op_sel_hi:[1,0,1]
	v_pk_fma_f32 v[18:19], v[20:21], v[0:1], v[56:57] op_sel_hi:[1,0,1]
	v_pk_fma_f32 v[20:21], v[22:23], v[0:1], v[42:43] op_sel_hi:[1,0,1]
	v_pk_fma_f32 v[22:23], v[24:25], v[0:1], v[58:59] op_sel_hi:[1,0,1]
	v_pk_fma_f32 v[24:25], v[26:27], v[0:1], v[44:45] op_sel_hi:[1,0,1]
	v_pk_fma_f32 v[26:27], v[32:33], v[0:1], v[60:61] op_sel_hi:[1,0,1]
	v_pk_fma_f32 v[32:33], v[34:35], v[0:1], v[46:47] op_sel_hi:[1,0,1]
	v_cvt_pk_bf16_f32 v2, v2, v3
	v_cvt_pk_bf16_f32 v3, v8, v9
	v_cvt_pk_bf16_f32 v8, v10, v11
	v_cvt_pk_bf16_f32 v9, v12, v13
	v_cvt_pk_bf16_f32 v10, v14, v15
	v_cvt_pk_bf16_f32 v11, v16, v17
	v_cvt_pk_bf16_f32 v12, v18, v19
	v_cvt_pk_bf16_f32 v13, v20, v21
	v_cvt_pk_bf16_f32 v14, v22, v23
	v_cvt_pk_bf16_f32 v15, v24, v25
	v_cvt_pk_bf16_f32 v16, v26, v27
	v_cvt_pk_bf16_f32 v17, v32, v33
	ds_write2st64_b64 v226, v[2:3], v[8:9] offset0:27 offset1:28
	ds_write2st64_b64 v226, v[10:11], v[12:13] offset0:29 offset1:30
	ds_write2st64_b64 v226, v[14:15], v[16:17] offset0:31 offset1:32
	v_pk_fma_f32 v[2:3], v[30:31], v[0:1], v[48:49] op_sel_hi:[1,0,1]
	v_pk_fma_f32 v[28:29], v[28:29], v[0:1], v[62:63] op_sel_hi:[1,0,1]
	v_cvt_pk_bf16_f32 v19, v2, v3
	v_lshlrev_b32_e32 v2, 16, v50
	v_and_b32_e32 v3, 0xffff0000, v50
	v_pk_fma_f32 v[2:3], v[4:5], v[0:1], v[2:3] op_sel_hi:[1,0,1]
	v_lshlrev_b32_e32 v4, 16, v51
	v_and_b32_e32 v5, 0xffff0000, v51
	v_pk_fma_f32 v[4:5], v[6:7], v[0:1], v[4:5] op_sel_hi:[1,0,1]
	v_cvt_pk_bf16_f32 v18, v28, v29
	v_cvt_pk_bf16_f32 v2, v2, v3
	v_cvt_pk_bf16_f32 v3, v4, v5
	ds_write2st64_b64 v226, v[18:19], v[2:3] offset0:33 offset1:34
	s_cbranch_scc1 .LBB0_925
; template <bool SLC, class Desc>
; __device__ __forceinline__ void attn_run_frag8(const i64_t (&qf)[4], const unsigned char* __restrict__ KF, const unsigned char* __restrict__ VF, const Desc& desc, int n,
;                                                int lo_in, int hi, int qi, AState& st, int lane) {
;     if (n <= 0) return;
;     Frag8 fa, fb, fc;
;     constexpr int NM = ~(1 << 30);
;     int d0 = desc(0), d1 = desc(n > 1 ? 1 : 0);
;     load_frag8(fa, KF, VF, SLC ? (d0 & 0xfffff) : (d0 & NM), lane);
;     load_frag8(fb, KF, VF, SLC ? (d1 & 0xfffff) : (d1 & NM), lane);
; __device__ __forceinline__ void nsa_unit(int unit, const bf16_t* proj, const bf16_t* kc, const bf16_t* vc, const bf16_t* gn, const float* cs, const float* sn, ...
;     ...
;     { const int lo = tc - 511 < 0 ? 0 : tc - 511; const int first = t0 < 511 ? 0 : (t0 - 511) >> 5, last = (t0 + 3) >> 5;
;       auto desc = [&](int i) { const int p0 = 32 * (first + i); return p0 | ((p0 >= t0 + 3 - 511 && p0 + 31 <= t0) ? (1 << 30) : 0); };
;       unsigned long long goff = (unsigned long long)g * S * 128; asm volatile("" : "+s"(goff));
;       attn_run_frag8<false>(q8, (const unsigned char*)kslf + ((size_t)16 << 20) + goff, (const unsigned char*)kslf + ((size_t)24 << 20) + goff, desc, last - first + 1, lo, tc, 0, st, lane); }
	s_add_u32 s10, s71, s12
	s_addc_u32 s11, s72, s13
	s_add_u32 s12, s73, s12
	s_addc_u32 s13, s74, s13
	s_lshl_b32 s20, s26, 5
	s_add_i32 s54, s90, 0xfffffe04
	s_cmp_lt_i32 s20, s54
	s_cselect_b64 s[16:17], -1, 0
	s_or_b32 s14, s20, 31
	s_cmp_gt_i32 s14, s90
	s_cselect_b64 s[18:19], -1, 0
	s_or_b64 s[16:17], s[16:17], s[18:19]
	s_and_b64 s[16:17], s[16:17], exec
	s_cselect_b32 s14, 0, 2.0
	s_or_b32 s14, s14, s20
	s_cmp_lg_u32 s15, s26
	s_cselect_b64 s[16:17], -1, 0
	v_cndmask_b32_e64 v0, 0, 1, s[16:17]
	v_lshl_add_u64 v[86:87], s[12:13], 0, v[120:121]
	v_readfirstlane_b32 s15, v0
	s_add_i32 s15, s26, s15
	s_lshl_b32 s21, s15, 5
	s_cmp_lt_i32 s21, s54
	s_cselect_b64 s[16:17], -1, 0
	s_or_b32 s18, s21, 31
	s_cmp_gt_i32 s18, s90
	s_cselect_b64 s[18:19], -1, 0
	s_or_b64 s[16:17], s[16:17], s[18:19]
	s_and_b64 s[16:17], s[16:17], exec
	s_cselect_b32 s16, 0, 2.0
	s_or_b32 s66, s16, s21
	s_and_b32 s16, s20, 0x3fffffe0
	s_lshr_b32 s50, s16, 4
	s_lshl_b64 s[16:17], s[50:51], 11
	s_add_u32 s16, s12, s16
	s_addc_u32 s17, s13, s17
	s_and_b32 s50, s26, 0x1ffffff
	v_lshl_add_u64 v[2:3], s[16:17], 0, v[120:121]
	s_lshl_b64 s[16:17], s[50:51], 12
	s_add_u32 s16, s10, s16
	s_addc_u32 s17, s11, s17
	v_lshl_add_u64 v[246:247], v[2:3], 0, v[120:121]
	global_load_dwordx4 v[138:141], v[246:247], off
	global_load_dwordx4 v[142:145], v[246:247], off offset:1024
	global_load_dwordx4 v[146:149], v[246:247], off offset:2048
	global_load_dwordx4 v[150:153], v[246:247], off offset:3072
	v_lshl_add_u64 v[2:3], s[16:17], 0, v[120:121]
	s_and_b32 s16, s21, 0x3fffffe0
	s_lshr_b32 s50, s16, 4
	s_lshl_b64 s[16:17], s[50:51], 11
	s_add_u32 s16, s12, s16
	s_addc_u32 s17, s13, s17
	s_and_b32 s50, s15, 0x1ffffff
	global_load_dwordx2 v[90:91], v[2:3], off
	global_load_dwordx2 v[92:93], v[2:3], off offset:512
	global_load_dwordx2 v[94:95], v[2:3], off offset:1024
	global_load_dwordx2 v[96:97], v[2:3], off offset:1536
	global_load_dwordx2 v[104:105], v[2:3], off offset:2048
	global_load_dwordx2 v[102:103], v[2:3], off offset:2560
	global_load_dwordx2 v[100:101], v[2:3], off offset:3072
	global_load_dwordx2 v[98:99], v[2:3], off offset:3584
	v_lshl_add_u64 v[2:3], s[16:17], 0, v[120:121]
	s_lshl_b64 s[16:17], s[50:51], 12
	s_add_u32 s16, s10, s16
	s_addc_u32 s17, s11, s17
	v_lshl_add_u64 v[246:247], v[2:3], 0, v[120:121]
	global_load_dwordx4 v[154:157], v[246:247], off
	global_load_dwordx4 v[158:161], v[246:247], off offset:1024
	global_load_dwordx4 v[162:165], v[246:247], off offset:2048
	global_load_dwordx4 v[166:169], v[246:247], off offset:3072
	v_lshl_add_u64 v[2:3], s[16:17], 0, v[120:121]
	global_load_dwordx2 v[106:107], v[2:3], off
	global_load_dwordx2 v[110:111], v[2:3], off offset:512
	global_load_dwordx2 v[112:113], v[2:3], off offset:1024
	global_load_dwordx2 v[116:117], v[2:3], off offset:1536
	global_load_dwordx2 v[136:137], v[2:3], off offset:2048
	global_load_dwordx2 v[134:135], v[2:3], off offset:2560
	global_load_dwordx2 v[114:115], v[2:3], off offset:3072
	global_load_dwordx2 v[108:109], v[2:3], off offset:3584
	v_max_i32_e32 v0, 0x1ff, v132
	v_mov_b32_e32 v2, v1
	v_mov_b32_e32 v3, v1
	v_add_u32_e32 v35, 0xfffffe01, v0
	v_mov_b32_e32 v0, v1
	v_mov_b64_e32 v[38:39], v[2:3]
	v_mov_b64_e32 v[42:43], v[2:3]
	v_mov_b64_e32 v[46:47], v[2:3]
	v_mov_b64_e32 v[50:51], v[2:3]
	v_mov_b64_e32 v[54:55], v[2:3]
	v_mov_b64_e32 v[58:59], v[2:3]
	v_mov_b64_e32 v[62:63], v[2:3]
	v_mov_b64_e32 v[66:67], v[2:3]
	v_lshl_add_u64 v[88:89], s[10:11], 0, v[120:121]
	v_mov_b32_e32 v133, 0xf149f2ca
	v_mov_b32_e32 v227, 0
	v_mov_b64_e32 v[36:37], v[0:1]
	v_mov_b64_e32 v[40:41], v[0:1]
	v_mov_b64_e32 v[44:45], v[0:1]
	v_mov_b64_e32 v[48:49], v[0:1]
	v_mov_b64_e32 v[52:53], v[0:1]
	v_mov_b64_e32 v[56:57], v[0:1]
	v_mov_b64_e32 v[60:61], v[0:1]
	v_mov_b64_e32 v[64:65], v[0:1]
	s_branch .LBB0_996

; template <bool SLC, bool NOMASK> ...
;     const int kq = lane >> 4;
;     const int pos0 = SLC ? (dcur & 0xfffff) : dcur;
;     const int lo = SLC ? ((((dcur >> 20) == qi) | ((dcur >> 20) == 4)) ? 0 : (1 << 30)) : lo_in;
;     load_frag8(nxt, KF, VF, SLC ? (dnext & 0xfffff) : dnext, lane);
;     f32x4 sa[2] = {(f32x4){0.f, 0.f, 0.f, 0.f}, (f32x4){0.f, 0.f, 0.f, 0.f}};
; #pragma unroll
;     for (int T = 0; T < 2; ++T)
; #pragma unroll
;         for (int s2 = 0; s2 < 4; ++s2) sa[T] = __builtin_amdgcn_mfma_f32_16x16x32_fp8_fp8(cur.k[T][s2], qf[s2], sa[T], 0, 0, 0);
;     float sc[8]; bool vd[8]; float mx = -1e30f;
;     const bool act = lo == 0 || !SLC;
;     if (NOMASK) {
; #pragma unroll
;         for (int j = 0; j < 8; ++j) { sc[j] = sa[j >> 2][j & 3]; vd[j] = act; }
;         mx = fmaxf(fmaxf(fmaxf(sc[0], sc[1]), fmaxf(sc[2], sc[3])), fmaxf(fmaxf(sc[4], sc[5]), fmaxf(sc[6], sc[7])));
;         mx = act ? mx : -1e30f;
;     } else {
; #pragma unroll
;         for (int T = 0; T < 2; ++T)
; #pragma unroll
;             for (int r = 0; r < 4; ++r) { const int p = pos0 + 16 * T + 4 * kq + r; const bool v = (p >= lo) & (p <= hi); const float x = sa[T][r];
;                 sc[4 * T + r] = x; vd[4 * T + r] = v; mx = v ? fmaxf(mx, x) : mx; }
;     }
;     if (__builtin_amdgcn_ballot_w64(mx > st.m + 4.f) != 0ull) {
;         mx = fmaxf(mx, __shfl_xor(mx, 16)); mx = fmaxf(mx, __shfl_xor(mx, 32));
;         const float mn = fmaxf(st.m, mx), alpha = __builtin_amdgcn_exp2f(st.m - mn); st.m = mn; st.l *= alpha;
; #pragma unroll
;         for (int j = 0; j < 8; ++j) st.o[j] = st.o[j] * alpha;
;     }
;     f32x4 pa, pb; float ps = 0.f;
;     const float mref = st.m - 4.f;
;     if (NOMASK) {
; #pragma unroll
;         for (int j = 0; j < 4; ++j) { pa[j] = __builtin_amdgcn_exp2f(sc[j] - mref); pb[j] = __builtin_amdgcn_exp2f(sc[4 + j] - mref); }
;         if (SLC) {
; #pragma unroll
;             for (int j = 0; j < 4; ++j) { pa[j] = act ? pa[j] : 0.f; pb[j] = act ? pb[j] : 0.f; }
;         }
; #pragma unroll
;         for (int j = 0; j < 4; ++j) ps += pa[j] + pb[j];
;     } else {
; #pragma unroll
;         for (int j = 0; j < 4; ++j) { pa[j] = vd[j] ? __builtin_amdgcn_exp2f(sc[j] - mref) : 0.f; pb[j] = vd[4 + j] ? __builtin_amdgcn_exp2f(sc[4 + j] - mref) : 0.f; ps += pa[j] + pb[j]; }
;     }
;     st.l += ps;
;     const u32x2 pw = pack8_fp8(pa, pb);
.LBB0_1002:
	v_lshl_add_u64 v[246:247], v[204:205], 0, v[120:121]
	global_load_dwordx4 v[186:189], v[246:247], off
	global_load_dwordx4 v[190:193], v[246:247], off offset:1024
	global_load_dwordx4 v[194:197], v[246:247], off offset:2048
	global_load_dwordx4 v[198:201], v[246:247], off offset:3072
	global_load_dwordx2 v[170:171], v[202:203], off
	global_load_dwordx2 v[172:173], v[202:203], off offset:512
	global_load_dwordx2 v[174:175], v[202:203], off offset:1024
	global_load_dwordx2 v[176:177], v[202:203], off offset:1536
	global_load_dwordx2 v[184:185], v[202:203], off offset:2048
	global_load_dwordx2 v[182:183], v[202:203], off offset:2560
	global_load_dwordx2 v[180:181], v[202:203], off offset:3072
	global_load_dwordx2 v[178:179], v[202:203], off offset:3584
	s_waitcnt vmcnt(32)
	v_mfma_f32_16x16x32_fp8_fp8 v[2:5], v[138:139], v[78:79], 0
	v_mov_b64_e32 v[74:75], v[38:39]
	v_mov_b64_e32 v[70:71], v[42:43]
	v_mov_b64_e32 v[30:31], v[44:45]
	v_mfma_f32_16x16x32_fp8_fp8 v[6:9], v[146:147], v[78:79], 0
	v_mov_b64_e32 v[26:27], v[48:49]
	v_mov_b64_e32 v[22:23], v[52:53]
	v_mov_b64_e32 v[18:19], v[56:57]
	v_mfma_f32_16x16x32_fp8_fp8 v[2:5], v[140:141], v[80:81], v[2:5]
	v_mov_b64_e32 v[14:15], v[60:61]
	v_mov_b32_e32 v228, v133
	v_mov_b64_e32 v[72:73], v[36:37]
	v_mfma_f32_16x16x32_fp8_fp8 v[6:9], v[148:149], v[80:81], v[6:9]
	v_mov_b64_e32 v[68:69], v[40:41]
	v_mov_b64_e32 v[32:33], v[46:47]
	v_mov_b64_e32 v[28:29], v[50:51]
	v_mfma_f32_16x16x32_fp8_fp8 v[2:5], v[142:143], v[82:83], v[2:5]
	v_mov_b64_e32 v[24:25], v[54:55]
	v_mov_b64_e32 v[20:21], v[58:59]
	v_mov_b64_e32 v[16:17], v[62:63]
	v_mfma_f32_16x16x32_fp8_fp8 v[6:9], v[150:151], v[82:83], v[6:9]
	v_mov_b32_e32 v34, v227
	v_mfma_f32_16x16x32_fp8_fp8 v[2:5], v[144:145], v[84:85], v[2:5]
	v_mfma_f32_16x16x32_fp8_fp8 v[6:9], v[152:153], v[84:85], v[6:9]
	s_nop 5
	v_max_f32_e32 v0, v3, v3
	v_max_f32_e32 v10, v2, v2
	v_max_f32_e32 v0, v10, v0
	v_max_f32_e32 v10, v5, v5
	v_max_f32_e32 v11, v4, v4
	v_max_f32_e32 v10, v11, v10
	v_max_f32_e32 v11, v9, v9
	v_max_f32_e32 v12, v8, v8
	v_max_f32_e32 v11, v12, v11
	v_max3_f32 v11, v6, v7, v11
	v_max3_f32 v0, v0, v10, v11
	v_add_f32_e32 v10, 4.0, v133
	v_cmp_gt_f32_e32 vcc, v0, v10
	v_mov_b64_e32 v[10:11], v[64:65]
	v_mov_b64_e32 v[12:13], v[66:67]
	s_cbranch_vccz .LBB0_1004
	ds_bpermute_b32 v10, v225, v0
	v_max_f32_e32 v0, v0, v0
	s_waitcnt lgkmcnt(0)
	v_max_f32_e32 v10, v10, v10
	v_max_f32_e32 v0, v0, v10
	ds_bpermute_b32 v10, v224, v0
	s_waitcnt lgkmcnt(0)
	v_max3_f32 v228, v133, v0, v10
	v_sub_f32_e32 v0, v133, v228
	v_exp_f32_e32 v0, v0
	s_nop 0
	v_mul_f32_e32 v34, v227, v0
	v_pk_mul_f32 v[12:13], v[66:67], v[0:1] op_sel_hi:[1,0]
	v_pk_mul_f32 v[10:11], v[64:65], v[0:1] op_sel_hi:[1,0]
	v_pk_mul_f32 v[16:17], v[62:63], v[0:1] op_sel_hi:[1,0]
	v_pk_mul_f32 v[14:15], v[60:61], v[0:1] op_sel_hi:[1,0]
	v_pk_mul_f32 v[20:21], v[58:59], v[0:1] op_sel_hi:[1,0]
	v_pk_mul_f32 v[18:19], v[56:57], v[0:1] op_sel_hi:[1,0]
	v_pk_mul_f32 v[24:25], v[54:55], v[0:1] op_sel_hi:[1,0]
	v_pk_mul_f32 v[22:23], v[52:53], v[0:1] op_sel_hi:[1,0]
	v_pk_mul_f32 v[28:29], v[50:51], v[0:1] op_sel_hi:[1,0]
	v_pk_mul_f32 v[26:27], v[48:49], v[0:1] op_sel_hi:[1,0]
	v_pk_mul_f32 v[32:33], v[46:47], v[0:1] op_sel_hi:[1,0]
	v_pk_mul_f32 v[30:31], v[44:45], v[0:1] op_sel_hi:[1,0]
	v_pk_mul_f32 v[70:71], v[42:43], v[0:1] op_sel_hi:[1,0]
	v_pk_mul_f32 v[68:69], v[40:41], v[0:1] op_sel_hi:[1,0]
	v_pk_mul_f32 v[74:75], v[38:39], v[0:1] op_sel_hi:[1,0]
	v_pk_mul_f32 v[72:73], v[36:37], v[0:1] op_sel_hi:[1,0]
.LBB0_1004:
	v_add_f32_e32 v229, -4.0, v228
	v_sub_f32_e32 v0, v2, v229
	v_exp_f32_e32 v231, v0
	v_sub_f32_e32 v0, v6, v229
	v_exp_f32_e32 v234, v0
	v_sub_f32_e32 v0, v3, v229
	v_exp_f32_e32 v2, v0
	v_sub_f32_e32 v0, v7, v229
	v_exp_f32_e32 v0, v0
	v_sub_f32_e32 v3, v4, v229
	v_exp_f32_e32 v235, v3
	v_sub_f32_e32 v3, v8, v229
	v_exp_f32_e32 v236, v3
	v_sub_f32_e32 v3, v5, v229
	v_exp_f32_e32 v4, v3
	v_sub_f32_e32 v3, v9, v229
	v_mov_b32_e32 v232, v1
	v_mov_b32_e32 v233, v1
	v_exp_f32_e32 v230, v3
	v_cvt_pk_fp8_f32 v232, v231, v2
	v_cvt_pk_fp8_f32 v233, v234, v0
	v_add_f32_e32 v3, v231, v234
	v_pk_add_f32 v[2:3], v[2:3], v[0:1]
	v_cvt_pk_fp8_f32 v232, v235, v4 op_sel:[0,0,1]
	v_cvt_pk_fp8_f32 v233, v236, v230 op_sel:[0,0,1]
	v_pk_add_f32 v[2:3], v[2:3], v[2:3] op_sel_hi:[0,1]
	v_add_f32_e32 v5, v235, v236
	v_mov_b32_e32 v231, v3
	v_pk_add_f32 v[2:3], v[4:5], v[230:231]
	s_waitcnt vmcnt(31)
	v_mfma_f32_16x16x32_fp8_fp8 v[6:9], v[90:91], v[232:233], v[10:13]
	v_add_f32_e32 v0, v2, v3
	v_add_f32_e32 v34, v0, v34
	s_waitcnt vmcnt(30)
	v_mfma_f32_16x16x32_fp8_fp8 v[10:13], v[92:93], v[232:233], v[14:17]
	s_waitcnt vmcnt(29)
	v_mfma_f32_16x16x32_fp8_fp8 v[14:17], v[94:95], v[232:233], v[18:21]
	s_waitcnt vmcnt(28)
	v_mfma_f32_16x16x32_fp8_fp8 v[18:21], v[96:97], v[232:233], v[22:25]
	s_waitcnt vmcnt(27)
	v_mfma_f32_16x16x32_fp8_fp8 v[22:25], v[104:105], v[232:233], v[26:29]
	s_waitcnt vmcnt(26)
	v_mfma_f32_16x16x32_fp8_fp8 v[26:29], v[102:103], v[232:233], v[30:33]
	s_waitcnt vmcnt(25)
	v_mfma_f32_16x16x32_fp8_fp8 v[30:33], v[100:101], v[232:233], v[68:71]
	s_waitcnt vmcnt(24)
	v_mfma_f32_16x16x32_fp8_fp8 v[2:5], v[98:99], v[232:233], v[72:75]
	s_branch .LBB0_998
; template <bool SLC, bool NOMASK> ...
;     const int kq = lane >> 4;
;     const int pos0 = SLC ? (dcur & 0xfffff) : dcur;
;     const int lo = SLC ? ((((dcur >> 20) == qi) | ((dcur >> 20) == 4)) ? 0 : (1 << 30)) : lo_in;
;     load_frag8(nxt, KF, VF, SLC ? (dnext & 0xfffff) : dnext, lane);
;     f32x4 sa[2] = {(f32x4){0.f, 0.f, 0.f, 0.f}, (f32x4){0.f, 0.f, 0.f, 0.f}};
; #pragma unroll
;     for (int T = 0; T < 2; ++T)
; #pragma unroll
;         for (int s2 = 0; s2 < 4; ++s2) sa[T] = __builtin_amdgcn_mfma_f32_16x16x32_fp8_fp8(cur.k[T][s2], qf[s2], sa[T], 0, 0, 0);
;     float sc[8]; bool vd[8]; float mx = -1e30f;
;     const bool act = lo == 0 || !SLC;
;     if (NOMASK) {
; #pragma unroll
;         for (int j = 0; j < 8; ++j) { sc[j] = sa[j >> 2][j & 3]; vd[j] = act; }
;         mx = fmaxf(fmaxf(fmaxf(sc[0], sc[1]), fmaxf(sc[2], sc[3])), fmaxf(fmaxf(sc[4], sc[5]), fmaxf(sc[6], sc[7])));
;         mx = act ? mx : -1e30f;
;     } else {
; #pragma unroll
;         for (int T = 0; T < 2; ++T)
; #pragma unroll
;             for (int r = 0; r < 4; ++r) { const int p = pos0 + 16 * T + 4 * kq + r; const bool v = (p >= lo) & (p <= hi); const float x = sa[T][r];
;                 sc[4 * T + r] = x; vd[4 * T + r] = v; mx = v ? fmaxf(mx, x) : mx; }
;     }
;     if (__builtin_amdgcn_ballot_w64(mx > st.m + 4.f) != 0ull) {
;         mx = fmaxf(mx, __shfl_xor(mx, 16)); mx = fmaxf(mx, __shfl_xor(mx, 32));
;         const float mn = fmaxf(st.m, mx), alpha = __builtin_amdgcn_exp2f(st.m - mn); st.m = mn; st.l *= alpha;
; #pragma unroll
;         for (int j = 0; j < 8; ++j) st.o[j] = st.o[j] * alpha;
;     }
;     f32x4 pa, pb; float ps = 0.f;
;     const float mref = st.m - 4.f;
;     if (NOMASK) {
; #pragma unroll
;         for (int j = 0; j < 4; ++j) { pa[j] = __builtin_amdgcn_exp2f(sc[j] - mref); pb[j] = __builtin_amdgcn_exp2f(sc[4 + j] - mref); }
;         if (SLC) {
; #pragma unroll
;             for (int j = 0; j < 4; ++j) { pa[j] = act ? pa[j] : 0.f; pb[j] = act ? pb[j] : 0.f; }
;         }
; #pragma unroll
;         for (int j = 0; j < 4; ++j) ps += pa[j] + pb[j];
;     } else {
; #pragma unroll
;         for (int j = 0; j < 4; ++j) { pa[j] = vd[j] ? __builtin_amdgcn_exp2f(sc[j] - mref) : 0.f; pb[j] = vd[4 + j] ? __builtin_amdgcn_exp2f(sc[4 + j] - mref) : 0.f; ps += pa[j] + pb[j]; }
;     }
;     st.l += ps;
;     const u32x2 pw = pack8_fp8(pa, pb);
.LBB0_1005:
	v_lshl_add_u64 v[246:247], v[204:205], 0, v[120:121]
	global_load_dwordx4 v[186:189], v[246:247], off
	global_load_dwordx4 v[190:193], v[246:247], off offset:1024
	global_load_dwordx4 v[194:197], v[246:247], off offset:2048
	global_load_dwordx4 v[198:201], v[246:247], off offset:3072
	global_load_dwordx2 v[170:171], v[202:203], off
	global_load_dwordx2 v[172:173], v[202:203], off offset:512
	global_load_dwordx2 v[174:175], v[202:203], off offset:1024
	global_load_dwordx2 v[176:177], v[202:203], off offset:1536
	global_load_dwordx2 v[184:185], v[202:203], off offset:2048
	global_load_dwordx2 v[182:183], v[202:203], off offset:2560
	global_load_dwordx2 v[180:181], v[202:203], off offset:3072
	global_load_dwordx2 v[178:179], v[202:203], off offset:3584
	s_waitcnt vmcnt(32)
	v_mfma_f32_16x16x32_fp8_fp8 v[2:5], v[138:139], v[78:79], 0
	v_add_u32_e32 v0, s14, v210
	v_cmp_ge_i32_e32 vcc, v0, v35
	v_cmp_le_i32_e64 s[10:11], v0, v132
	v_mfma_f32_16x16x32_fp8_fp8 v[2:5], v[140:141], v[80:81], v[2:5]
	s_and_b64 s[16:17], vcc, s[10:11]
	v_add_u32_e32 v11, 1, v0
	v_cmp_ge_i32_e32 vcc, v11, v35
	v_mfma_f32_16x16x32_fp8_fp8 v[2:5], v[142:143], v[82:83], v[2:5]
	v_cmp_lt_i32_e64 s[10:11], v0, v132
	s_and_b64 s[12:13], s[10:11], vcc
	v_mfma_f32_16x16x32_fp8_fp8 v[6:9], v[146:147], v[78:79], 0
	v_mfma_f32_16x16x32_fp8_fp8 v[2:5], v[144:145], v[84:85], v[2:5]
	v_mfma_f32_16x16x32_fp8_fp8 v[6:9], v[148:149], v[80:81], v[6:9]
	v_mfma_f32_16x16x32_fp8_fp8 v[6:9], v[150:151], v[82:83], v[6:9]
	s_nop 3
	v_max_f32_e32 v10, v2, v2
	v_max_f32_e32 v10, 0xf149f2ca, v10
	v_cndmask_b32_e64 v10, v220, v10, s[16:17]
	v_max_f32_e32 v11, v3, v3
	v_max_f32_e32 v11, v10, v11
	v_cndmask_b32_e64 v10, v10, v11, s[12:13]
	v_add_u32_e32 v11, 2, v0
	v_cmp_ge_i32_e32 vcc, v11, v35
	v_cmp_le_i32_e64 s[10:11], v11, v132
	v_max_f32_e32 v11, v4, v4
	v_max_f32_e32 v11, v10, v11
	s_and_b64 s[14:15], vcc, s[10:11]
	v_mfma_f32_16x16x32_fp8_fp8 v[6:9], v[152:153], v[84:85], v[6:9]
	v_cndmask_b32_e64 v10, v10, v11, s[14:15]
	v_add_u32_e32 v11, 3, v0
	v_cmp_ge_i32_e32 vcc, v11, v35
	v_cmp_le_i32_e64 s[10:11], v11, v132
	v_max_f32_e32 v11, v5, v5
	v_max_f32_e32 v11, v10, v11
	s_and_b64 s[10:11], vcc, s[10:11]
	v_cndmask_b32_e64 v10, v10, v11, s[10:11]
	v_add_u32_e32 v11, 16, v0
	v_cmp_ge_i32_e32 vcc, v11, v35
	v_cmp_le_i32_e64 s[18:19], v11, v132
	v_max_f32_e32 v11, v6, v6
	v_max_f32_e32 v11, v10, v11
	s_and_b64 s[24:25], vcc, s[18:19]
	v_cndmask_b32_e64 v10, v10, v11, s[24:25]
	v_add_u32_e32 v11, 17, v0
	v_cmp_ge_i32_e32 vcc, v11, v35
	v_cmp_le_i32_e64 s[18:19], v11, v132
	v_max_f32_e32 v11, v10, v10
	v_max_f32_e32 v12, v7, v7
	v_max_f32_e32 v11, v11, v12
	s_and_b64 s[20:21], vcc, s[18:19]
	v_cndmask_b32_e64 v10, v10, v11, s[20:21]
	v_add_u32_e32 v11, 18, v0
	v_cmp_ge_i32_e32 vcc, v11, v35
	v_cmp_le_i32_e64 s[18:19], v11, v132
	v_max_f32_e32 v11, v10, v10
	v_max_f32_e32 v12, v8, v8
	v_max_f32_e32 v11, v11, v12
	s_and_b64 s[22:23], vcc, s[18:19]
	v_cndmask_b32_e64 v10, v10, v11, s[22:23]
	v_add_u32_e32 v0, 19, v0
	v_cmp_ge_i32_e32 vcc, v0, v35
	v_cmp_le_i32_e64 s[18:19], v0, v132
	v_max_f32_e32 v0, v10, v10
	v_max_f32_e32 v11, v9, v9
	v_max_f32_e32 v0, v0, v11
	s_and_b64 s[18:19], vcc, s[18:19]
	v_cndmask_b32_e64 v0, v10, v0, s[18:19]
	v_add_f32_e32 v10, 4.0, v133
	v_cmp_gt_f32_e32 vcc, v0, v10
	s_cbranch_vccz .LBB0_1007
	ds_bpermute_b32 v10, v225, v0
	v_max_f32_e32 v0, v0, v0
	s_waitcnt lgkmcnt(0)
	v_max_f32_e32 v10, v10, v10
	v_max_f32_e32 v0, v0, v10
	ds_bpermute_b32 v10, v224, v0
	s_waitcnt lgkmcnt(0)
	v_max3_f32 v10, v133, v0, v10
	v_sub_f32_e32 v0, v133, v10
	v_exp_f32_e32 v0, v0
	v_mov_b32_e32 v133, v10
	v_mul_f32_e32 v227, v227, v0
	v_pk_mul_f32 v[66:67], v[66:67], v[0:1] op_sel_hi:[1,0]
	v_pk_mul_f32 v[64:65], v[64:65], v[0:1] op_sel_hi:[1,0]
	v_pk_mul_f32 v[62:63], v[62:63], v[0:1] op_sel_hi:[1,0]
	v_pk_mul_f32 v[60:61], v[60:61], v[0:1] op_sel_hi:[1,0]
	v_pk_mul_f32 v[58:59], v[58:59], v[0:1] op_sel_hi:[1,0]
	v_pk_mul_f32 v[56:57], v[56:57], v[0:1] op_sel_hi:[1,0]
	v_pk_mul_f32 v[54:55], v[54:55], v[0:1] op_sel_hi:[1,0]
	v_pk_mul_f32 v[52:53], v[52:53], v[0:1] op_sel_hi:[1,0]
	v_pk_mul_f32 v[50:51], v[50:51], v[0:1] op_sel_hi:[1,0]
	v_pk_mul_f32 v[48:49], v[48:49], v[0:1] op_sel_hi:[1,0]
	v_pk_mul_f32 v[46:47], v[46:47], v[0:1] op_sel_hi:[1,0]
	v_pk_mul_f32 v[44:45], v[44:45], v[0:1] op_sel_hi:[1,0]
	v_pk_mul_f32 v[42:43], v[42:43], v[0:1] op_sel_hi:[1,0]
	v_pk_mul_f32 v[40:41], v[40:41], v[0:1] op_sel_hi:[1,0]
	v_pk_mul_f32 v[38:39], v[38:39], v[0:1] op_sel_hi:[1,0]
	v_pk_mul_f32 v[36:37], v[36:37], v[0:1] op_sel_hi:[1,0]
.LBB0_1007:
	v_add_f32_e32 v0, -4.0, v133
	v_sub_f32_e32 v2, v2, v0
	v_exp_f32_e32 v2, v2
	v_sub_f32_e32 v6, v6, v0
	v_exp_f32_e32 v6, v6
	v_sub_f32_e32 v4, v4, v0
	v_cndmask_b32_e64 v26, 0, v2, s[16:17]
	v_sub_f32_e32 v2, v3, v0
	v_exp_f32_e32 v2, v2
	v_sub_f32_e32 v3, v7, v0
	v_exp_f32_e32 v3, v3
	v_cndmask_b32_e64 v27, 0, v6, s[24:25]
	v_sub_f32_e32 v6, v8, v0
	v_cndmask_b32_e64 v28, 0, v2, s[12:13]
	v_sub_f32_e32 v2, v5, v0
	v_sub_f32_e32 v0, v9, v0
	v_exp_f32_e32 v4, v4
	v_exp_f32_e32 v6, v6
	v_cndmask_b32_e64 v29, 0, v3, s[20:21]
	v_exp_f32_e32 v5, v2
	v_exp_f32_e32 v0, v0
	v_mov_b32_e32 v2, v1
	v_mov_b32_e32 v3, v1
	v_cvt_pk_fp8_f32 v2, v26, v28
	v_cvt_pk_fp8_f32 v3, v27, v29
	v_cndmask_b32_e64 v4, 0, v4, s[14:15]
	v_cndmask_b32_e64 v30, 0, v6, s[22:23]
	v_cndmask_b32_e64 v5, 0, v5, s[10:11]
	v_cndmask_b32_e64 v0, 0, v0, s[18:19]
	v_cvt_pk_fp8_f32 v2, v4, v5 op_sel:[0,0,1]
	v_cvt_pk_fp8_f32 v3, v30, v0 op_sel:[0,0,1]
	v_add_f32_e32 v26, v26, v27
	v_add_f32_e32 v31, 0, v26
	v_add_f32_e32 v32, v28, v29
	v_add_f32_e32 v31, v32, v31
	v_add_f32_e32 v4, v4, v30
	v_add_f32_e32 v4, v4, v31
	v_add_f32_e32 v0, v5, v0
	s_waitcnt vmcnt(31)
	v_mfma_f32_16x16x32_fp8_fp8 v[6:9], v[90:91], v[2:3], v[64:67]
	v_add_f32_e32 v0, v0, v4
	v_add_f32_e32 v34, v227, v0
	v_mov_b32_e32 v228, v133
	s_waitcnt vmcnt(30)
	v_mfma_f32_16x16x32_fp8_fp8 v[10:13], v[92:93], v[2:3], v[60:63]
	s_waitcnt vmcnt(29)
	v_mfma_f32_16x16x32_fp8_fp8 v[14:17], v[94:95], v[2:3], v[56:59]
	s_waitcnt vmcnt(28)
	v_mfma_f32_16x16x32_fp8_fp8 v[18:21], v[96:97], v[2:3], v[52:55]
	s_waitcnt vmcnt(27)
	v_mfma_f32_16x16x32_fp8_fp8 v[22:25], v[104:105], v[2:3], v[48:51]
	s_waitcnt vmcnt(26)
	v_mfma_f32_16x16x32_fp8_fp8 v[26:29], v[102:103], v[2:3], v[44:47]
	s_waitcnt vmcnt(25)
	v_mfma_f32_16x16x32_fp8_fp8 v[30:33], v[100:101], v[2:3], v[40:43]
	s_waitcnt vmcnt(24)
	v_mfma_f32_16x16x32_fp8_fp8 v[2:5], v[98:99], v[2:3], v[36:39]
	s_cmp_ge_i32 s56, s27
	s_mov_b64 s[10:11], -1
	s_cbranch_scc0 .LBB0_999

; template <bool SLC, bool NOMASK> ...
;     const int kq = lane >> 4;
;     const int pos0 = SLC ? (dcur & 0xfffff) : dcur;
;     const int lo = SLC ? ((((dcur >> 20) == qi) | ((dcur >> 20) == 4)) ? 0 : (1 << 30)) : lo_in;
;     load_frag8(nxt, KF, VF, SLC ? (dnext & 0xfffff) : dnext, lane);
;     f32x4 sa[2] = {(f32x4){0.f, 0.f, 0.f, 0.f}, (f32x4){0.f, 0.f, 0.f, 0.f}};
; #pragma unroll
;     for (int T = 0; T < 2; ++T)
; #pragma unroll
;         for (int s2 = 0; s2 < 4; ++s2) sa[T] = __builtin_amdgcn_mfma_f32_16x16x32_fp8_fp8(cur.k[T][s2], qf[s2], sa[T], 0, 0, 0);
;     float sc[8]; bool vd[8]; float mx = -1e30f;
;     const bool act = lo == 0 || !SLC;
;     if (NOMASK) {
; #pragma unroll
;         for (int j = 0; j < 8; ++j) { sc[j] = sa[j >> 2][j & 3]; vd[j] = act; }
;         mx = fmaxf(fmaxf(fmaxf(sc[0], sc[1]), fmaxf(sc[2], sc[3])), fmaxf(fmaxf(sc[4], sc[5]), fmaxf(sc[6], sc[7])));
;         mx = act ? mx : -1e30f;
;     } else {
; #pragma unroll
;         for (int T = 0; T < 2; ++T)
; #pragma unroll
;             for (int r = 0; r < 4; ++r) { const int p = pos0 + 16 * T + 4 * kq + r; const bool v = (p >= lo) & (p <= hi); const float x = sa[T][r];
;                 sc[4 * T + r] = x; vd[4 * T + r] = v; mx = v ? fmaxf(mx, x) : mx; }
;     }
;     if (__builtin_amdgcn_ballot_w64(mx > st.m + 4.f) != 0ull) {
;         mx = fmaxf(mx, __shfl_xor(mx, 16)); mx = fmaxf(mx, __shfl_xor(mx, 32));
;         const float mn = fmaxf(st.m, mx), alpha = __builtin_amdgcn_exp2f(st.m - mn); st.m = mn; st.l *= alpha;
; #pragma unroll
;         for (int j = 0; j < 8; ++j) st.o[j] = st.o[j] * alpha;
;     }
;     f32x4 pa, pb; float ps = 0.f;
;     const float mref = st.m - 4.f;
;     if (NOMASK) {
; #pragma unroll
;         for (int j = 0; j < 4; ++j) { pa[j] = __builtin_amdgcn_exp2f(sc[j] - mref); pb[j] = __builtin_amdgcn_exp2f(sc[4 + j] - mref); }
;         if (SLC) {
; #pragma unroll
;             for (int j = 0; j < 4; ++j) { pa[j] = act ? pa[j] : 0.f; pb[j] = act ? pb[j] : 0.f; }
;         }
; #pragma unroll
;         for (int j = 0; j < 4; ++j) ps += pa[j] + pb[j];
;     } else {
; #pragma unroll
;         for (int j = 0; j < 4; ++j) { pa[j] = vd[j] ? __builtin_amdgcn_exp2f(sc[j] - mref) : 0.f; pb[j] = vd[4 + j] ? __builtin_amdgcn_exp2f(sc[4 + j] - mref) : 0.f; ps += pa[j] + pb[j]; }
;     }
;     st.l += ps;
;     const u32x2 pw = pack8_fp8(pa, pb);
.LBB0_1009:
	v_lshl_add_u64 v[246:247], v[204:205], 0, v[120:121]
	global_load_dwordx4 v[138:141], v[246:247], off
	global_load_dwordx4 v[142:145], v[246:247], off offset:1024
	global_load_dwordx4 v[146:149], v[246:247], off offset:2048
	global_load_dwordx4 v[150:153], v[246:247], off offset:3072
	global_load_dwordx2 v[90:91], v[202:203], off
	global_load_dwordx2 v[92:93], v[202:203], off offset:512
	global_load_dwordx2 v[94:95], v[202:203], off offset:1024
	global_load_dwordx2 v[96:97], v[202:203], off offset:1536
	global_load_dwordx2 v[104:105], v[202:203], off offset:2048
	global_load_dwordx2 v[102:103], v[202:203], off offset:2560
	global_load_dwordx2 v[100:101], v[202:203], off offset:3072
	global_load_dwordx2 v[98:99], v[202:203], off offset:3584
	s_waitcnt vmcnt(32)
	v_mfma_f32_16x16x32_fp8_fp8 v[36:39], v[154:155], v[78:79], 0
	v_mov_b64_e32 v[74:75], v[4:5]
	v_mov_b64_e32 v[70:71], v[32:33]
	v_mov_b64_e32 v[66:67], v[28:29]
	v_mfma_f32_16x16x32_fp8_fp8 v[40:43], v[162:163], v[78:79], 0
	v_mov_b64_e32 v[62:63], v[24:25]
	v_mov_b64_e32 v[58:59], v[20:21]
	v_mov_b64_e32 v[54:55], v[16:17]
	v_mfma_f32_16x16x32_fp8_fp8 v[36:39], v[156:157], v[80:81], v[36:39]
	v_mov_b64_e32 v[50:51], v[12:13]
	v_mov_b32_e32 v227, v228
	v_mov_b64_e32 v[72:73], v[2:3]
	v_mfma_f32_16x16x32_fp8_fp8 v[40:43], v[164:165], v[80:81], v[40:43]
	v_mov_b64_e32 v[68:69], v[30:31]
	v_mov_b64_e32 v[64:65], v[26:27]
	v_mov_b64_e32 v[60:61], v[22:23]
	v_mfma_f32_16x16x32_fp8_fp8 v[36:39], v[158:159], v[82:83], v[36:39]
	v_mov_b64_e32 v[56:57], v[18:19]
	v_mov_b64_e32 v[52:53], v[14:15]
	v_mov_b64_e32 v[48:49], v[10:11]
	v_mfma_f32_16x16x32_fp8_fp8 v[40:43], v[166:167], v[82:83], v[40:43]
	v_mov_b32_e32 v229, v34
	v_mfma_f32_16x16x32_fp8_fp8 v[36:39], v[160:161], v[84:85], v[36:39]
	v_mfma_f32_16x16x32_fp8_fp8 v[40:43], v[168:169], v[84:85], v[40:43]
	s_nop 5
	v_max_f32_e32 v0, v37, v37
	v_max_f32_e32 v44, v36, v36
	v_max_f32_e32 v0, v44, v0
	v_max_f32_e32 v44, v39, v39
	v_max_f32_e32 v45, v38, v38
	v_max_f32_e32 v44, v45, v44
	v_max_f32_e32 v45, v43, v43
	v_max_f32_e32 v46, v42, v42
	v_max_f32_e32 v45, v46, v45
	v_max3_f32 v45, v40, v41, v45
	v_max3_f32 v0, v0, v44, v45
	v_mov_b64_e32 v[46:47], v[8:9]
	v_cmp_gt_f32_e32 vcc, v0, v133
	v_mov_b64_e32 v[44:45], v[6:7]
	s_cbranch_vccz .LBB0_1011
	ds_bpermute_b32 v44, v225, v0
	v_max_f32_e32 v0, v0, v0
	s_waitcnt lgkmcnt(0)
	v_max_f32_e32 v44, v44, v44
	v_max_f32_e32 v0, v0, v44
	ds_bpermute_b32 v44, v224, v0
	s_waitcnt lgkmcnt(0)
	v_max3_f32 v227, v228, v0, v44
	v_sub_f32_e32 v0, v228, v227
	v_exp_f32_e32 v0, v0
	s_nop 0
	v_mul_f32_e32 v229, v34, v0
	v_pk_mul_f32 v[46:47], v[8:9], v[0:1] op_sel_hi:[1,0]
	v_pk_mul_f32 v[44:45], v[6:7], v[0:1] op_sel_hi:[1,0]
	v_pk_mul_f32 v[50:51], v[12:13], v[0:1] op_sel_hi:[1,0]
	v_pk_mul_f32 v[48:49], v[10:11], v[0:1] op_sel_hi:[1,0]
	v_pk_mul_f32 v[54:55], v[16:17], v[0:1] op_sel_hi:[1,0]
	v_pk_mul_f32 v[52:53], v[14:15], v[0:1] op_sel_hi:[1,0]
	v_pk_mul_f32 v[58:59], v[20:21], v[0:1] op_sel_hi:[1,0]
	v_pk_mul_f32 v[56:57], v[18:19], v[0:1] op_sel_hi:[1,0]
	v_pk_mul_f32 v[62:63], v[24:25], v[0:1] op_sel_hi:[1,0]
	v_pk_mul_f32 v[60:61], v[22:23], v[0:1] op_sel_hi:[1,0]
	v_pk_mul_f32 v[66:67], v[28:29], v[0:1] op_sel_hi:[1,0]
	v_pk_mul_f32 v[64:65], v[26:27], v[0:1] op_sel_hi:[1,0]
	v_pk_mul_f32 v[70:71], v[32:33], v[0:1] op_sel_hi:[1,0]
	v_pk_mul_f32 v[68:69], v[30:31], v[0:1] op_sel_hi:[1,0]
	v_pk_mul_f32 v[74:75], v[4:5], v[0:1] op_sel_hi:[1,0]
	v_pk_mul_f32 v[72:73], v[2:3], v[0:1] op_sel_hi:[1,0]
.LBB0_1011:
	v_add_f32_e32 v231, -4.0, v227
	v_sub_f32_e32 v0, v36, v231
	v_exp_f32_e32 v233, v0
	v_sub_f32_e32 v0, v40, v231
	v_exp_f32_e32 v235, v0
	v_sub_f32_e32 v0, v37, v231
	v_exp_f32_e32 v230, v0
	v_sub_f32_e32 v0, v41, v231
	v_exp_f32_e32 v0, v0
	v_sub_f32_e32 v36, v38, v231
	v_exp_f32_e32 v238, v36
	v_sub_f32_e32 v36, v42, v231
	v_exp_f32_e32 v239, v36
	v_sub_f32_e32 v36, v39, v231
	v_exp_f32_e32 v232, v36
	v_sub_f32_e32 v36, v43, v231
	v_mov_b32_e32 v236, v1
	v_mov_b32_e32 v237, v1
	v_exp_f32_e32 v234, v36
	v_cvt_pk_fp8_f32 v236, v233, v230
	v_cvt_pk_fp8_f32 v237, v235, v0
	v_add_f32_e32 v231, v233, v235
	v_add_f32_e32 v233, v238, v239
	v_cvt_pk_fp8_f32 v236, v238, v232 op_sel:[0,0,1]
	v_cvt_pk_fp8_f32 v237, v239, v234 op_sel:[0,0,1]
	s_nop 0
	s_waitcnt vmcnt(31)
	v_mfma_f32_16x16x32_fp8_fp8 v[36:39], v[106:107], v[236:237], v[44:47]
	s_waitcnt vmcnt(30)
	v_mfma_f32_16x16x32_fp8_fp8 v[44:47], v[112:113], v[236:237], v[52:55]
	s_waitcnt vmcnt(29)
	v_mfma_f32_16x16x32_fp8_fp8 v[52:55], v[136:137], v[236:237], v[60:63]
	s_nop 2
	v_add_f32_e64 v60, v230, v0
	v_add_f32_e64 v61, v231, v1
	s_waitcnt vmcnt(28)
	v_mfma_f32_16x16x32_fp8_fp8 v[40:43], v[110:111], v[236:237], v[48:51]
	v_pk_add_f32 v[60:61], v[60:61], v[60:61] op_sel_hi:[0,1]
	v_mov_b32_e32 v235, v61
	s_waitcnt vmcnt(27)
	v_mfma_f32_16x16x32_fp8_fp8 v[48:51], v[116:117], v[236:237], v[56:59]
	s_waitcnt vmcnt(26)
	v_mfma_f32_16x16x32_fp8_fp8 v[56:59], v[134:135], v[236:237], v[64:67]
	s_nop 2
	v_add_f32_e64 v64, v232, v234
	v_add_f32_e64 v65, v233, v235
	s_waitcnt vmcnt(25)
	v_mfma_f32_16x16x32_fp8_fp8 v[60:63], v[114:115], v[236:237], v[68:71]
	v_add_f32_e32 v0, v64, v65
	v_add_f32_e32 v229, v0, v229
	s_waitcnt vmcnt(24)
	v_mfma_f32_16x16x32_fp8_fp8 v[64:67], v[108:109], v[236:237], v[72:75]
	s_branch .LBB0_1001
; template <bool SLC, bool NOMASK> ...
;     const int kq = lane >> 4;
;     const int pos0 = SLC ? (dcur & 0xfffff) : dcur;
;     const int lo = SLC ? ((((dcur >> 20) == qi) | ((dcur >> 20) == 4)) ? 0 : (1 << 30)) : lo_in;
;     load_frag8(nxt, KF, VF, SLC ? (dnext & 0xfffff) : dnext, lane);
;     f32x4 sa[2] = {(f32x4){0.f, 0.f, 0.f, 0.f}, (f32x4){0.f, 0.f, 0.f, 0.f}};
; #pragma unroll
;     for (int T = 0; T < 2; ++T)
; #pragma unroll
;         for (int s2 = 0; s2 < 4; ++s2) sa[T] = __builtin_amdgcn_mfma_f32_16x16x32_fp8_fp8(cur.k[T][s2], qf[s2], sa[T], 0, 0, 0);
;     float sc[8]; bool vd[8]; float mx = -1e30f;
;     const bool act = lo == 0 || !SLC;
;     if (NOMASK) {
; #pragma unroll
;         for (int j = 0; j < 8; ++j) { sc[j] = sa[j >> 2][j & 3]; vd[j] = act; }
;         mx = fmaxf(fmaxf(fmaxf(sc[0], sc[1]), fmaxf(sc[2], sc[3])), fmaxf(fmaxf(sc[4], sc[5]), fmaxf(sc[6], sc[7])));
;         mx = act ? mx : -1e30f;
;     } else {
; #pragma unroll
;         for (int T = 0; T < 2; ++T)
; #pragma unroll
;             for (int r = 0; r < 4; ++r) { const int p = pos0 + 16 * T + 4 * kq + r; const bool v = (p >= lo) & (p <= hi); const float x = sa[T][r];
;                 sc[4 * T + r] = x; vd[4 * T + r] = v; mx = v ? fmaxf(mx, x) : mx; }
;     }
;     if (__builtin_amdgcn_ballot_w64(mx > st.m + 4.f) != 0ull) {
;         mx = fmaxf(mx, __shfl_xor(mx, 16)); mx = fmaxf(mx, __shfl_xor(mx, 32));
;         const float mn = fmaxf(st.m, mx), alpha = __builtin_amdgcn_exp2f(st.m - mn); st.m = mn; st.l *= alpha;
; #pragma unroll
;         for (int j = 0; j < 8; ++j) st.o[j] = st.o[j] * alpha;
;     }
;     f32x4 pa, pb; float ps = 0.f;
;     const float mref = st.m - 4.f;
;     if (NOMASK) {
; #pragma unroll
;         for (int j = 0; j < 4; ++j) { pa[j] = __builtin_amdgcn_exp2f(sc[j] - mref); pb[j] = __builtin_amdgcn_exp2f(sc[4 + j] - mref); }
;         if (SLC) {
; #pragma unroll
;             for (int j = 0; j < 4; ++j) { pa[j] = act ? pa[j] : 0.f; pb[j] = act ? pb[j] : 0.f; }
;         }
; #pragma unroll
;         for (int j = 0; j < 4; ++j) ps += pa[j] + pb[j];
;     } else {
; #pragma unroll
;         for (int j = 0; j < 4; ++j) { pa[j] = vd[j] ? __builtin_amdgcn_exp2f(sc[j] - mref) : 0.f; pb[j] = vd[4 + j] ? __builtin_amdgcn_exp2f(sc[4 + j] - mref) : 0.f; ps += pa[j] + pb[j]; }
;     }
;     st.l += ps;
;     const u32x2 pw = pack8_fp8(pa, pb);
.LBB0_1012:
	v_lshl_add_u64 v[246:247], v[204:205], 0, v[120:121]
	global_load_dwordx4 v[138:141], v[246:247], off
	global_load_dwordx4 v[142:145], v[246:247], off offset:1024
	global_load_dwordx4 v[146:149], v[246:247], off offset:2048
	global_load_dwordx4 v[150:153], v[246:247], off offset:3072
	global_load_dwordx2 v[90:91], v[202:203], off
	global_load_dwordx2 v[92:93], v[202:203], off offset:512
	global_load_dwordx2 v[94:95], v[202:203], off offset:1024
	global_load_dwordx2 v[96:97], v[202:203], off offset:1536
	global_load_dwordx2 v[104:105], v[202:203], off offset:2048
	global_load_dwordx2 v[102:103], v[202:203], off offset:2560
	global_load_dwordx2 v[100:101], v[202:203], off offset:3072
	global_load_dwordx2 v[98:99], v[202:203], off offset:3584
	s_waitcnt vmcnt(32)
	v_mfma_f32_16x16x32_fp8_fp8 v[36:39], v[154:155], v[78:79], 0
	v_add_u32_e32 v0, s66, v210
	v_cmp_ge_i32_e32 vcc, v0, v35
	v_cmp_le_i32_e64 s[10:11], v0, v132
	v_mfma_f32_16x16x32_fp8_fp8 v[36:39], v[156:157], v[80:81], v[36:39]
	s_and_b64 s[16:17], vcc, s[10:11]
	v_add_u32_e32 v45, 1, v0
	v_cmp_ge_i32_e32 vcc, v45, v35
	v_mfma_f32_16x16x32_fp8_fp8 v[36:39], v[158:159], v[82:83], v[36:39]
	v_cmp_lt_i32_e64 s[10:11], v0, v132
	s_and_b64 s[12:13], s[10:11], vcc
	v_mfma_f32_16x16x32_fp8_fp8 v[40:43], v[162:163], v[78:79], 0
	v_mfma_f32_16x16x32_fp8_fp8 v[36:39], v[160:161], v[84:85], v[36:39]
	v_mfma_f32_16x16x32_fp8_fp8 v[40:43], v[164:165], v[80:81], v[40:43]
	v_mfma_f32_16x16x32_fp8_fp8 v[40:43], v[166:167], v[82:83], v[40:43]
	s_nop 3
	v_max_f32_e32 v44, v36, v36
	v_max_f32_e32 v44, 0xf149f2ca, v44
	v_cndmask_b32_e64 v44, v220, v44, s[16:17]
	v_max_f32_e32 v45, v37, v37
	v_max_f32_e32 v45, v44, v45
	v_cndmask_b32_e64 v44, v44, v45, s[12:13]
	v_add_u32_e32 v45, 2, v0
	v_cmp_ge_i32_e32 vcc, v45, v35
	v_cmp_le_i32_e64 s[10:11], v45, v132
	v_max_f32_e32 v45, v38, v38
	v_max_f32_e32 v45, v44, v45
	s_and_b64 s[14:15], vcc, s[10:11]
	v_mfma_f32_16x16x32_fp8_fp8 v[40:43], v[168:169], v[84:85], v[40:43]
	v_cndmask_b32_e64 v44, v44, v45, s[14:15]
	v_add_u32_e32 v45, 3, v0
	v_cmp_ge_i32_e32 vcc, v45, v35
	v_cmp_le_i32_e64 s[10:11], v45, v132
	v_max_f32_e32 v45, v39, v39
	v_max_f32_e32 v45, v44, v45
	s_and_b64 s[10:11], vcc, s[10:11]
	v_cndmask_b32_e64 v44, v44, v45, s[10:11]
	v_add_u32_e32 v45, 16, v0
	v_cmp_ge_i32_e32 vcc, v45, v35
	v_cmp_le_i32_e64 s[18:19], v45, v132
	v_max_f32_e32 v45, v40, v40
	v_max_f32_e32 v45, v44, v45
	s_and_b64 s[24:25], vcc, s[18:19]
	v_cndmask_b32_e64 v44, v44, v45, s[24:25]
	v_add_u32_e32 v45, 17, v0
	v_cmp_ge_i32_e32 vcc, v45, v35
	v_cmp_le_i32_e64 s[18:19], v45, v132
	v_max_f32_e32 v45, v44, v44
	v_max_f32_e32 v46, v41, v41
	v_max_f32_e32 v45, v45, v46
	s_and_b64 s[20:21], vcc, s[18:19]
	v_cndmask_b32_e64 v44, v44, v45, s[20:21]
	v_add_u32_e32 v45, 18, v0
	v_cmp_ge_i32_e32 vcc, v45, v35
	v_cmp_le_i32_e64 s[18:19], v45, v132
	v_max_f32_e32 v45, v44, v44
	v_max_f32_e32 v46, v42, v42
	v_max_f32_e32 v45, v45, v46
	s_and_b64 s[22:23], vcc, s[18:19]
	v_cndmask_b32_e64 v44, v44, v45, s[22:23]
	v_add_u32_e32 v0, 19, v0
	v_cmp_ge_i32_e32 vcc, v0, v35
	v_cmp_le_i32_e64 s[18:19], v0, v132
	v_max_f32_e32 v0, v44, v44
	v_max_f32_e32 v45, v43, v43
	v_max_f32_e32 v0, v0, v45
	s_and_b64 s[18:19], vcc, s[18:19]
	v_cndmask_b32_e64 v0, v44, v0, s[18:19]
	v_cmp_gt_f32_e32 vcc, v0, v133
	s_cbranch_vccz .LBB0_1014
	ds_bpermute_b32 v44, v225, v0
	v_max_f32_e32 v0, v0, v0
	s_waitcnt lgkmcnt(0)
	v_max_f32_e32 v44, v44, v44
	v_max_f32_e32 v0, v0, v44
	ds_bpermute_b32 v44, v224, v0
	s_waitcnt lgkmcnt(0)
	v_max3_f32 v44, v228, v0, v44
	v_sub_f32_e32 v0, v228, v44
	v_exp_f32_e32 v0, v0
	v_mov_b32_e32 v228, v44
	v_mul_f32_e32 v34, v34, v0
	v_pk_mul_f32 v[8:9], v[8:9], v[0:1] op_sel_hi:[1,0]
	v_pk_mul_f32 v[6:7], v[6:7], v[0:1] op_sel_hi:[1,0]
	v_pk_mul_f32 v[12:13], v[12:13], v[0:1] op_sel_hi:[1,0]
	v_pk_mul_f32 v[10:11], v[10:11], v[0:1] op_sel_hi:[1,0]
	v_pk_mul_f32 v[16:17], v[16:17], v[0:1] op_sel_hi:[1,0]
	v_pk_mul_f32 v[14:15], v[14:15], v[0:1] op_sel_hi:[1,0]
	v_pk_mul_f32 v[20:21], v[20:21], v[0:1] op_sel_hi:[1,0]
	v_pk_mul_f32 v[18:19], v[18:19], v[0:1] op_sel_hi:[1,0]
	v_pk_mul_f32 v[24:25], v[24:25], v[0:1] op_sel_hi:[1,0]
	v_pk_mul_f32 v[22:23], v[22:23], v[0:1] op_sel_hi:[1,0]
	v_pk_mul_f32 v[28:29], v[28:29], v[0:1] op_sel_hi:[1,0]
	v_pk_mul_f32 v[26:27], v[26:27], v[0:1] op_sel_hi:[1,0]
	v_pk_mul_f32 v[32:33], v[32:33], v[0:1] op_sel_hi:[1,0]
	v_pk_mul_f32 v[30:31], v[30:31], v[0:1] op_sel_hi:[1,0]
	v_pk_mul_f32 v[4:5], v[4:5], v[0:1] op_sel_hi:[1,0]
	v_pk_mul_f32 v[2:3], v[2:3], v[0:1] op_sel_hi:[1,0]
.LBB0_1014:
	v_add_f32_e32 v0, -4.0, v228
	v_sub_f32_e32 v36, v36, v0
	v_exp_f32_e32 v36, v36
	v_sub_f32_e32 v40, v40, v0
	v_exp_f32_e32 v40, v40
	v_sub_f32_e32 v38, v38, v0
	v_cndmask_b32_e64 v56, 0, v36, s[16:17]
	v_sub_f32_e32 v36, v37, v0
	v_exp_f32_e32 v36, v36
	v_sub_f32_e32 v37, v41, v0
	v_exp_f32_e32 v37, v37
	v_cndmask_b32_e64 v57, 0, v40, s[24:25]
	v_sub_f32_e32 v40, v42, v0
	v_cndmask_b32_e64 v58, 0, v36, s[12:13]
	v_sub_f32_e32 v36, v39, v0
	v_sub_f32_e32 v0, v43, v0
	v_exp_f32_e32 v38, v38
	v_exp_f32_e32 v40, v40
	v_cndmask_b32_e64 v59, 0, v37, s[20:21]
	v_exp_f32_e32 v36, v36
	v_exp_f32_e32 v0, v0
	v_mov_b32_e32 v64, v1
	v_mov_b32_e32 v65, v1
	v_cvt_pk_fp8_f32 v64, v56, v58
	v_cvt_pk_fp8_f32 v65, v57, v59
	v_cndmask_b32_e64 v60, 0, v38, s[14:15]
	v_cndmask_b32_e64 v61, 0, v40, s[22:23]
	v_cndmask_b32_e64 v66, 0, v36, s[10:11]
	v_cndmask_b32_e64 v0, 0, v0, s[18:19]
	v_cvt_pk_fp8_f32 v64, v60, v66 op_sel:[0,0,1]
	v_cvt_pk_fp8_f32 v65, v61, v0 op_sel:[0,0,1]
	v_add_f32_e32 v0, v66, v0
	v_mov_b32_e32 v227, v228
	s_waitcnt vmcnt(31)
	v_mfma_f32_16x16x32_fp8_fp8 v[36:39], v[106:107], v[64:65], v[6:9]
	s_nop 2
	v_add_f32_e32 v6, v56, v57
	v_add_f32_e32 v6, 0, v6
	v_add_f32_e32 v7, v58, v59
	s_waitcnt vmcnt(30)
	v_mfma_f32_16x16x32_fp8_fp8 v[40:43], v[110:111], v[64:65], v[10:13]
	v_add_f32_e32 v6, v7, v6
	v_add_f32_e32 v7, v60, v61
	v_add_f32_e32 v6, v7, v6
	s_waitcnt vmcnt(29)
	v_mfma_f32_16x16x32_fp8_fp8 v[44:47], v[112:113], v[64:65], v[14:17]
	v_add_f32_e32 v0, v0, v6
	v_add_f32_e32 v229, v34, v0
	s_waitcnt vmcnt(28)
	v_mfma_f32_16x16x32_fp8_fp8 v[48:51], v[116:117], v[64:65], v[18:21]
	s_waitcnt vmcnt(27)
	v_mfma_f32_16x16x32_fp8_fp8 v[52:55], v[136:137], v[64:65], v[22:25]
	s_waitcnt vmcnt(26)
	v_mfma_f32_16x16x32_fp8_fp8 v[56:59], v[134:135], v[64:65], v[26:29]
	s_waitcnt vmcnt(25)
	v_mfma_f32_16x16x32_fp8_fp8 v[60:63], v[114:115], v[64:65], v[30:33]
	s_waitcnt vmcnt(24)
	v_mfma_f32_16x16x32_fp8_fp8 v[64:67], v[108:109], v[64:65], v[2:5]
	s_cmp_gt_i32 s55, s27
	s_mov_b64 s[10:11], -1
	s_cbranch_scc1 .LBB0_994
; template <bool SLC, bool NOMASK> ...
;     const int kq = lane >> 4;
;     const int pos0 = SLC ? (dcur & 0xfffff) : dcur;
;     const int lo = SLC ? ((((dcur >> 20) == qi) | ((dcur >> 20) == 4)) ? 0 : (1 << 30)) : lo_in;
;     load_frag8(nxt, KF, VF, SLC ? (dnext & 0xfffff) : dnext, lane);
;     f32x4 sa[2] = {(f32x4){0.f, 0.f, 0.f, 0.f}, (f32x4){0.f, 0.f, 0.f, 0.f}};
; #pragma unroll
;     for (int T = 0; T < 2; ++T)
; #pragma unroll
;         for (int s2 = 0; s2 < 4; ++s2) sa[T] = __builtin_amdgcn_mfma_f32_16x16x32_fp8_fp8(cur.k[T][s2], qf[s2], sa[T], 0, 0, 0);
;     float sc[8]; bool vd[8]; float mx = -1e30f;
;     const bool act = lo == 0 || !SLC;
;     if (NOMASK) {
; #pragma unroll
;         for (int j = 0; j < 8; ++j) { sc[j] = sa[j >> 2][j & 3]; vd[j] = act; }
;         mx = fmaxf(fmaxf(fmaxf(sc[0], sc[1]), fmaxf(sc[2], sc[3])), fmaxf(fmaxf(sc[4], sc[5]), fmaxf(sc[6], sc[7])));
;         mx = act ? mx : -1e30f;
;     } else {
; #pragma unroll
;         for (int T = 0; T < 2; ++T)
; #pragma unroll
;             for (int r = 0; r < 4; ++r) { const int p = pos0 + 16 * T + 4 * kq + r; const bool v = (p >= lo) & (p <= hi); const float x = sa[T][r];
;                 sc[4 * T + r] = x; vd[4 * T + r] = v; mx = v ? fmaxf(mx, x) : mx; }
;     }
;     if (__builtin_amdgcn_ballot_w64(mx > st.m + 4.f) != 0ull) {
;         mx = fmaxf(mx, __shfl_xor(mx, 16)); mx = fmaxf(mx, __shfl_xor(mx, 32));
;         const float mn = fmaxf(st.m, mx), alpha = __builtin_amdgcn_exp2f(st.m - mn); st.m = mn; st.l *= alpha;
; #pragma unroll
;         for (int j = 0; j < 8; ++j) st.o[j] = st.o[j] * alpha;
;     }
;     f32x4 pa, pb; float ps = 0.f;
;     const float mref = st.m - 4.f;
; template <bool SLC, class Desc>
; __device__ __forceinline__ void attn_run_frag8(const i64_t (&qf)[4], const unsigned char* __restrict__ KF, const unsigned char* __restrict__ VF, const Desc& desc, int n,
;                                                int lo_in, int hi, int qi, AState& st, int lane) {
;     ...
;     for (int i = 0; i < n; i += 3) {
;         const int d2 = desc(i + 2 < n ? i + 2 : n - 1);
;         F8_STEP(fa, fc, d0, d2);
;         if (i + 1 >= n) break;
;         const int d3 = desc(i + 3 < n ? i + 3 : n - 1);
;         F8_STEP(fb, fa, d1, d3);
;         if (i + 2 >= n) break;
;         const int d4 = desc(i + 4 < n ? i + 4 : n - 1);
;         F8_STEP(fc, fb, d2, d4);
.LBB0_1015:
	s_cmp_lt_i32 s57, s54
	s_cselect_b64 s[10:11], -1, 0
	s_or_b32 s12, s57, 31
	s_cmp_gt_i32 s12, s90
	s_cselect_b64 s[12:13], -1, 0
	s_or_b64 s[10:11], s[10:11], s[12:13]
	s_and_b64 s[10:11], s[10:11], exec
	s_cselect_b32 s10, 0, 2.0
	s_add_i32 s56, s56, 4
	s_or_b32 s14, s10, s57
	s_min_i32 s10, s56, s27
	s_add_i32 s12, s10, s26
	s_lshl_b32 s43, s12, 5
	s_and_b32 s10, s43, 0x3fffffe0
	s_lshr_b32 s50, s10, 4
	s_lshl_b64 s[10:11], s[50:51], 11
	s_and_b32 s50, s12, 0x1ffffff
	s_lshl_b64 s[12:13], s[50:51], 12
	s_cmp_lt_u32 s14, 2.0
	v_lshl_add_u64 v[204:205], v[86:87], 0, s[10:11]
	v_lshl_add_u64 v[202:203], v[88:89], 0, s[12:13]
	s_mov_b64 s[10:11], -1
	v_add_f32_e32 v228, 4.0, v227
	s_cbranch_scc1 .LBB0_1019
	v_lshl_add_u64 v[246:247], v[204:205], 0, v[120:121]
	global_load_dwordx4 v[154:157], v[246:247], off
	global_load_dwordx4 v[158:161], v[246:247], off offset:1024
	global_load_dwordx4 v[162:165], v[246:247], off offset:2048
	global_load_dwordx4 v[166:169], v[246:247], off offset:3072
	global_load_dwordx2 v[106:107], v[202:203], off
	global_load_dwordx2 v[110:111], v[202:203], off offset:512
	global_load_dwordx2 v[112:113], v[202:203], off offset:1024
	global_load_dwordx2 v[116:117], v[202:203], off offset:1536
	global_load_dwordx2 v[136:137], v[202:203], off offset:2048
	global_load_dwordx2 v[134:135], v[202:203], off offset:2560
	global_load_dwordx2 v[114:115], v[202:203], off offset:3072
	global_load_dwordx2 v[108:109], v[202:203], off offset:3584
	s_waitcnt vmcnt(32)
	v_mfma_f32_16x16x32_fp8_fp8 v[2:5], v[186:187], v[78:79], 0
	v_mov_b64_e32 v[74:75], v[66:67]
	v_mov_b64_e32 v[70:71], v[62:63]
	v_mov_b64_e32 v[30:31], v[56:57]
	v_mfma_f32_16x16x32_fp8_fp8 v[6:9], v[194:195], v[78:79], 0
	v_mov_b64_e32 v[26:27], v[52:53]
	v_mov_b64_e32 v[22:23], v[48:49]
	v_mov_b64_e32 v[18:19], v[44:45]
	v_mfma_f32_16x16x32_fp8_fp8 v[2:5], v[188:189], v[80:81], v[2:5]
	v_mov_b64_e32 v[14:15], v[40:41]
	v_mov_b32_e32 v133, v227
	v_mov_b64_e32 v[72:73], v[64:65]
	v_mfma_f32_16x16x32_fp8_fp8 v[6:9], v[196:197], v[80:81], v[6:9]
	v_mov_b64_e32 v[68:69], v[60:61]
	v_mov_b64_e32 v[32:33], v[58:59]
	v_mov_b64_e32 v[28:29], v[54:55]
	v_mfma_f32_16x16x32_fp8_fp8 v[2:5], v[190:191], v[82:83], v[2:5]
	v_mov_b64_e32 v[24:25], v[50:51]
	v_mov_b64_e32 v[20:21], v[46:47]
	v_mov_b64_e32 v[16:17], v[42:43]
	v_mfma_f32_16x16x32_fp8_fp8 v[6:9], v[198:199], v[82:83], v[6:9]
	v_mov_b32_e32 v34, v229
	v_mfma_f32_16x16x32_fp8_fp8 v[2:5], v[192:193], v[84:85], v[2:5]
	v_mfma_f32_16x16x32_fp8_fp8 v[6:9], v[200:201], v[84:85], v[6:9]
	s_nop 5
	v_max_f32_e32 v0, v3, v3
	v_max_f32_e32 v10, v2, v2
	v_max_f32_e32 v0, v10, v0
	v_max_f32_e32 v10, v5, v5
	v_max_f32_e32 v11, v4, v4
	v_max_f32_e32 v10, v11, v10
	v_max_f32_e32 v11, v9, v9
	v_max_f32_e32 v12, v8, v8
	v_max_f32_e32 v11, v12, v11
	v_max3_f32 v11, v6, v7, v11
	v_max3_f32 v0, v0, v10, v11
	v_mov_b64_e32 v[10:11], v[36:37]
	v_cmp_gt_f32_e32 vcc, v0, v228
	v_mov_b64_e32 v[12:13], v[38:39]
	s_cbranch_vccz .LBB0_1018
	ds_bpermute_b32 v10, v225, v0
	v_max_f32_e32 v0, v0, v0
	s_waitcnt lgkmcnt(0)
	v_max_f32_e32 v10, v10, v10
	v_max_f32_e32 v0, v0, v10
	ds_bpermute_b32 v10, v224, v0
	s_waitcnt lgkmcnt(0)
	v_max3_f32 v133, v227, v0, v10
	v_sub_f32_e32 v0, v227, v133
	v_exp_f32_e32 v0, v0
	s_nop 0
	v_mul_f32_e32 v34, v229, v0
	v_pk_mul_f32 v[12:13], v[38:39], v[0:1] op_sel_hi:[1,0]
	v_pk_mul_f32 v[10:11], v[36:37], v[0:1] op_sel_hi:[1,0]
	v_pk_mul_f32 v[16:17], v[42:43], v[0:1] op_sel_hi:[1,0]
	v_pk_mul_f32 v[14:15], v[40:41], v[0:1] op_sel_hi:[1,0]
	v_pk_mul_f32 v[20:21], v[46:47], v[0:1] op_sel_hi:[1,0]
	v_pk_mul_f32 v[18:19], v[44:45], v[0:1] op_sel_hi:[1,0]
	v_pk_mul_f32 v[24:25], v[50:51], v[0:1] op_sel_hi:[1,0]
	v_pk_mul_f32 v[22:23], v[48:49], v[0:1] op_sel_hi:[1,0]
	v_pk_mul_f32 v[28:29], v[54:55], v[0:1] op_sel_hi:[1,0]
	v_pk_mul_f32 v[26:27], v[52:53], v[0:1] op_sel_hi:[1,0]
	v_pk_mul_f32 v[32:33], v[58:59], v[0:1] op_sel_hi:[1,0]
	v_pk_mul_f32 v[30:31], v[56:57], v[0:1] op_sel_hi:[1,0]
	v_pk_mul_f32 v[70:71], v[62:63], v[0:1] op_sel_hi:[1,0]
	v_pk_mul_f32 v[68:69], v[60:61], v[0:1] op_sel_hi:[1,0]
	v_pk_mul_f32 v[74:75], v[66:67], v[0:1] op_sel_hi:[1,0]
	v_pk_mul_f32 v[72:73], v[64:65], v[0:1] op_sel_hi:[1,0]
.LBB0_1018:
	v_add_f32_e32 v230, -4.0, v133
	v_sub_f32_e32 v0, v2, v230
	v_exp_f32_e32 v231, v0
	v_sub_f32_e32 v0, v6, v230
	v_exp_f32_e32 v234, v0
	v_sub_f32_e32 v0, v3, v230
	v_exp_f32_e32 v2, v0
	v_sub_f32_e32 v0, v7, v230
	v_exp_f32_e32 v0, v0
	v_sub_f32_e32 v3, v4, v230
	v_exp_f32_e32 v235, v3
	v_sub_f32_e32 v3, v8, v230
	v_exp_f32_e32 v236, v3
	v_sub_f32_e32 v3, v5, v230
	v_exp_f32_e32 v4, v3
	v_sub_f32_e32 v3, v9, v230
	v_mov_b32_e32 v232, v1
	v_mov_b32_e32 v233, v1
	v_exp_f32_e32 v230, v3
	v_cvt_pk_fp8_f32 v232, v231, v2
	v_cvt_pk_fp8_f32 v233, v234, v0
	v_add_f32_e32 v3, v231, v234
	v_pk_add_f32 v[2:3], v[2:3], v[0:1]
	v_cvt_pk_fp8_f32 v232, v235, v4 op_sel:[0,0,1]
	v_cvt_pk_fp8_f32 v233, v236, v230 op_sel:[0,0,1]
	v_pk_add_f32 v[2:3], v[2:3], v[2:3] op_sel_hi:[0,1]
	v_add_f32_e32 v5, v235, v236
	v_mov_b32_e32 v231, v3
	v_pk_add_f32 v[2:3], v[4:5], v[230:231]
	s_waitcnt vmcnt(31)
	v_mfma_f32_16x16x32_fp8_fp8 v[6:9], v[170:171], v[232:233], v[10:13]
	v_add_f32_e32 v0, v2, v3
	v_add_f32_e32 v34, v0, v34
	s_mov_b64 s[10:11], 0
	s_waitcnt vmcnt(30)
	v_mfma_f32_16x16x32_fp8_fp8 v[10:13], v[172:173], v[232:233], v[14:17]
	s_waitcnt vmcnt(29)
	v_mfma_f32_16x16x32_fp8_fp8 v[14:17], v[174:175], v[232:233], v[18:21]
	s_waitcnt vmcnt(28)
	v_mfma_f32_16x16x32_fp8_fp8 v[18:21], v[176:177], v[232:233], v[22:25]
	s_waitcnt vmcnt(27)
	v_mfma_f32_16x16x32_fp8_fp8 v[22:25], v[184:185], v[232:233], v[26:29]
	s_waitcnt vmcnt(26)
	v_mfma_f32_16x16x32_fp8_fp8 v[26:29], v[182:183], v[232:233], v[30:33]
	s_waitcnt vmcnt(25)
	v_mfma_f32_16x16x32_fp8_fp8 v[30:33], v[180:181], v[232:233], v[68:71]
	s_waitcnt vmcnt(24)
	v_mfma_f32_16x16x32_fp8_fp8 v[2:5], v[178:179], v[232:233], v[72:75]
; template <bool SLC, bool NOMASK> ...
;     const int kq = lane >> 4;
;     const int pos0 = SLC ? (dcur & 0xfffff) : dcur;
;     const int lo = SLC ? ((((dcur >> 20) == qi) | ((dcur >> 20) == 4)) ? 0 : (1 << 30)) : lo_in;
;     load_frag8(nxt, KF, VF, SLC ? (dnext & 0xfffff) : dnext, lane);
;     f32x4 sa[2] = {(f32x4){0.f, 0.f, 0.f, 0.f}, (f32x4){0.f, 0.f, 0.f, 0.f}};
; #pragma unroll
;     for (int T = 0; T < 2; ++T)
; #pragma unroll
;         for (int s2 = 0; s2 < 4; ++s2) sa[T] = __builtin_amdgcn_mfma_f32_16x16x32_fp8_fp8(cur.k[T][s2], qf[s2], sa[T], 0, 0, 0);
;     float sc[8]; bool vd[8]; float mx = -1e30f;
;     const bool act = lo == 0 || !SLC;
;     if (NOMASK) {
; #pragma unroll
;         for (int j = 0; j < 8; ++j) { sc[j] = sa[j >> 2][j & 3]; vd[j] = act; }
;         mx = fmaxf(fmaxf(fmaxf(sc[0], sc[1]), fmaxf(sc[2], sc[3])), fmaxf(fmaxf(sc[4], sc[5]), fmaxf(sc[6], sc[7])));
;         mx = act ? mx : -1e30f;
;     } else {
; #pragma unroll
;         for (int T = 0; T < 2; ++T)
; #pragma unroll
;             for (int r = 0; r < 4; ++r) { const int p = pos0 + 16 * T + 4 * kq + r; const bool v = (p >= lo) & (p <= hi); const float x = sa[T][r];
;                 sc[4 * T + r] = x; vd[4 * T + r] = v; mx = v ? fmaxf(mx, x) : mx; }
;     }
;     if (__builtin_amdgcn_ballot_w64(mx > st.m + 4.f) != 0ull) {
;         mx = fmaxf(mx, __shfl_xor(mx, 16)); mx = fmaxf(mx, __shfl_xor(mx, 32));
;         const float mn = fmaxf(st.m, mx), alpha = __builtin_amdgcn_exp2f(st.m - mn); st.m = mn; st.l *= alpha;
; #pragma unroll
;         for (int j = 0; j < 8; ++j) st.o[j] = st.o[j] * alpha;
;     }
;     f32x4 pa, pb; float ps = 0.f;
;     const float mref = st.m - 4.f;
;     if (NOMASK) {
; #pragma unroll
;         for (int j = 0; j < 4; ++j) { pa[j] = __builtin_amdgcn_exp2f(sc[j] - mref); pb[j] = __builtin_amdgcn_exp2f(sc[4 + j] - mref); }
;         if (SLC) {
; #pragma unroll
;             for (int j = 0; j < 4; ++j) { pa[j] = act ? pa[j] : 0.f; pb[j] = act ? pb[j] : 0.f; }
;         }
; #pragma unroll
;         for (int j = 0; j < 4; ++j) ps += pa[j] + pb[j];
;     } else {
; #pragma unroll
;         for (int j = 0; j < 4; ++j) { pa[j] = vd[j] ? __builtin_amdgcn_exp2f(sc[j] - mref) : 0.f; pb[j] = vd[4 + j] ? __builtin_amdgcn_exp2f(sc[4 + j] - mref) : 0.f; ps += pa[j] + pb[j]; }
;     }
;     st.l += ps;
;     const u32x2 pw = pack8_fp8(pa, pb);
.LBB0_1019:
	s_and_b64 vcc, exec, s[10:11]
	s_cbranch_vccz .LBB0_1023
	v_lshl_add_u64 v[246:247], v[204:205], 0, v[120:121]
	global_load_dwordx4 v[154:157], v[246:247], off
	global_load_dwordx4 v[158:161], v[246:247], off offset:1024
	global_load_dwordx4 v[162:165], v[246:247], off offset:2048
	global_load_dwordx4 v[166:169], v[246:247], off offset:3072
	global_load_dwordx2 v[106:107], v[202:203], off
	global_load_dwordx2 v[110:111], v[202:203], off offset:512
	global_load_dwordx2 v[112:113], v[202:203], off offset:1024
	global_load_dwordx2 v[116:117], v[202:203], off offset:1536
	global_load_dwordx2 v[136:137], v[202:203], off offset:2048
	global_load_dwordx2 v[134:135], v[202:203], off offset:2560
	global_load_dwordx2 v[114:115], v[202:203], off offset:3072
	global_load_dwordx2 v[108:109], v[202:203], off offset:3584
	s_waitcnt vmcnt(32)
	v_mfma_f32_16x16x32_fp8_fp8 v[2:5], v[186:187], v[78:79], 0
	v_or_b32_e32 v0, s57, v210
	v_cmp_ge_i32_e32 vcc, v0, v35
	v_cmp_le_i32_e64 s[10:11], v0, v132
	v_mfma_f32_16x16x32_fp8_fp8 v[2:5], v[188:189], v[80:81], v[2:5]
	s_and_b64 s[16:17], vcc, s[10:11]
	v_or_b32_e32 v11, 1, v0
	v_cmp_ge_i32_e32 vcc, v11, v35
	v_mfma_f32_16x16x32_fp8_fp8 v[2:5], v[190:191], v[82:83], v[2:5]
	v_cmp_lt_i32_e64 s[10:11], v0, v132
	s_and_b64 s[12:13], s[10:11], vcc
	v_mfma_f32_16x16x32_fp8_fp8 v[6:9], v[194:195], v[78:79], 0
	v_mfma_f32_16x16x32_fp8_fp8 v[2:5], v[192:193], v[84:85], v[2:5]
	v_mfma_f32_16x16x32_fp8_fp8 v[6:9], v[196:197], v[80:81], v[6:9]
	v_mfma_f32_16x16x32_fp8_fp8 v[6:9], v[198:199], v[82:83], v[6:9]
	s_nop 3
	v_max_f32_e32 v10, v2, v2
	v_max_f32_e32 v10, 0xf149f2ca, v10
	v_cndmask_b32_e64 v10, v220, v10, s[16:17]
	v_max_f32_e32 v11, v3, v3
	v_max_f32_e32 v11, v10, v11
	v_cndmask_b32_e64 v10, v10, v11, s[12:13]
	v_or_b32_e32 v11, 2, v0
	v_cmp_ge_i32_e32 vcc, v11, v35
	v_cmp_le_i32_e64 s[10:11], v11, v132
	v_max_f32_e32 v11, v4, v4
	v_max_f32_e32 v11, v10, v11
	s_and_b64 s[14:15], vcc, s[10:11]
	v_mfma_f32_16x16x32_fp8_fp8 v[6:9], v[200:201], v[84:85], v[6:9]
	v_cndmask_b32_e64 v10, v10, v11, s[14:15]
	v_or_b32_e32 v11, 3, v0
	v_cmp_ge_i32_e32 vcc, v11, v35
	v_cmp_le_i32_e64 s[10:11], v11, v132
	v_max_f32_e32 v11, v5, v5
	v_max_f32_e32 v11, v10, v11
	s_and_b64 s[10:11], vcc, s[10:11]
	v_cndmask_b32_e64 v10, v10, v11, s[10:11]
	v_or_b32_e32 v11, 16, v0
	v_cmp_ge_i32_e32 vcc, v11, v35
	v_cmp_le_i32_e64 s[18:19], v11, v132
	v_max_f32_e32 v11, v6, v6
	v_max_f32_e32 v11, v10, v11
	s_and_b64 s[24:25], vcc, s[18:19]
	v_cndmask_b32_e64 v10, v10, v11, s[24:25]
	v_or_b32_e32 v11, 17, v0
	v_cmp_ge_i32_e32 vcc, v11, v35
	v_cmp_le_i32_e64 s[18:19], v11, v132
	v_max_f32_e32 v11, v10, v10
	v_max_f32_e32 v12, v7, v7
	v_max_f32_e32 v11, v11, v12
	s_and_b64 s[20:21], vcc, s[18:19]
	v_cndmask_b32_e64 v10, v10, v11, s[20:21]
	v_or_b32_e32 v11, 18, v0
	v_cmp_ge_i32_e32 vcc, v11, v35
	v_cmp_le_i32_e64 s[18:19], v11, v132
	v_max_f32_e32 v11, v10, v10
	v_max_f32_e32 v12, v8, v8
	v_max_f32_e32 v11, v11, v12
	s_and_b64 s[22:23], vcc, s[18:19]
	v_cndmask_b32_e64 v10, v10, v11, s[22:23]
	v_or_b32_e32 v0, 19, v0
	v_cmp_ge_i32_e32 vcc, v0, v35
	v_cmp_le_i32_e64 s[18:19], v0, v132
	v_max_f32_e32 v0, v10, v10
	v_max_f32_e32 v11, v9, v9
	v_max_f32_e32 v0, v0, v11
	s_and_b64 s[18:19], vcc, s[18:19]
	v_cndmask_b32_e64 v0, v10, v0, s[18:19]
	v_cmp_gt_f32_e32 vcc, v0, v228
	s_cbranch_vccz .LBB0_1022
	ds_bpermute_b32 v10, v225, v0
	v_max_f32_e32 v0, v0, v0
	s_waitcnt lgkmcnt(0)
	v_max_f32_e32 v10, v10, v10
	v_max_f32_e32 v0, v0, v10
	ds_bpermute_b32 v10, v224, v0
	s_waitcnt lgkmcnt(0)
	v_max3_f32 v10, v227, v0, v10
	v_sub_f32_e32 v0, v227, v10
	v_exp_f32_e32 v0, v0
	v_mov_b32_e32 v227, v10
	v_mul_f32_e32 v229, v229, v0
	v_pk_mul_f32 v[38:39], v[38:39], v[0:1] op_sel_hi:[1,0]
	v_pk_mul_f32 v[36:37], v[36:37], v[0:1] op_sel_hi:[1,0]
	v_pk_mul_f32 v[42:43], v[42:43], v[0:1] op_sel_hi:[1,0]
	v_pk_mul_f32 v[40:41], v[40:41], v[0:1] op_sel_hi:[1,0]
	v_pk_mul_f32 v[46:47], v[46:47], v[0:1] op_sel_hi:[1,0]
	v_pk_mul_f32 v[44:45], v[44:45], v[0:1] op_sel_hi:[1,0]
	v_pk_mul_f32 v[50:51], v[50:51], v[0:1] op_sel_hi:[1,0]
	v_pk_mul_f32 v[48:49], v[48:49], v[0:1] op_sel_hi:[1,0]
	v_pk_mul_f32 v[54:55], v[54:55], v[0:1] op_sel_hi:[1,0]
	v_pk_mul_f32 v[52:53], v[52:53], v[0:1] op_sel_hi:[1,0]
	v_pk_mul_f32 v[58:59], v[58:59], v[0:1] op_sel_hi:[1,0]
	v_pk_mul_f32 v[56:57], v[56:57], v[0:1] op_sel_hi:[1,0]
	v_pk_mul_f32 v[62:63], v[62:63], v[0:1] op_sel_hi:[1,0]
	v_pk_mul_f32 v[60:61], v[60:61], v[0:1] op_sel_hi:[1,0]
	v_pk_mul_f32 v[66:67], v[66:67], v[0:1] op_sel_hi:[1,0]
	v_pk_mul_f32 v[64:65], v[64:65], v[0:1] op_sel_hi:[1,0]
.LBB0_1022:
	v_add_f32_e32 v0, -4.0, v227
	v_sub_f32_e32 v2, v2, v0
	v_exp_f32_e32 v2, v2
	v_sub_f32_e32 v6, v6, v0
	v_exp_f32_e32 v6, v6
	v_sub_f32_e32 v4, v4, v0
	v_cndmask_b32_e64 v26, 0, v2, s[16:17]
	v_sub_f32_e32 v2, v3, v0
	v_exp_f32_e32 v2, v2
	v_sub_f32_e32 v3, v7, v0
	v_exp_f32_e32 v3, v3
	v_cndmask_b32_e64 v27, 0, v6, s[24:25]
	v_sub_f32_e32 v6, v8, v0
	v_cndmask_b32_e64 v28, 0, v2, s[12:13]
	v_sub_f32_e32 v2, v5, v0
	v_sub_f32_e32 v0, v9, v0
	v_exp_f32_e32 v4, v4
	v_exp_f32_e32 v6, v6
	v_cndmask_b32_e64 v29, 0, v3, s[20:21]
	v_exp_f32_e32 v5, v2
	v_exp_f32_e32 v0, v0
	v_mov_b32_e32 v2, v1
	v_mov_b32_e32 v3, v1
	v_cvt_pk_fp8_f32 v2, v26, v28
	v_cvt_pk_fp8_f32 v3, v27, v29
	v_cndmask_b32_e64 v4, 0, v4, s[14:15]
	v_cndmask_b32_e64 v30, 0, v6, s[22:23]
	v_cndmask_b32_e64 v5, 0, v5, s[10:11]
	v_cndmask_b32_e64 v0, 0, v0, s[18:19]
	v_cvt_pk_fp8_f32 v2, v4, v5 op_sel:[0,0,1]
	v_cvt_pk_fp8_f32 v3, v30, v0 op_sel:[0,0,1]
	v_add_f32_e32 v26, v26, v27
	v_add_f32_e32 v31, 0, v26
	v_add_f32_e32 v32, v28, v29
	v_add_f32_e32 v31, v32, v31
	v_add_f32_e32 v4, v4, v30
	v_add_f32_e32 v4, v4, v31
	v_add_f32_e32 v0, v5, v0
	s_waitcnt vmcnt(31)
	v_mfma_f32_16x16x32_fp8_fp8 v[6:9], v[170:171], v[2:3], v[36:39]
	v_add_f32_e32 v0, v0, v4
	v_add_f32_e32 v34, v229, v0
	v_mov_b32_e32 v133, v227
	s_waitcnt vmcnt(30)
	v_mfma_f32_16x16x32_fp8_fp8 v[10:13], v[172:173], v[2:3], v[40:43]
	s_waitcnt vmcnt(29)
	v_mfma_f32_16x16x32_fp8_fp8 v[14:17], v[174:175], v[2:3], v[44:47]
	s_waitcnt vmcnt(28)
	v_mfma_f32_16x16x32_fp8_fp8 v[18:21], v[176:177], v[2:3], v[48:51]
	s_waitcnt vmcnt(27)
	v_mfma_f32_16x16x32_fp8_fp8 v[22:25], v[184:185], v[2:3], v[52:55]
	s_waitcnt vmcnt(26)
	v_mfma_f32_16x16x32_fp8_fp8 v[26:29], v[182:183], v[2:3], v[56:59]
	s_waitcnt vmcnt(25)
	v_mfma_f32_16x16x32_fp8_fp8 v[30:33], v[180:181], v[2:3], v[60:63]
	s_waitcnt vmcnt(24)
	v_mfma_f32_16x16x32_fp8_fp8 v[2:5], v[178:179], v[2:3], v[64:67]
